# v22 + trailing s_setprio 0 of each MFMA block moved after the closing s_barrier (MFMA wave reaches the barrier one slot earlier)
# speedup vs baseline: 1.0149x; 1.0149x over previous
; #define PG8_STAGE(bufoff, gbase, voff) do { _Pragma("unroll") for (int _i = 0; _i < 2; ++_i) \
;         __builtin_amdgcn_global_load_lds((const unsigned*)((const char*)(gbase) + (voff)[_i]), (PG8_LAS unsigned*)(lds + (bufoff) + ldsw + _i * 8192), 16, 0, 0); } while (0)
; #define PG8_LDA(dst, b, h) do { _Pragma("unroll") for (int m = 0; m < 4; ++m) _Pragma("unroll") for (int k = 0; k < 2; ++k) dst[m][k] = *(const PG8_LAS bf16x8*)(lds + PG8_SA(b, h) + aoff + m * 2048 + k * 1024); } while (0)
; #define PG8_LDB(dst, b, h) do { _Pragma("unroll") for (int n = 0; n < 2; ++n) _Pragma("unroll") for (int k = 0; k < 2; ++k) dst[n][k] = *(const PG8_LAS bf16x8*)(lds + PG8_SB(b, h) + boff + n * 2048 + k * 1024); } while (0)
; #define PG8_MMA(ai, bj, At, Bt) do { __builtin_amdgcn_s_setprio(1); _Pragma("unroll") for (int m = 0; m < 4; ++m) _Pragma("unroll") for (int n = 0; n < 2; ++n) _Pragma("unroll") for (int k = 0; k < 2; ++k) \
;         acc[ai][bj][m][n] = __builtin_amdgcn_mfma_f32_16x16x32_bf16(Bt[n][k], At[m][k], acc[ai][bj][m][n], 0, 0, 0); __builtin_amdgcn_s_setprio(0); } while (0)
; #define PG8_WAIT_V(n) asm volatile("s_waitcnt vmcnt(" #n ")" ::: "memory")
; #define PG8_WAIT_L(n) asm volatile("s_waitcnt lgkmcnt(" #n ")" ::: "memory")
; #define PG8_BAR __builtin_amdgcn_s_barrier()
; template <class Epi, class Sched, bool ALIGN_EPI = false, bool SP2 = false>
; __device__ __forceinline__ void gemm_phase(PG8_LAS unsigned char* lds, const Gemm g, const Sched& S, const Epi& E) {
;     ...
;         const bool has_next = S.next(ui + 1, nxt);
;         const char* nA = has_next ? (const char*)g.A + (size_t)nxt.pm * tstep : cA; const char* nB = has_next ? (const char*)g.Bt + (size_t)nxt.pn * tstep : cB;
;         for (int t = 0; t < nt; t += 2) {
;             const bool last = (t == nt - 2);
;             const char* a1 = cA + (size_t)(t + 1) * kstep;
;             const char* a2 = last ? nA : cA + (size_t)(t + 2) * kstep; const char* b2 = last ? nB : cB + (size_t)(t + 2) * kstep;
;             const char* a3 = a2 + kstep; const char* b3 = b2 + kstep;
;             if (last && has_next) S.a_ready(nxt);
;             if constexpr (SP2) {
;             PG8_LDB(B0, 0, 0); PG8_LDB(B1, 0, 1); PG8_SCHED; PG8_LDA(At, 0, 0); PG8_STAGE(PG8_SA(1, 1), a1 + hstep, voffA);
;             PG8_WAIT_V(8); PG8_WAIT_L(0); PG8_BAR; PG8_MMA(0, 0, At, B0); PG8_MMA(0, 1, At, B1); PG8_BAR; PG8_SCHED;
.LBB0_367:
	s_ashr_i32 s11, s10, 31
	s_lshl_b64 s[12:13], s[10:11], 19
	s_add_u32 s12, s90, s12
	s_addc_u32 s13, s91, s13
	s_and_b64 s[14:15], s[4:5], exec
	s_cselect_b32 s11, s13, s17
	s_cselect_b32 s50, s12, s16
	s_ashr_i32 s9, s8, 31
	s_lshl_b64 s[14:15], s[8:9], 19
	s_add_u32 s14, s22, s14
	s_addc_u32 s15, s23, s15
	s_and_b64 s[20:21], s[4:5], exec
	s_cselect_b32 s9, s15, s19
	s_cselect_b32 s51, s14, s18
	s_add_u32 s16, s16, 0x40080
	s_addc_u32 s17, s17, 0
	s_add_u32 s52, s18, 0x100
	s_addc_u32 s53, s19, 0
	s_mov_b32 s55, -2
	s_add_u32 s18, s16, 0xfffc0080
	s_addc_u32 s19, s17, -1
	s_add_i32 s56, 0, 0x10000
	s_cmp_eq_u32 s55, 12
	s_cselect_b32 s21, s11, s19
	s_cselect_b32 s20, s50, s18
	s_cselect_b32 s19, s9, s53
	s_cselect_b32 s18, s51, s52
	s_add_i32 s58, 0, 0x14000
	v_lshl_add_u64 v[140:141], s[16:17], 0, v[136:137]
	s_add_i32 m0, s25, 0xc000
	global_load_lds_dwordx4 v[140:141], off
	v_lshl_add_u64 v[140:141], s[16:17], 0, v[138:139]
	s_add_i32 m0, s25, 0xe000
	s_nop 0
	global_load_lds_dwordx4 v[140:141], off
	s_waitcnt vmcnt(16)
	s_waitcnt lgkmcnt(0)
	s_barrier
	s_setprio 1
	s_waitcnt lgkmcnt(0)
	v_mfma_f32_16x16x32_bf16 v[122:125], v[154:157], v[204:207], 0
	v_mfma_f32_16x16x32_bf16 v[114:117], v[162:165], v[204:207], 0
	v_mfma_f32_16x16x32_bf16 v[106:109], v[154:157], v[212:215], 0
	v_mfma_f32_16x16x32_bf16 v[98:101], v[162:165], v[212:215], 0
	v_mfma_f32_16x16x32_bf16 v[90:93], v[154:157], v[220:223], 0
	v_mfma_f32_16x16x32_bf16 v[82:85], v[162:165], v[220:223], 0
	v_mfma_f32_16x16x32_bf16 v[74:77], v[154:157], v[228:231], 0
	v_mfma_f32_16x16x32_bf16 v[66:69], v[162:165], v[228:231], 0
	v_mfma_f32_16x16x32_bf16 v[122:125], v[158:161], v[208:211], v[122:125]
	v_mfma_f32_16x16x32_bf16 v[114:117], v[166:169], v[208:211], v[114:117]
	v_mfma_f32_16x16x32_bf16 v[106:109], v[158:161], v[216:219], v[106:109]
	v_mfma_f32_16x16x32_bf16 v[98:101], v[166:169], v[216:219], v[98:101]
	v_mfma_f32_16x16x32_bf16 v[90:93], v[158:161], v[224:227], v[90:93]
	v_mfma_f32_16x16x32_bf16 v[82:85], v[166:169], v[224:227], v[82:85]
	v_mfma_f32_16x16x32_bf16 v[74:77], v[158:161], v[232:235], v[74:77]
	v_mfma_f32_16x16x32_bf16 v[66:69], v[166:169], v[232:235], v[66:69]
	s_setprio 0
	s_setprio 1
	v_mfma_f32_16x16x32_bf16 v[126:129], v[170:173], v[204:207], 0
	v_mfma_f32_16x16x32_bf16 v[118:121], v[178:181], v[204:207], 0
	v_mfma_f32_16x16x32_bf16 v[110:113], v[170:173], v[212:215], 0
	v_mfma_f32_16x16x32_bf16 v[102:105], v[178:181], v[212:215], 0
	v_mfma_f32_16x16x32_bf16 v[94:97], v[170:173], v[220:223], 0
	v_mfma_f32_16x16x32_bf16 v[86:89], v[178:181], v[220:223], 0
	v_mfma_f32_16x16x32_bf16 v[78:81], v[170:173], v[228:231], 0
	v_mfma_f32_16x16x32_bf16 v[70:73], v[178:181], v[228:231], 0
	v_mfma_f32_16x16x32_bf16 v[126:129], v[174:177], v[208:211], v[126:129]
	v_mfma_f32_16x16x32_bf16 v[118:121], v[200:203], v[208:211], v[118:121]
	v_mfma_f32_16x16x32_bf16 v[110:113], v[174:177], v[216:219], v[110:113]
	v_mfma_f32_16x16x32_bf16 v[102:105], v[200:203], v[216:219], v[102:105]
	v_mfma_f32_16x16x32_bf16 v[94:97], v[174:177], v[224:227], v[94:97]
	v_mfma_f32_16x16x32_bf16 v[86:89], v[200:203], v[224:227], v[86:89]
	v_mfma_f32_16x16x32_bf16 v[78:81], v[174:177], v[232:235], v[78:81]
	v_mfma_f32_16x16x32_bf16 v[70:73], v[200:203], v[232:235], v[70:73]
	s_barrier
	s_setprio 0
	s_add_i32 s56, s56, s24
	v_lshl_add_u64 v[140:141], s[18:19], 0, v[0:1]
	s_mov_b32 m0, s56
	ds_read_b128 v[204:207], v145 offset:16384
	ds_read_b128 v[208:211], v145 offset:17408
	ds_read_b128 v[212:215], v145 offset:18432
	ds_read_b128 v[216:219], v145 offset:19456
	ds_read_b128 v[220:223], v145 offset:20480
	ds_read_b128 v[224:227], v145 offset:21504
	ds_read_b128 v[228:231], v145 offset:22528
	ds_read_b128 v[232:235], v145 offset:23552
	global_load_lds_dwordx4 v[140:141], off
	s_add_i32 m0, s56, 0x2000
	s_add_u32 s56, s18, 0x40000
	v_lshl_add_u64 v[146:147], s[18:19], 0, v[130:131]
	s_addc_u32 s57, s19, 0
	s_add_i32 s58, s58, s24
	global_load_lds_dwordx4 v[146:147], off
	v_lshl_add_u64 v[148:149], s[56:57], 0, v[0:1]
	s_mov_b32 m0, s58
	v_lshl_add_u64 v[236:237], s[20:21], 0, v[132:133]
	global_load_lds_dwordx4 v[148:149], off
	v_lshl_add_u64 v[148:149], s[56:57], 0, v[130:131]
	s_add_i32 m0, s58, 0x2000
	s_nop 0
	global_load_lds_dwordx4 v[148:149], off
	v_lshl_add_u64 v[148:149], s[20:21], 0, v[134:135]
	s_mov_b32 m0, s25
	s_nop 0
	global_load_lds_dwordx4 v[148:149], off
	s_mov_b32 m0, s26
	s_nop 0
	global_load_lds_dwordx4 v[236:237], off
	s_waitcnt vmcnt(16)
	s_waitcnt lgkmcnt(0)
	s_barrier
	s_setprio 1
	s_waitcnt lgkmcnt(0)
	v_mfma_f32_16x16x32_bf16 v[58:61], v[154:157], v[204:207], 0
	v_mfma_f32_16x16x32_bf16 v[50:53], v[162:165], v[204:207], 0
	v_mfma_f32_16x16x32_bf16 v[42:45], v[154:157], v[212:215], 0
	v_mfma_f32_16x16x32_bf16 v[34:37], v[162:165], v[212:215], 0
	v_mfma_f32_16x16x32_bf16 v[26:29], v[154:157], v[220:223], 0
	v_mfma_f32_16x16x32_bf16 v[18:21], v[162:165], v[220:223], 0
	v_mfma_f32_16x16x32_bf16 v[10:13], v[154:157], v[228:231], 0
	v_mfma_f32_16x16x32_bf16 v[2:5], v[162:165], v[228:231], 0
	v_mfma_f32_16x16x32_bf16 v[58:61], v[158:161], v[208:211], v[58:61]
	v_mfma_f32_16x16x32_bf16 v[50:53], v[166:169], v[208:211], v[50:53]
	v_mfma_f32_16x16x32_bf16 v[42:45], v[158:161], v[216:219], v[42:45]
	v_mfma_f32_16x16x32_bf16 v[34:37], v[166:169], v[216:219], v[34:37]
	v_mfma_f32_16x16x32_bf16 v[26:29], v[158:161], v[224:227], v[26:29]
	v_mfma_f32_16x16x32_bf16 v[18:21], v[166:169], v[224:227], v[18:21]
	v_mfma_f32_16x16x32_bf16 v[10:13], v[158:161], v[232:235], v[10:13]
	v_mfma_f32_16x16x32_bf16 v[2:5], v[166:169], v[232:235], v[2:5]
	s_setprio 0
	s_setprio 1
	v_mfma_f32_16x16x32_bf16 v[62:65], v[170:173], v[204:207], 0
	v_mfma_f32_16x16x32_bf16 v[54:57], v[178:181], v[204:207], 0
	v_mfma_f32_16x16x32_bf16 v[46:49], v[170:173], v[212:215], 0
	v_mfma_f32_16x16x32_bf16 v[38:41], v[178:181], v[212:215], 0
	v_mfma_f32_16x16x32_bf16 v[30:33], v[170:173], v[220:223], 0
	v_mfma_f32_16x16x32_bf16 v[22:25], v[178:181], v[220:223], 0
	v_mfma_f32_16x16x32_bf16 v[14:17], v[170:173], v[228:231], 0
	v_mfma_f32_16x16x32_bf16 v[6:9], v[178:181], v[228:231], 0
	v_mfma_f32_16x16x32_bf16 v[62:65], v[174:177], v[208:211], v[62:65]
	v_mfma_f32_16x16x32_bf16 v[54:57], v[200:203], v[208:211], v[54:57]
	v_mfma_f32_16x16x32_bf16 v[46:49], v[174:177], v[216:219], v[46:49]
	v_mfma_f32_16x16x32_bf16 v[38:41], v[200:203], v[216:219], v[38:41]
	v_mfma_f32_16x16x32_bf16 v[30:33], v[174:177], v[224:227], v[30:33]
	v_mfma_f32_16x16x32_bf16 v[22:25], v[200:203], v[224:227], v[22:25]
	v_mfma_f32_16x16x32_bf16 v[14:17], v[174:177], v[232:235], v[14:17]
	v_mfma_f32_16x16x32_bf16 v[6:9], v[200:203], v[232:235], v[6:9]
	s_barrier
; #define PG8_STAGE(bufoff, gbase, voff) do { _Pragma("unroll") for (int _i = 0; _i < 2; ++_i) \
;         __builtin_amdgcn_global_load_lds((const unsigned*)((const char*)(gbase) + (voff)[_i]), (PG8_LAS unsigned*)(lds + (bufoff) + ldsw + _i * 8192), 16, 0, 0); } while (0)
; #define PG8_LDA(dst, b, h) do { _Pragma("unroll") for (int m = 0; m < 4; ++m) _Pragma("unroll") for (int k = 0; k < 2; ++k) dst[m][k] = *(const PG8_LAS bf16x8*)(lds + PG8_SA(b, h) + aoff + m * 2048 + k * 1024); } while (0)
; #define PG8_LDB(dst, b, h) do { _Pragma("unroll") for (int n = 0; n < 2; ++n) _Pragma("unroll") for (int k = 0; k < 2; ++k) dst[n][k] = *(const PG8_LAS bf16x8*)(lds + PG8_SB(b, h) + boff + n * 2048 + k * 1024); } while (0)
; #define PG8_MMA(ai, bj, At, Bt) do { __builtin_amdgcn_s_setprio(1); _Pragma("unroll") for (int m = 0; m < 4; ++m) _Pragma("unroll") for (int n = 0; n < 2; ++n) _Pragma("unroll") for (int k = 0; k < 2; ++k) \
;         acc[ai][bj][m][n] = __builtin_amdgcn_mfma_f32_16x16x32_bf16(Bt[n][k], At[m][k], acc[ai][bj][m][n], 0, 0, 0); __builtin_amdgcn_s_setprio(0); } while (0)
; #define PG8_WAIT_V(n) asm volatile("s_waitcnt vmcnt(" #n ")" ::: "memory")
; #define PG8_WAIT_L(n) asm volatile("s_waitcnt lgkmcnt(" #n ")" ::: "memory")
; #define PG8_BAR __builtin_amdgcn_s_barrier()
; #define PG8_SCHED __builtin_amdgcn_sched_barrier(0)
; template <class Epi, class Sched, bool ALIGN_EPI = false, bool SP2 = false>
; __device__ __forceinline__ void gemm_phase(PG8_LAS unsigned char* lds, const Gemm g, const Sched& S, const Epi& E) {
;     ...
;             PG8_LDA(At, 0, 1); PG8_STAGE(PG8_SB(0, 0), b2, voffB); PG8_STAGE(PG8_SB(0, 1), b2 + hstep, voffB); PG8_STAGE(PG8_SA(0, 0), a2, voffA);
;             PG8_WAIT_V(8); PG8_WAIT_L(0); PG8_BAR; PG8_MMA(1, 0, At, B0); PG8_MMA(1, 1, At, B1); PG8_BAR; PG8_SCHED;
;             PG8_LDB(B0, 1, 0); PG8_LDB(B1, 1, 1); PG8_SCHED; PG8_LDA(At, 1, 0); PG8_STAGE(PG8_SA(0, 1), a2 + hstep, voffA);
;             PG8_WAIT_V(8); PG8_WAIT_L(0); PG8_BAR; PG8_MMA(0, 0, At, B0); PG8_MMA(0, 1, At, B1); PG8_BAR; PG8_SCHED;
;             PG8_LDA(At, 1, 1); PG8_STAGE(PG8_SB(1, 0), b3, voffB); PG8_STAGE(PG8_SB(1, 1), b3 + hstep, voffB); PG8_STAGE(PG8_SA(1, 0), a3, voffA);
	s_setprio 0
	s_add_i32 s56, 0, 0x18000
	s_add_i32 s57, 0, 0x1c000
	v_add_u32_e32 v166, s56, v143
	v_add_u32_e32 v200, s57, v143
	ds_read_b128 v[154:157], v166
	ds_read_b128 v[158:161], v166 offset:1024
	ds_read_b128 v[162:165], v166 offset:2048
	ds_read_b128 v[166:169], v166 offset:3072
	ds_read_b128 v[170:173], v200
	ds_read_b128 v[174:177], v200 offset:1024
	ds_read_b128 v[178:181], v200 offset:2048
	ds_read_b128 v[200:203], v200 offset:3072
	s_add_u32 s20, s20, 0x40000
	s_addc_u32 s21, s21, 0
	s_mov_b32 m0, s27
	v_lshl_add_u64 v[238:239], s[20:21], 0, v[134:135]
	ds_read_b128 v[204:207], v145 offset:32768
	ds_read_b128 v[208:211], v145 offset:33792
	ds_read_b128 v[212:215], v145 offset:34816
	ds_read_b128 v[216:219], v145 offset:35840
	ds_read_b128 v[220:223], v145 offset:36864
	ds_read_b128 v[224:227], v145 offset:37888
	ds_read_b128 v[228:231], v145 offset:38912
	ds_read_b128 v[232:235], v145 offset:39936
	global_load_lds_dwordx4 v[238:239], off
	v_lshl_add_u64 v[238:239], s[20:21], 0, v[132:133]
	s_mov_b32 m0, s28
	s_nop 0
	global_load_lds_dwordx4 v[238:239], off
	s_waitcnt vmcnt(8)
	s_waitcnt lgkmcnt(0)
	s_barrier
	s_setprio 1
	s_waitcnt lgkmcnt(0)
	v_mfma_f32_16x16x32_bf16 v[122:125], v[154:157], v[204:207], v[122:125]
	v_mfma_f32_16x16x32_bf16 v[114:117], v[162:165], v[204:207], v[114:117]
	v_mfma_f32_16x16x32_bf16 v[106:109], v[154:157], v[212:215], v[106:109]
	v_mfma_f32_16x16x32_bf16 v[98:101], v[162:165], v[212:215], v[98:101]
	v_mfma_f32_16x16x32_bf16 v[90:93], v[154:157], v[220:223], v[90:93]
	v_mfma_f32_16x16x32_bf16 v[82:85], v[162:165], v[220:223], v[82:85]
	v_mfma_f32_16x16x32_bf16 v[74:77], v[154:157], v[228:231], v[74:77]
	v_mfma_f32_16x16x32_bf16 v[66:69], v[162:165], v[228:231], v[66:69]
	v_mfma_f32_16x16x32_bf16 v[122:125], v[158:161], v[208:211], v[122:125]
	v_mfma_f32_16x16x32_bf16 v[114:117], v[166:169], v[208:211], v[114:117]
	v_mfma_f32_16x16x32_bf16 v[106:109], v[158:161], v[216:219], v[106:109]
	v_mfma_f32_16x16x32_bf16 v[98:101], v[166:169], v[216:219], v[98:101]
	v_mfma_f32_16x16x32_bf16 v[90:93], v[158:161], v[224:227], v[90:93]
	v_mfma_f32_16x16x32_bf16 v[82:85], v[166:169], v[224:227], v[82:85]
	v_mfma_f32_16x16x32_bf16 v[74:77], v[158:161], v[232:235], v[74:77]
	v_mfma_f32_16x16x32_bf16 v[66:69], v[166:169], v[232:235], v[66:69]
	s_setprio 0
	s_setprio 1
	v_mfma_f32_16x16x32_bf16 v[126:129], v[170:173], v[204:207], v[126:129]
	v_mfma_f32_16x16x32_bf16 v[118:121], v[178:181], v[204:207], v[118:121]
	v_mfma_f32_16x16x32_bf16 v[110:113], v[170:173], v[212:215], v[110:113]
	v_mfma_f32_16x16x32_bf16 v[102:105], v[178:181], v[212:215], v[102:105]
	v_mfma_f32_16x16x32_bf16 v[94:97], v[170:173], v[220:223], v[94:97]
	v_mfma_f32_16x16x32_bf16 v[86:89], v[178:181], v[220:223], v[86:89]
	v_mfma_f32_16x16x32_bf16 v[78:81], v[170:173], v[228:231], v[78:81]
	v_mfma_f32_16x16x32_bf16 v[70:73], v[178:181], v[228:231], v[70:73]
	v_mfma_f32_16x16x32_bf16 v[126:129], v[174:177], v[208:211], v[126:129]
	v_mfma_f32_16x16x32_bf16 v[118:121], v[200:203], v[208:211], v[118:121]
	v_mfma_f32_16x16x32_bf16 v[110:113], v[174:177], v[216:219], v[110:113]
	v_mfma_f32_16x16x32_bf16 v[102:105], v[200:203], v[216:219], v[102:105]
	v_mfma_f32_16x16x32_bf16 v[94:97], v[174:177], v[224:227], v[94:97]
	v_mfma_f32_16x16x32_bf16 v[86:89], v[200:203], v[224:227], v[86:89]
	v_mfma_f32_16x16x32_bf16 v[78:81], v[174:177], v[232:235], v[78:81]
	v_mfma_f32_16x16x32_bf16 v[70:73], v[200:203], v[232:235], v[70:73]
	s_barrier
	s_setprio 0
	s_add_i32 s20, s56, s24
	v_lshl_add_u64 v[140:141], v[140:141], 0, s[38:39]
	s_mov_b32 m0, s20
	ds_read_b128 v[204:207], v145 offset:49152
	ds_read_b128 v[208:211], v145 offset:50176
	ds_read_b128 v[212:215], v145 offset:51200
	ds_read_b128 v[216:219], v145 offset:52224
	ds_read_b128 v[220:223], v145 offset:53248
	ds_read_b128 v[224:227], v145 offset:54272
	ds_read_b128 v[228:231], v145 offset:55296
	ds_read_b128 v[232:235], v145 offset:56320
	global_load_lds_dwordx4 v[140:141], off
	s_add_i32 m0, s20, 0x2000
	s_add_u32 s18, s18, 0x40080
	v_lshl_add_u64 v[140:141], v[146:147], 0, s[38:39]
	s_addc_u32 s19, s19, 0
	s_add_i32 s20, s57, s24
	global_load_lds_dwordx4 v[140:141], off
	v_lshl_add_u64 v[140:141], s[18:19], 0, v[0:1]
	s_mov_b32 m0, s20
	s_nop 0
	global_load_lds_dwordx4 v[140:141], off
	v_lshl_add_u64 v[140:141], s[18:19], 0, v[130:131]
	s_add_i32 m0, s20, 0x2000
	s_nop 0
	global_load_lds_dwordx4 v[140:141], off
	v_lshl_add_u64 v[140:141], v[148:149], 0, s[38:39]
	s_mov_b32 m0, s29
	s_nop 0
	global_load_lds_dwordx4 v[140:141], off
	v_lshl_add_u64 v[140:141], v[236:237], 0, s[38:39]
	s_mov_b32 m0, s30
	s_nop 0
	global_load_lds_dwordx4 v[140:141], off
	s_waitcnt vmcnt(8)
	s_waitcnt lgkmcnt(0)
	s_barrier
; #define PG8_STAGE(bufoff, gbase, voff) do { _Pragma("unroll") for (int _i = 0; _i < 2; ++_i) \
;         __builtin_amdgcn_global_load_lds((const unsigned*)((const char*)(gbase) + (voff)[_i]), (PG8_LAS unsigned*)(lds + (bufoff) + ldsw + _i * 8192), 16, 0, 0); } while (0)
; #define PG8_LDA(dst, b, h) do { _Pragma("unroll") for (int m = 0; m < 4; ++m) _Pragma("unroll") for (int k = 0; k < 2; ++k) dst[m][k] = *(const PG8_LAS bf16x8*)(lds + PG8_SA(b, h) + aoff + m * 2048 + k * 1024); } while (0)
; #define PG8_LDB(dst, b, h) do { _Pragma("unroll") for (int n = 0; n < 2; ++n) _Pragma("unroll") for (int k = 0; k < 2; ++k) dst[n][k] = *(const PG8_LAS bf16x8*)(lds + PG8_SB(b, h) + boff + n * 2048 + k * 1024); } while (0)
; #define PG8_MMA(ai, bj, At, Bt) do { __builtin_amdgcn_s_setprio(1); _Pragma("unroll") for (int m = 0; m < 4; ++m) _Pragma("unroll") for (int n = 0; n < 2; ++n) _Pragma("unroll") for (int k = 0; k < 2; ++k) \
;         acc[ai][bj][m][n] = __builtin_amdgcn_mfma_f32_16x16x32_bf16(Bt[n][k], At[m][k], acc[ai][bj][m][n], 0, 0, 0); __builtin_amdgcn_s_setprio(0); } while (0)
; template <class Epi, class Sched, bool ALIGN_EPI = false, bool SP2 = false>
; __device__ __forceinline__ void gemm_phase(PG8_LAS unsigned char* lds, const Gemm g, const Sched& S, const Epi& E) {
;     ...
;         for (int t = 0; t < nt; t += 2) {
;             const bool last = (t == nt - 2);
;             const char* a1 = cA + (size_t)(t + 1) * kstep;
;             const char* a2 = last ? nA : cA + (size_t)(t + 2) * kstep; const char* b2 = last ? nB : cB + (size_t)(t + 2) * kstep;
;             const char* a3 = a2 + kstep; const char* b3 = b2 + kstep;
;             if (last && has_next) S.a_ready(nxt);
;             if constexpr (SP2) {
;             PG8_LDB(B0, 0, 0); PG8_LDB(B1, 0, 1); PG8_SCHED; PG8_LDA(At, 0, 0); PG8_STAGE(PG8_SA(1, 1), a1 + hstep, voffA);
;             PG8_WAIT_V(8); PG8_WAIT_L(0); PG8_BAR; PG8_MMA(0, 0, At, B0); PG8_MMA(0, 1, At, B1); PG8_BAR; PG8_SCHED;
;     ...
;             PG8_WAIT_V(8); PG8_WAIT_L(0); PG8_BAR; PG8_MMA(0, 0, At, B0); PG8_MMA(0, 1, At, B1); PG8_BAR; PG8_SCHED;
;             PG8_LDA(At, 1, 1); PG8_STAGE(PG8_SB(1, 0), b3, voffB); PG8_STAGE(PG8_SB(1, 1), b3 + hstep, voffB); PG8_STAGE(PG8_SA(1, 0), a3, voffA);
;             PG8_WAIT_V(8); PG8_WAIT_L(0); PG8_BAR; PG8_MMA(1, 0, At, B0); PG8_MMA(1, 1, At, B1); PG8_BAR; PG8_SCHED;
	s_setprio 1
	s_waitcnt lgkmcnt(0)
	v_mfma_f32_16x16x32_bf16 v[58:61], v[154:157], v[204:207], v[58:61]
	v_mfma_f32_16x16x32_bf16 v[50:53], v[162:165], v[204:207], v[50:53]
	v_mfma_f32_16x16x32_bf16 v[42:45], v[154:157], v[212:215], v[42:45]
	v_mfma_f32_16x16x32_bf16 v[34:37], v[162:165], v[212:215], v[34:37]
	v_mfma_f32_16x16x32_bf16 v[26:29], v[154:157], v[220:223], v[26:29]
	v_mfma_f32_16x16x32_bf16 v[18:21], v[162:165], v[220:223], v[18:21]
	v_mfma_f32_16x16x32_bf16 v[10:13], v[154:157], v[228:231], v[10:13]
	v_mfma_f32_16x16x32_bf16 v[2:5], v[162:165], v[228:231], v[2:5]
	v_mfma_f32_16x16x32_bf16 v[58:61], v[158:161], v[208:211], v[58:61]
	v_mfma_f32_16x16x32_bf16 v[50:53], v[166:169], v[208:211], v[50:53]
	v_mfma_f32_16x16x32_bf16 v[42:45], v[158:161], v[216:219], v[42:45]
	v_mfma_f32_16x16x32_bf16 v[34:37], v[166:169], v[216:219], v[34:37]
	v_mfma_f32_16x16x32_bf16 v[26:29], v[158:161], v[224:227], v[26:29]
	v_mfma_f32_16x16x32_bf16 v[18:21], v[166:169], v[224:227], v[18:21]
	v_mfma_f32_16x16x32_bf16 v[10:13], v[158:161], v[232:235], v[10:13]
	v_mfma_f32_16x16x32_bf16 v[2:5], v[166:169], v[232:235], v[2:5]
	s_setprio 0
	s_setprio 1
	v_mfma_f32_16x16x32_bf16 v[62:65], v[170:173], v[204:207], v[62:65]
	v_mfma_f32_16x16x32_bf16 v[54:57], v[178:181], v[204:207], v[54:57]
	v_mfma_f32_16x16x32_bf16 v[46:49], v[170:173], v[212:215], v[46:49]
	v_mfma_f32_16x16x32_bf16 v[38:41], v[178:181], v[212:215], v[38:41]
	v_mfma_f32_16x16x32_bf16 v[30:33], v[170:173], v[220:223], v[30:33]
	v_mfma_f32_16x16x32_bf16 v[22:25], v[178:181], v[220:223], v[22:25]
	v_mfma_f32_16x16x32_bf16 v[14:17], v[170:173], v[228:231], v[14:17]
	v_mfma_f32_16x16x32_bf16 v[6:9], v[178:181], v[228:231], v[6:9]
	v_mfma_f32_16x16x32_bf16 v[62:65], v[174:177], v[208:211], v[62:65]
	v_mfma_f32_16x16x32_bf16 v[54:57], v[200:203], v[208:211], v[54:57]
	v_mfma_f32_16x16x32_bf16 v[46:49], v[174:177], v[216:219], v[46:49]
	v_mfma_f32_16x16x32_bf16 v[38:41], v[200:203], v[216:219], v[38:41]
	v_mfma_f32_16x16x32_bf16 v[30:33], v[174:177], v[224:227], v[30:33]
	v_mfma_f32_16x16x32_bf16 v[22:25], v[200:203], v[224:227], v[22:25]
	v_mfma_f32_16x16x32_bf16 v[14:17], v[174:177], v[232:235], v[14:17]
	v_mfma_f32_16x16x32_bf16 v[6:9], v[200:203], v[232:235], v[6:9]
	s_barrier
	s_setprio 0
	s_add_i32 s55, s55, 2
	s_add_u32 s16, s16, 0x100
	s_addc_u32 s17, s17, 0
	s_add_u32 s52, s52, 0x100
	s_addc_u32 s53, s53, 0
.LBB0_368:
	s_add_u32 s18, s16, 0xfffc0080
	s_addc_u32 s19, s17, -1
	s_add_i32 s56, 0, 0x10000
	s_cmp_eq_u32 s55, 12
	s_cselect_b32 s21, s11, s19
	s_cselect_b32 s20, s50, s18
	v_add_u32_e32 v140, s56, v143
	s_cselect_b32 s19, s9, s53
	s_cselect_b32 s18, s51, s52
	s_add_i32 s58, 0, 0x14000
	ds_read_b128 v[154:157], v140
	ds_read_b128 v[158:161], v140 offset:1024
	ds_read_b128 v[162:165], v140 offset:2048
	ds_read_b128 v[166:169], v140 offset:3072
	v_add_u32_e32 v140, s58, v143
	ds_read_b128 v[170:173], v140
	ds_read_b128 v[174:177], v140 offset:1024
	ds_read_b128 v[178:181], v140 offset:2048
	ds_read_b128 v[200:203], v140 offset:3072
	v_lshl_add_u64 v[140:141], s[16:17], 0, v[136:137]
	s_add_i32 m0, s25, 0xc000
	ds_read_b128 v[204:207], v145
	ds_read_b128 v[208:211], v145 offset:1024
	ds_read_b128 v[212:215], v145 offset:2048
	ds_read_b128 v[216:219], v145 offset:3072
	ds_read_b128 v[220:223], v145 offset:4096
	ds_read_b128 v[224:227], v145 offset:5120
	ds_read_b128 v[228:231], v145 offset:6144
	ds_read_b128 v[232:235], v145 offset:7168
	global_load_lds_dwordx4 v[140:141], off
	v_lshl_add_u64 v[140:141], s[16:17], 0, v[138:139]
	s_add_i32 m0, s25, 0xe000
	s_nop 0
	global_load_lds_dwordx4 v[140:141], off
	s_waitcnt vmcnt(8)
	s_waitcnt lgkmcnt(0)
	s_barrier
	s_setprio 1
	s_waitcnt lgkmcnt(0)
	v_mfma_f32_16x16x32_bf16 v[122:125], v[154:157], v[204:207], v[122:125]
	v_mfma_f32_16x16x32_bf16 v[114:117], v[162:165], v[204:207], v[114:117]
	v_mfma_f32_16x16x32_bf16 v[106:109], v[154:157], v[212:215], v[106:109]
	v_mfma_f32_16x16x32_bf16 v[98:101], v[162:165], v[212:215], v[98:101]
	v_mfma_f32_16x16x32_bf16 v[90:93], v[154:157], v[220:223], v[90:93]
	v_mfma_f32_16x16x32_bf16 v[82:85], v[162:165], v[220:223], v[82:85]
	v_mfma_f32_16x16x32_bf16 v[74:77], v[154:157], v[228:231], v[74:77]
	v_mfma_f32_16x16x32_bf16 v[66:69], v[162:165], v[228:231], v[66:69]
	v_mfma_f32_16x16x32_bf16 v[122:125], v[158:161], v[208:211], v[122:125]
	v_mfma_f32_16x16x32_bf16 v[114:117], v[166:169], v[208:211], v[114:117]
	v_mfma_f32_16x16x32_bf16 v[106:109], v[158:161], v[216:219], v[106:109]
	v_mfma_f32_16x16x32_bf16 v[98:101], v[166:169], v[216:219], v[98:101]
	v_mfma_f32_16x16x32_bf16 v[90:93], v[158:161], v[224:227], v[90:93]
	v_mfma_f32_16x16x32_bf16 v[82:85], v[166:169], v[224:227], v[82:85]
	v_mfma_f32_16x16x32_bf16 v[74:77], v[158:161], v[232:235], v[74:77]
	v_mfma_f32_16x16x32_bf16 v[66:69], v[166:169], v[232:235], v[66:69]
	s_setprio 0
	s_setprio 1
	v_mfma_f32_16x16x32_bf16 v[126:129], v[170:173], v[204:207], v[126:129]
	v_mfma_f32_16x16x32_bf16 v[118:121], v[178:181], v[204:207], v[118:121]
	v_mfma_f32_16x16x32_bf16 v[110:113], v[170:173], v[212:215], v[110:113]
	v_mfma_f32_16x16x32_bf16 v[102:105], v[178:181], v[212:215], v[102:105]
	v_mfma_f32_16x16x32_bf16 v[94:97], v[170:173], v[220:223], v[94:97]
	v_mfma_f32_16x16x32_bf16 v[86:89], v[178:181], v[220:223], v[86:89]
	v_mfma_f32_16x16x32_bf16 v[78:81], v[170:173], v[228:231], v[78:81]
	v_mfma_f32_16x16x32_bf16 v[70:73], v[178:181], v[228:231], v[70:73]
	v_mfma_f32_16x16x32_bf16 v[126:129], v[174:177], v[208:211], v[126:129]
	v_mfma_f32_16x16x32_bf16 v[118:121], v[200:203], v[208:211], v[118:121]
	v_mfma_f32_16x16x32_bf16 v[110:113], v[174:177], v[216:219], v[110:113]
	v_mfma_f32_16x16x32_bf16 v[102:105], v[200:203], v[216:219], v[102:105]
	v_mfma_f32_16x16x32_bf16 v[94:97], v[174:177], v[224:227], v[94:97]
	v_mfma_f32_16x16x32_bf16 v[86:89], v[200:203], v[224:227], v[86:89]
	v_mfma_f32_16x16x32_bf16 v[78:81], v[174:177], v[232:235], v[78:81]
	v_mfma_f32_16x16x32_bf16 v[70:73], v[200:203], v[232:235], v[70:73]
	s_barrier
; #define PG8_STAGE(bufoff, gbase, voff) do { _Pragma("unroll") for (int _i = 0; _i < 2; ++_i) \
;         __builtin_amdgcn_global_load_lds((const unsigned*)((const char*)(gbase) + (voff)[_i]), (PG8_LAS unsigned*)(lds + (bufoff) + ldsw + _i * 8192), 16, 0, 0); } while (0)
; #define PG8_LDA(dst, b, h) do { _Pragma("unroll") for (int m = 0; m < 4; ++m) _Pragma("unroll") for (int k = 0; k < 2; ++k) dst[m][k] = *(const PG8_LAS bf16x8*)(lds + PG8_SA(b, h) + aoff + m * 2048 + k * 1024); } while (0)
; #define PG8_LDB(dst, b, h) do { _Pragma("unroll") for (int n = 0; n < 2; ++n) _Pragma("unroll") for (int k = 0; k < 2; ++k) dst[n][k] = *(const PG8_LAS bf16x8*)(lds + PG8_SB(b, h) + boff + n * 2048 + k * 1024); } while (0)
; #define PG8_MMA(ai, bj, At, Bt) do { __builtin_amdgcn_s_setprio(1); _Pragma("unroll") for (int m = 0; m < 4; ++m) _Pragma("unroll") for (int n = 0; n < 2; ++n) _Pragma("unroll") for (int k = 0; k < 2; ++k) \
;         acc[ai][bj][m][n] = __builtin_amdgcn_mfma_f32_16x16x32_bf16(Bt[n][k], At[m][k], acc[ai][bj][m][n], 0, 0, 0); __builtin_amdgcn_s_setprio(0); } while (0)
; #define PG8_WAIT_V(n) asm volatile("s_waitcnt vmcnt(" #n ")" ::: "memory")
; #define PG8_WAIT_L(n) asm volatile("s_waitcnt lgkmcnt(" #n ")" ::: "memory")
; #define PG8_BAR __builtin_amdgcn_s_barrier()
; #define PG8_SCHED __builtin_amdgcn_sched_barrier(0)
; template <class Epi, class Sched, bool ALIGN_EPI = false, bool SP2 = false>
; __device__ __forceinline__ void gemm_phase(PG8_LAS unsigned char* lds, const Gemm g, const Sched& S, const Epi& E) {
;     ...
;             PG8_WAIT_V(8); PG8_WAIT_L(0); PG8_BAR; PG8_MMA(0, 0, At, B0); PG8_MMA(0, 1, At, B1); PG8_BAR; PG8_SCHED;
;             PG8_LDA(At, 0, 1); PG8_STAGE(PG8_SB(0, 0), b2, voffB); PG8_STAGE(PG8_SB(0, 1), b2 + hstep, voffB); PG8_STAGE(PG8_SA(0, 0), a2, voffA);
;             PG8_WAIT_V(8); PG8_WAIT_L(0); PG8_BAR; PG8_MMA(1, 0, At, B0); PG8_MMA(1, 1, At, B1); PG8_BAR; PG8_SCHED;
;             PG8_LDB(B0, 1, 0); PG8_LDB(B1, 1, 1); PG8_SCHED; PG8_LDA(At, 1, 0); PG8_STAGE(PG8_SA(0, 1), a2 + hstep, voffA);
	s_setprio 0
	s_add_i32 s56, s56, s24
	v_lshl_add_u64 v[140:141], s[18:19], 0, v[0:1]
	s_mov_b32 m0, s56
	ds_read_b128 v[204:207], v145 offset:16384
	ds_read_b128 v[208:211], v145 offset:17408
	ds_read_b128 v[212:215], v145 offset:18432
	ds_read_b128 v[216:219], v145 offset:19456
	ds_read_b128 v[220:223], v145 offset:20480
	ds_read_b128 v[224:227], v145 offset:21504
	ds_read_b128 v[228:231], v145 offset:22528
	ds_read_b128 v[232:235], v145 offset:23552
	global_load_lds_dwordx4 v[140:141], off
	s_add_i32 m0, s56, 0x2000
	s_add_u32 s56, s18, 0x40000
	v_lshl_add_u64 v[146:147], s[18:19], 0, v[130:131]
	s_addc_u32 s57, s19, 0
	s_add_i32 s58, s58, s24
	global_load_lds_dwordx4 v[146:147], off
	v_lshl_add_u64 v[148:149], s[56:57], 0, v[0:1]
	s_mov_b32 m0, s58
	v_lshl_add_u64 v[236:237], s[20:21], 0, v[132:133]
	global_load_lds_dwordx4 v[148:149], off
	v_lshl_add_u64 v[148:149], s[56:57], 0, v[130:131]
	s_add_i32 m0, s58, 0x2000
	s_nop 0
	global_load_lds_dwordx4 v[148:149], off
	v_lshl_add_u64 v[148:149], s[20:21], 0, v[134:135]
	s_mov_b32 m0, s25
	s_nop 0
	global_load_lds_dwordx4 v[148:149], off
	s_mov_b32 m0, s26
	s_nop 0
	global_load_lds_dwordx4 v[236:237], off
	s_waitcnt vmcnt(8)
	s_waitcnt lgkmcnt(0)
	s_barrier
	s_setprio 1
	s_waitcnt lgkmcnt(0)
	v_mfma_f32_16x16x32_bf16 v[58:61], v[154:157], v[204:207], v[58:61]
	v_mfma_f32_16x16x32_bf16 v[50:53], v[162:165], v[204:207], v[50:53]
	v_mfma_f32_16x16x32_bf16 v[42:45], v[154:157], v[212:215], v[42:45]
	v_mfma_f32_16x16x32_bf16 v[34:37], v[162:165], v[212:215], v[34:37]
	v_mfma_f32_16x16x32_bf16 v[26:29], v[154:157], v[220:223], v[26:29]
	v_mfma_f32_16x16x32_bf16 v[18:21], v[162:165], v[220:223], v[18:21]
	v_mfma_f32_16x16x32_bf16 v[10:13], v[154:157], v[228:231], v[10:13]
	v_mfma_f32_16x16x32_bf16 v[2:5], v[162:165], v[228:231], v[2:5]
	v_mfma_f32_16x16x32_bf16 v[58:61], v[158:161], v[208:211], v[58:61]
	v_mfma_f32_16x16x32_bf16 v[50:53], v[166:169], v[208:211], v[50:53]
	v_mfma_f32_16x16x32_bf16 v[42:45], v[158:161], v[216:219], v[42:45]
	v_mfma_f32_16x16x32_bf16 v[34:37], v[166:169], v[216:219], v[34:37]
	v_mfma_f32_16x16x32_bf16 v[26:29], v[158:161], v[224:227], v[26:29]
	v_mfma_f32_16x16x32_bf16 v[18:21], v[166:169], v[224:227], v[18:21]
	v_mfma_f32_16x16x32_bf16 v[10:13], v[158:161], v[232:235], v[10:13]
	v_mfma_f32_16x16x32_bf16 v[2:5], v[166:169], v[232:235], v[2:5]
	s_setprio 0
	s_setprio 1
	v_mfma_f32_16x16x32_bf16 v[62:65], v[170:173], v[204:207], v[62:65]
	v_mfma_f32_16x16x32_bf16 v[54:57], v[178:181], v[204:207], v[54:57]
	v_mfma_f32_16x16x32_bf16 v[46:49], v[170:173], v[212:215], v[46:49]
	v_mfma_f32_16x16x32_bf16 v[38:41], v[178:181], v[212:215], v[38:41]
	v_mfma_f32_16x16x32_bf16 v[30:33], v[170:173], v[220:223], v[30:33]
	v_mfma_f32_16x16x32_bf16 v[22:25], v[178:181], v[220:223], v[22:25]
	v_mfma_f32_16x16x32_bf16 v[14:17], v[170:173], v[228:231], v[14:17]
	v_mfma_f32_16x16x32_bf16 v[6:9], v[178:181], v[228:231], v[6:9]
	v_mfma_f32_16x16x32_bf16 v[62:65], v[174:177], v[208:211], v[62:65]
	v_mfma_f32_16x16x32_bf16 v[54:57], v[200:203], v[208:211], v[54:57]
	v_mfma_f32_16x16x32_bf16 v[46:49], v[174:177], v[216:219], v[46:49]
	v_mfma_f32_16x16x32_bf16 v[38:41], v[200:203], v[216:219], v[38:41]
	v_mfma_f32_16x16x32_bf16 v[30:33], v[174:177], v[224:227], v[30:33]
	v_mfma_f32_16x16x32_bf16 v[22:25], v[200:203], v[224:227], v[22:25]
	v_mfma_f32_16x16x32_bf16 v[14:17], v[174:177], v[232:235], v[14:17]
	v_mfma_f32_16x16x32_bf16 v[6:9], v[200:203], v[232:235], v[6:9]
	s_barrier
	s_setprio 0
	s_add_i32 s56, 0, 0x18000
	s_add_i32 s57, 0, 0x1c000
	v_add_u32_e32 v166, s56, v143
	v_add_u32_e32 v200, s57, v143
	ds_read_b128 v[154:157], v166
	ds_read_b128 v[158:161], v166 offset:1024
	ds_read_b128 v[162:165], v166 offset:2048
	ds_read_b128 v[166:169], v166 offset:3072
	ds_read_b128 v[170:173], v200
	ds_read_b128 v[174:177], v200 offset:1024
	ds_read_b128 v[178:181], v200 offset:2048
	ds_read_b128 v[200:203], v200 offset:3072
	s_add_u32 s20, s20, 0x40000
	s_addc_u32 s21, s21, 0
	s_mov_b32 m0, s27
	v_lshl_add_u64 v[238:239], s[20:21], 0, v[134:135]
	ds_read_b128 v[204:207], v145 offset:32768
	ds_read_b128 v[208:211], v145 offset:33792
	ds_read_b128 v[212:215], v145 offset:34816
	ds_read_b128 v[216:219], v145 offset:35840
	ds_read_b128 v[220:223], v145 offset:36864
	ds_read_b128 v[224:227], v145 offset:37888
	ds_read_b128 v[228:231], v145 offset:38912
	ds_read_b128 v[232:235], v145 offset:39936
	global_load_lds_dwordx4 v[238:239], off
	v_lshl_add_u64 v[238:239], s[20:21], 0, v[132:133]
	s_mov_b32 m0, s28
	s_nop 0
	global_load_lds_dwordx4 v[238:239], off
	s_waitcnt vmcnt(8)
	s_waitcnt lgkmcnt(0)
	s_barrier
; #define PG8_STAGE(bufoff, gbase, voff) do { _Pragma("unroll") for (int _i = 0; _i < 2; ++_i) \
;         __builtin_amdgcn_global_load_lds((const unsigned*)((const char*)(gbase) + (voff)[_i]), (PG8_LAS unsigned*)(lds + (bufoff) + ldsw + _i * 8192), 16, 0, 0); } while (0)
; #define PG8_LDA(dst, b, h) do { _Pragma("unroll") for (int m = 0; m < 4; ++m) _Pragma("unroll") for (int k = 0; k < 2; ++k) dst[m][k] = *(const PG8_LAS bf16x8*)(lds + PG8_SA(b, h) + aoff + m * 2048 + k * 1024); } while (0)
; #define PG8_LDB(dst, b, h) do { _Pragma("unroll") for (int n = 0; n < 2; ++n) _Pragma("unroll") for (int k = 0; k < 2; ++k) dst[n][k] = *(const PG8_LAS bf16x8*)(lds + PG8_SB(b, h) + boff + n * 2048 + k * 1024); } while (0)
; #define PG8_MMA(ai, bj, At, Bt) do { __builtin_amdgcn_s_setprio(1); _Pragma("unroll") for (int m = 0; m < 4; ++m) _Pragma("unroll") for (int n = 0; n < 2; ++n) _Pragma("unroll") for (int k = 0; k < 2; ++k) \
;         acc[ai][bj][m][n] = __builtin_amdgcn_mfma_f32_16x16x32_bf16(Bt[n][k], At[m][k], acc[ai][bj][m][n], 0, 0, 0); __builtin_amdgcn_s_setprio(0); } while (0)
; #define PG8_WAIT_V(n) asm volatile("s_waitcnt vmcnt(" #n ")" ::: "memory")
; #define PG8_WAIT_L(n) asm volatile("s_waitcnt lgkmcnt(" #n ")" ::: "memory")
; #define PG8_BAR __builtin_amdgcn_s_barrier()
; #define PG8_SCHED __builtin_amdgcn_sched_barrier(0)
; template <class Epi, class Sched, bool ALIGN_EPI = false, bool SP2 = false>
; __device__ __forceinline__ void gemm_phase(PG8_LAS unsigned char* lds, const Gemm g, const Sched& S, const Epi& E) {
;     ...
;         for (int t = 0; t < nt; t += 2) {
;     ...
;             PG8_LDB(B0, 1, 0); PG8_LDB(B1, 1, 1); PG8_SCHED; PG8_LDA(At, 1, 0); PG8_STAGE(PG8_SA(0, 1), a2 + hstep, voffA);
;             PG8_WAIT_V(8); PG8_WAIT_L(0); PG8_BAR; PG8_MMA(0, 0, At, B0); PG8_MMA(0, 1, At, B1); PG8_BAR; PG8_SCHED;
;             PG8_LDA(At, 1, 1); PG8_STAGE(PG8_SB(1, 0), b3, voffB); PG8_STAGE(PG8_SB(1, 1), b3 + hstep, voffB); PG8_STAGE(PG8_SA(1, 0), a3, voffA);
;             PG8_WAIT_V(8); PG8_WAIT_L(0); PG8_BAR; PG8_MMA(1, 0, At, B0); PG8_MMA(1, 1, At, B1); PG8_BAR; PG8_SCHED;
	s_setprio 1
	s_waitcnt lgkmcnt(0)
	v_mfma_f32_16x16x32_bf16 v[122:125], v[154:157], v[204:207], v[122:125]
	v_mfma_f32_16x16x32_bf16 v[114:117], v[162:165], v[204:207], v[114:117]
	v_mfma_f32_16x16x32_bf16 v[106:109], v[154:157], v[212:215], v[106:109]
	v_mfma_f32_16x16x32_bf16 v[98:101], v[162:165], v[212:215], v[98:101]
	v_mfma_f32_16x16x32_bf16 v[90:93], v[154:157], v[220:223], v[90:93]
	v_mfma_f32_16x16x32_bf16 v[82:85], v[162:165], v[220:223], v[82:85]
	v_mfma_f32_16x16x32_bf16 v[74:77], v[154:157], v[228:231], v[74:77]
	v_mfma_f32_16x16x32_bf16 v[66:69], v[162:165], v[228:231], v[66:69]
	v_mfma_f32_16x16x32_bf16 v[122:125], v[158:161], v[208:211], v[122:125]
	v_mfma_f32_16x16x32_bf16 v[114:117], v[166:169], v[208:211], v[114:117]
	v_mfma_f32_16x16x32_bf16 v[106:109], v[158:161], v[216:219], v[106:109]
	v_mfma_f32_16x16x32_bf16 v[98:101], v[166:169], v[216:219], v[98:101]
	v_mfma_f32_16x16x32_bf16 v[90:93], v[158:161], v[224:227], v[90:93]
	v_mfma_f32_16x16x32_bf16 v[82:85], v[166:169], v[224:227], v[82:85]
	v_mfma_f32_16x16x32_bf16 v[74:77], v[158:161], v[232:235], v[74:77]
	v_mfma_f32_16x16x32_bf16 v[66:69], v[166:169], v[232:235], v[66:69]
	s_setprio 0
	s_setprio 1
	v_mfma_f32_16x16x32_bf16 v[126:129], v[170:173], v[204:207], v[126:129]
	v_mfma_f32_16x16x32_bf16 v[118:121], v[178:181], v[204:207], v[118:121]
	v_mfma_f32_16x16x32_bf16 v[110:113], v[170:173], v[212:215], v[110:113]
	v_mfma_f32_16x16x32_bf16 v[102:105], v[178:181], v[212:215], v[102:105]
	v_mfma_f32_16x16x32_bf16 v[94:97], v[170:173], v[220:223], v[94:97]
	v_mfma_f32_16x16x32_bf16 v[86:89], v[178:181], v[220:223], v[86:89]
	v_mfma_f32_16x16x32_bf16 v[78:81], v[170:173], v[228:231], v[78:81]
	v_mfma_f32_16x16x32_bf16 v[70:73], v[178:181], v[228:231], v[70:73]
	v_mfma_f32_16x16x32_bf16 v[126:129], v[174:177], v[208:211], v[126:129]
	v_mfma_f32_16x16x32_bf16 v[118:121], v[200:203], v[208:211], v[118:121]
	v_mfma_f32_16x16x32_bf16 v[110:113], v[174:177], v[216:219], v[110:113]
	v_mfma_f32_16x16x32_bf16 v[102:105], v[200:203], v[216:219], v[102:105]
	v_mfma_f32_16x16x32_bf16 v[94:97], v[174:177], v[224:227], v[94:97]
	v_mfma_f32_16x16x32_bf16 v[86:89], v[200:203], v[224:227], v[86:89]
	v_mfma_f32_16x16x32_bf16 v[78:81], v[174:177], v[232:235], v[78:81]
	v_mfma_f32_16x16x32_bf16 v[70:73], v[200:203], v[232:235], v[70:73]
	s_barrier
	s_setprio 0
	s_add_i32 s20, s56, s24
	v_lshl_add_u64 v[140:141], v[140:141], 0, s[38:39]
	s_mov_b32 m0, s20
	ds_read_b128 v[204:207], v145 offset:49152
	ds_read_b128 v[208:211], v145 offset:50176
	ds_read_b128 v[212:215], v145 offset:51200
	ds_read_b128 v[216:219], v145 offset:52224
	ds_read_b128 v[220:223], v145 offset:53248
	ds_read_b128 v[224:227], v145 offset:54272
	ds_read_b128 v[228:231], v145 offset:55296
	ds_read_b128 v[232:235], v145 offset:56320
	global_load_lds_dwordx4 v[140:141], off
	s_add_i32 m0, s20, 0x2000
	s_add_u32 s18, s18, 0x40080
	v_lshl_add_u64 v[140:141], v[146:147], 0, s[38:39]
	s_addc_u32 s19, s19, 0
	s_add_i32 s20, s57, s24
	global_load_lds_dwordx4 v[140:141], off
	v_lshl_add_u64 v[140:141], s[18:19], 0, v[0:1]
	s_mov_b32 m0, s20
	s_nop 0
	global_load_lds_dwordx4 v[140:141], off
	v_lshl_add_u64 v[140:141], s[18:19], 0, v[130:131]
	s_add_i32 m0, s20, 0x2000
	s_nop 0
	global_load_lds_dwordx4 v[140:141], off
	v_lshl_add_u64 v[140:141], v[148:149], 0, s[38:39]
	s_mov_b32 m0, s29
	s_nop 0
	global_load_lds_dwordx4 v[140:141], off
	v_lshl_add_u64 v[140:141], v[236:237], 0, s[38:39]
	s_mov_b32 m0, s30
	s_nop 0
	global_load_lds_dwordx4 v[140:141], off
	s_waitcnt vmcnt(8)
	s_waitcnt lgkmcnt(0)
	s_barrier
	s_setprio 1
	s_waitcnt lgkmcnt(0)
	v_mfma_f32_16x16x32_bf16 v[58:61], v[154:157], v[204:207], v[58:61]
	v_mfma_f32_16x16x32_bf16 v[50:53], v[162:165], v[204:207], v[50:53]
	v_mfma_f32_16x16x32_bf16 v[42:45], v[154:157], v[212:215], v[42:45]
	v_mfma_f32_16x16x32_bf16 v[34:37], v[162:165], v[212:215], v[34:37]
	v_mfma_f32_16x16x32_bf16 v[26:29], v[154:157], v[220:223], v[26:29]
	v_mfma_f32_16x16x32_bf16 v[18:21], v[162:165], v[220:223], v[18:21]
	v_mfma_f32_16x16x32_bf16 v[10:13], v[154:157], v[228:231], v[10:13]
	v_mfma_f32_16x16x32_bf16 v[2:5], v[162:165], v[228:231], v[2:5]
	v_mfma_f32_16x16x32_bf16 v[58:61], v[158:161], v[208:211], v[58:61]
	v_mfma_f32_16x16x32_bf16 v[50:53], v[166:169], v[208:211], v[50:53]
	v_mfma_f32_16x16x32_bf16 v[42:45], v[158:161], v[216:219], v[42:45]
	v_mfma_f32_16x16x32_bf16 v[34:37], v[166:169], v[216:219], v[34:37]
	v_mfma_f32_16x16x32_bf16 v[26:29], v[158:161], v[224:227], v[26:29]
	v_mfma_f32_16x16x32_bf16 v[18:21], v[166:169], v[224:227], v[18:21]
	v_mfma_f32_16x16x32_bf16 v[10:13], v[158:161], v[232:235], v[10:13]
	v_mfma_f32_16x16x32_bf16 v[2:5], v[166:169], v[232:235], v[2:5]
	s_setprio 0
	s_setprio 1
	v_mfma_f32_16x16x32_bf16 v[62:65], v[170:173], v[204:207], v[62:65]
	v_mfma_f32_16x16x32_bf16 v[54:57], v[178:181], v[204:207], v[54:57]
	v_mfma_f32_16x16x32_bf16 v[46:49], v[170:173], v[212:215], v[46:49]
	v_mfma_f32_16x16x32_bf16 v[38:41], v[178:181], v[212:215], v[38:41]
	v_mfma_f32_16x16x32_bf16 v[30:33], v[170:173], v[220:223], v[30:33]
	v_mfma_f32_16x16x32_bf16 v[22:25], v[178:181], v[220:223], v[22:25]
	v_mfma_f32_16x16x32_bf16 v[14:17], v[170:173], v[228:231], v[14:17]
	v_mfma_f32_16x16x32_bf16 v[6:9], v[178:181], v[228:231], v[6:9]
	v_mfma_f32_16x16x32_bf16 v[62:65], v[174:177], v[208:211], v[62:65]
	v_mfma_f32_16x16x32_bf16 v[54:57], v[200:203], v[208:211], v[54:57]
	v_mfma_f32_16x16x32_bf16 v[46:49], v[174:177], v[216:219], v[46:49]
	v_mfma_f32_16x16x32_bf16 v[38:41], v[200:203], v[216:219], v[38:41]
	v_mfma_f32_16x16x32_bf16 v[30:33], v[174:177], v[224:227], v[30:33]
	v_mfma_f32_16x16x32_bf16 v[22:25], v[200:203], v[224:227], v[22:25]
	v_mfma_f32_16x16x32_bf16 v[14:17], v[174:177], v[232:235], v[14:17]
	v_mfma_f32_16x16x32_bf16 v[6:9], v[200:203], v[232:235], v[6:9]
	s_barrier
	s_setprio 0
	s_add_i32 s55, s55, 2
	s_add_u32 s16, s16, 0x100
	s_addc_u32 s17, s17, 0
	s_add_u32 s52, s52, 0x100
	s_addc_u32 s53, s53, 0
	s_cmp_gt_u32 s55, 13
	s_cbranch_scc0 .LBB0_368
	s_and_b64 vcc, exec, s[6:7]
	s_cbranch_vccz .LBB0_371
	s_barrier

; #define PG8_STAGE(bufoff, gbase, voff) do { _Pragma("unroll") for (int _i = 0; _i < 2; ++_i) \
;         __builtin_amdgcn_global_load_lds((const unsigned*)((const char*)(gbase) + (voff)[_i]), (PG8_LAS unsigned*)(lds + (bufoff) + ldsw + _i * 8192), 16, 0, 0); } while (0)
; #define PG8_LDA(dst, b, h) do { _Pragma("unroll") for (int m = 0; m < 4; ++m) _Pragma("unroll") for (int k = 0; k < 2; ++k) dst[m][k] = *(const PG8_LAS bf16x8*)(lds + PG8_SA(b, h) + aoff + m * 2048 + k * 1024); } while (0)
; #define PG8_LDB(dst, b, h) do { _Pragma("unroll") for (int n = 0; n < 2; ++n) _Pragma("unroll") for (int k = 0; k < 2; ++k) dst[n][k] = *(const PG8_LAS bf16x8*)(lds + PG8_SB(b, h) + boff + n * 2048 + k * 1024); } while (0)
; #define PG8_WAIT_V(n) asm volatile("s_waitcnt vmcnt(" #n ")" ::: "memory")
; #define PG8_WAIT_L(n) asm volatile("s_waitcnt lgkmcnt(" #n ")" ::: "memory")
; #define PG8_BAR __builtin_amdgcn_s_barrier()
; #define PG8_SCHED __builtin_amdgcn_sched_barrier(0)
; template <class Epi, class Sched, bool ALIGN_EPI = false, bool SP2 = false>
; __device__ __forceinline__ void gemm_phase(PG8_LAS unsigned char* lds, const Gemm g, const Sched& S, const Epi& E) {
;     ...
;         const bool has_next = S.next(ui + 1, nxt);
;         const char* nA = has_next ? (const char*)g.A + (size_t)nxt.pm * tstep : cA; const char* nB = has_next ? (const char*)g.Bt + (size_t)nxt.pn * tstep : cB;
;         for (int t = 0; t < nt; t += 2) {
;             const bool last = (t == nt - 2);
;             const char* a1 = cA + (size_t)(t + 1) * kstep;
;             const char* a2 = last ? nA : cA + (size_t)(t + 2) * kstep; const char* b2 = last ? nB : cB + (size_t)(t + 2) * kstep;
;             const char* a3 = a2 + kstep; const char* b3 = b2 + kstep;
;             if (last && has_next) S.a_ready(nxt);
;             if constexpr (SP2) {
;             PG8_LDB(B0, 0, 0); PG8_LDB(B1, 0, 1); PG8_SCHED; PG8_LDA(At, 0, 0); PG8_STAGE(PG8_SA(1, 1), a1 + hstep, voffA);
;             PG8_WAIT_V(8); PG8_WAIT_L(0); PG8_BAR; PG8_MMA(0, 0, At, B0); PG8_MMA(0, 1, At, B1); PG8_BAR; PG8_SCHED;
;             PG8_LDA(At, 0, 1); PG8_STAGE(PG8_SB(0, 0), b2, voffB); PG8_STAGE(PG8_SB(0, 1), b2 + hstep, voffB); PG8_STAGE(PG8_SA(0, 0), a2, voffA);
;             PG8_WAIT_V(8); PG8_WAIT_L(0); PG8_BAR; PG8_MMA(1, 0, At, B0); PG8_MMA(1, 1, At, B1); PG8_BAR; PG8_SCHED;
.LBB0_431:
	s_ashr_i32 s11, s10, 31
	s_lshl_b64 s[12:13], s[10:11], 21
	s_add_u32 s12, s92, s12
	s_addc_u32 s13, s93, s13
	s_and_b64 s[14:15], s[4:5], exec
	s_cselect_b32 s11, s13, s17
	s_cselect_b32 s51, s12, s16
	s_ashr_i32 s9, s8, 31
	s_lshl_b64 s[14:15], s[8:9], 21
	s_add_u32 s14, s22, s14
	s_addc_u32 s15, s23, s15
	s_and_b64 s[20:21], s[4:5], exec
	s_cselect_b32 s9, s15, s19
	s_cselect_b32 s52, s14, s18
	s_add_u32 s16, s16, 0x100080
	s_addc_u32 s17, s17, 0
	s_add_u32 s53, s18, 0x100
	s_addc_u32 s54, s19, 0
	s_mov_b32 s55, -2
	s_add_u32 s18, s16, 0xfff00080
	s_addc_u32 s19, s17, -1
	s_add_i32 s56, 0, 0x10000
	s_cmp_eq_u32 s55, 60
	s_cselect_b32 s21, s11, s19
	s_cselect_b32 s20, s51, s18
	s_cselect_b32 s19, s9, s54
	s_cselect_b32 s18, s52, s53
	s_add_i32 s58, 0, 0x14000
	v_lshl_add_u64 v[146:147], s[16:17], 0, v[160:161]
	s_add_i32 m0, s25, 0xc000
	global_load_lds_dwordx4 v[146:147], off
	v_lshl_add_u64 v[146:147], s[16:17], 0, v[162:163]
	s_add_i32 m0, s25, 0xe000
	s_nop 0
	global_load_lds_dwordx4 v[146:147], off
	s_waitcnt vmcnt(20)
	s_waitcnt lgkmcnt(0)
	s_barrier
	s_setprio 1
	s_waitcnt lgkmcnt(0)
	v_mfma_f32_16x16x32_bf16 v[126:129], v[130:133], v[204:207], 0
	v_mfma_f32_16x16x32_bf16 v[122:125], v[138:141], v[204:207], 0
	v_mfma_f32_16x16x32_bf16 v[118:121], v[130:133], v[212:215], 0
	v_mfma_f32_16x16x32_bf16 v[114:117], v[138:141], v[212:215], 0
	v_mfma_f32_16x16x32_bf16 v[110:113], v[130:133], v[220:223], 0
	v_mfma_f32_16x16x32_bf16 v[106:109], v[138:141], v[220:223], 0
	v_mfma_f32_16x16x32_bf16 v[102:105], v[130:133], v[228:231], 0
	v_mfma_f32_16x16x32_bf16 v[98:101], v[138:141], v[228:231], 0
	v_mfma_f32_16x16x32_bf16 v[126:129], v[134:137], v[208:211], v[126:129]
	v_mfma_f32_16x16x32_bf16 v[122:125], v[142:145], v[208:211], v[122:125]
	v_mfma_f32_16x16x32_bf16 v[118:121], v[134:137], v[216:219], v[118:121]
	v_mfma_f32_16x16x32_bf16 v[114:117], v[142:145], v[216:219], v[114:117]
	v_mfma_f32_16x16x32_bf16 v[110:113], v[134:137], v[224:227], v[110:113]
	v_mfma_f32_16x16x32_bf16 v[106:109], v[142:145], v[224:227], v[106:109]
	v_mfma_f32_16x16x32_bf16 v[102:105], v[134:137], v[232:235], v[102:105]
	v_mfma_f32_16x16x32_bf16 v[98:101], v[142:145], v[232:235], v[98:101]
	s_setprio 0
	s_setprio 1
	v_mfma_f32_16x16x32_bf16 v[62:65], v[164:167], v[204:207], 0
	v_mfma_f32_16x16x32_bf16 v[58:61], v[172:175], v[204:207], 0
	v_mfma_f32_16x16x32_bf16 v[54:57], v[164:167], v[212:215], 0
	v_mfma_f32_16x16x32_bf16 v[50:53], v[172:175], v[212:215], 0
	v_mfma_f32_16x16x32_bf16 v[46:49], v[164:167], v[220:223], 0
	v_mfma_f32_16x16x32_bf16 v[42:45], v[172:175], v[220:223], 0
	v_mfma_f32_16x16x32_bf16 v[38:41], v[164:167], v[228:231], 0
	v_mfma_f32_16x16x32_bf16 v[34:37], v[172:175], v[228:231], 0
	v_mfma_f32_16x16x32_bf16 v[62:65], v[168:171], v[208:211], v[62:65]
	v_mfma_f32_16x16x32_bf16 v[58:61], v[176:179], v[208:211], v[58:61]
	v_mfma_f32_16x16x32_bf16 v[54:57], v[168:171], v[216:219], v[54:57]
	v_mfma_f32_16x16x32_bf16 v[50:53], v[176:179], v[216:219], v[50:53]
	v_mfma_f32_16x16x32_bf16 v[46:49], v[168:171], v[224:227], v[46:49]
	v_mfma_f32_16x16x32_bf16 v[42:45], v[176:179], v[224:227], v[42:45]
	v_mfma_f32_16x16x32_bf16 v[38:41], v[168:171], v[232:235], v[38:41]
	v_mfma_f32_16x16x32_bf16 v[34:37], v[176:179], v[232:235], v[34:37]
	s_barrier
	s_setprio 0
	s_add_i32 s56, s56, s24
	v_lshl_add_u64 v[146:147], s[18:19], 0, v[0:1]
	s_mov_b32 m0, s56
	ds_read_b128 v[204:207], v203 offset:16384
	ds_read_b128 v[208:211], v203 offset:17408
	ds_read_b128 v[212:215], v203 offset:18432
	ds_read_b128 v[216:219], v203 offset:19456
	ds_read_b128 v[220:223], v203 offset:20480
	ds_read_b128 v[224:227], v203 offset:21504
	ds_read_b128 v[228:231], v203 offset:22528
	ds_read_b128 v[232:235], v203 offset:23552
	global_load_lds_dwordx4 v[146:147], off
	s_add_i32 m0, s56, 0x2000
	s_add_u32 s56, s18, 0x100000
	v_lshl_add_u64 v[148:149], s[18:19], 0, v[154:155]
	s_addc_u32 s57, s19, 0
	s_add_i32 s58, s58, s24
	global_load_lds_dwordx4 v[148:149], off
	v_lshl_add_u64 v[180:181], s[56:57], 0, v[0:1]
	s_mov_b32 m0, s58
	v_lshl_add_u64 v[236:237], s[20:21], 0, v[156:157]
	global_load_lds_dwordx4 v[180:181], off
	v_lshl_add_u64 v[180:181], s[56:57], 0, v[154:155]
	s_add_i32 m0, s58, 0x2000
	s_nop 0
	global_load_lds_dwordx4 v[180:181], off
	v_lshl_add_u64 v[180:181], s[20:21], 0, v[158:159]
	s_mov_b32 m0, s25
	s_nop 0
	global_load_lds_dwordx4 v[180:181], off
	s_mov_b32 m0, s26
	s_nop 0
	global_load_lds_dwordx4 v[236:237], off
	s_waitcnt vmcnt(20)
	s_waitcnt lgkmcnt(0)
	s_barrier
	s_setprio 1
	s_waitcnt lgkmcnt(0)
	v_mfma_f32_16x16x32_bf16 v[94:97], v[130:133], v[204:207], 0
	v_mfma_f32_16x16x32_bf16 v[90:93], v[138:141], v[204:207], 0
	v_mfma_f32_16x16x32_bf16 v[86:89], v[130:133], v[212:215], 0
	v_mfma_f32_16x16x32_bf16 v[82:85], v[138:141], v[212:215], 0
	v_mfma_f32_16x16x32_bf16 v[78:81], v[130:133], v[220:223], 0
	v_mfma_f32_16x16x32_bf16 v[74:77], v[138:141], v[220:223], 0
	v_mfma_f32_16x16x32_bf16 v[70:73], v[130:133], v[228:231], 0
	v_mfma_f32_16x16x32_bf16 v[66:69], v[138:141], v[228:231], 0
	v_mfma_f32_16x16x32_bf16 v[94:97], v[134:137], v[208:211], v[94:97]
	v_mfma_f32_16x16x32_bf16 v[90:93], v[142:145], v[208:211], v[90:93]
	v_mfma_f32_16x16x32_bf16 v[86:89], v[134:137], v[216:219], v[86:89]
	v_mfma_f32_16x16x32_bf16 v[82:85], v[142:145], v[216:219], v[82:85]
	v_mfma_f32_16x16x32_bf16 v[78:81], v[134:137], v[224:227], v[78:81]
	v_mfma_f32_16x16x32_bf16 v[74:77], v[142:145], v[224:227], v[74:77]
	v_mfma_f32_16x16x32_bf16 v[70:73], v[134:137], v[232:235], v[70:73]
	v_mfma_f32_16x16x32_bf16 v[66:69], v[142:145], v[232:235], v[66:69]
	s_setprio 0
	s_setprio 1
	v_mfma_f32_16x16x32_bf16 v[30:33], v[164:167], v[204:207], 0
	v_mfma_f32_16x16x32_bf16 v[26:29], v[172:175], v[204:207], 0
	v_mfma_f32_16x16x32_bf16 v[22:25], v[164:167], v[212:215], 0
	v_mfma_f32_16x16x32_bf16 v[18:21], v[172:175], v[212:215], 0
	v_mfma_f32_16x16x32_bf16 v[14:17], v[164:167], v[220:223], 0
	v_mfma_f32_16x16x32_bf16 v[10:13], v[172:175], v[220:223], 0
	v_mfma_f32_16x16x32_bf16 v[6:9], v[164:167], v[228:231], 0
	v_mfma_f32_16x16x32_bf16 v[2:5], v[172:175], v[228:231], 0
	v_mfma_f32_16x16x32_bf16 v[30:33], v[168:171], v[208:211], v[30:33]
	v_mfma_f32_16x16x32_bf16 v[26:29], v[176:179], v[208:211], v[26:29]
	v_mfma_f32_16x16x32_bf16 v[22:25], v[168:171], v[216:219], v[22:25]
	v_mfma_f32_16x16x32_bf16 v[18:21], v[176:179], v[216:219], v[18:21]
	v_mfma_f32_16x16x32_bf16 v[14:17], v[168:171], v[224:227], v[14:17]
	v_mfma_f32_16x16x32_bf16 v[10:13], v[176:179], v[224:227], v[10:13]
	v_mfma_f32_16x16x32_bf16 v[6:9], v[168:171], v[232:235], v[6:9]
	v_mfma_f32_16x16x32_bf16 v[2:5], v[176:179], v[232:235], v[2:5]
	s_barrier
; #define PG8_STAGE(bufoff, gbase, voff) do { _Pragma("unroll") for (int _i = 0; _i < 2; ++_i) \
;         __builtin_amdgcn_global_load_lds((const unsigned*)((const char*)(gbase) + (voff)[_i]), (PG8_LAS unsigned*)(lds + (bufoff) + ldsw + _i * 8192), 16, 0, 0); } while (0)
; #define PG8_LDA(dst, b, h) do { _Pragma("unroll") for (int m = 0; m < 4; ++m) _Pragma("unroll") for (int k = 0; k < 2; ++k) dst[m][k] = *(const PG8_LAS bf16x8*)(lds + PG8_SA(b, h) + aoff + m * 2048 + k * 1024); } while (0)
; #define PG8_LDB(dst, b, h) do { _Pragma("unroll") for (int n = 0; n < 2; ++n) _Pragma("unroll") for (int k = 0; k < 2; ++k) dst[n][k] = *(const PG8_LAS bf16x8*)(lds + PG8_SB(b, h) + boff + n * 2048 + k * 1024); } while (0)
; #define PG8_MMA(ai, bj, At, Bt) do { __builtin_amdgcn_s_setprio(1); _Pragma("unroll") for (int m = 0; m < 4; ++m) _Pragma("unroll") for (int n = 0; n < 2; ++n) _Pragma("unroll") for (int k = 0; k < 2; ++k) \
;         acc[ai][bj][m][n] = __builtin_amdgcn_mfma_f32_16x16x32_bf16(Bt[n][k], At[m][k], acc[ai][bj][m][n], 0, 0, 0); __builtin_amdgcn_s_setprio(0); } while (0)
; #define PG8_WAIT_V(n) asm volatile("s_waitcnt vmcnt(" #n ")" ::: "memory")
; #define PG8_WAIT_L(n) asm volatile("s_waitcnt lgkmcnt(" #n ")" ::: "memory")
; #define PG8_BAR __builtin_amdgcn_s_barrier()
; #define PG8_SCHED __builtin_amdgcn_sched_barrier(0)
; template <class Epi, class Sched, bool ALIGN_EPI = false, bool SP2 = false>
; __device__ __forceinline__ void gemm_phase(PG8_LAS unsigned char* lds, const Gemm g, const Sched& S, const Epi& E) {
;     ...
;             PG8_LDB(B0, 1, 0); PG8_LDB(B1, 1, 1); PG8_SCHED; PG8_LDA(At, 1, 0); PG8_STAGE(PG8_SA(0, 1), a2 + hstep, voffA);
;             PG8_WAIT_V(8); PG8_WAIT_L(0); PG8_BAR; PG8_MMA(0, 0, At, B0); PG8_MMA(0, 1, At, B1); PG8_BAR; PG8_SCHED;
;             PG8_LDA(At, 1, 1); PG8_STAGE(PG8_SB(1, 0), b3, voffB); PG8_STAGE(PG8_SB(1, 1), b3 + hstep, voffB); PG8_STAGE(PG8_SA(1, 0), a3, voffA);
;             PG8_WAIT_V(8); PG8_WAIT_L(0); PG8_BAR; PG8_MMA(1, 0, At, B0); PG8_MMA(1, 1, At, B1); PG8_BAR; PG8_SCHED;
	s_setprio 0
	s_add_i32 s56, 0, 0x18000
	s_add_i32 s57, 0, 0x1c000
	v_add_u32_e32 v142, s56, v201
	v_add_u32_e32 v176, s57, v201
	ds_read_b128 v[130:133], v142
	ds_read_b128 v[134:137], v142 offset:1024
	ds_read_b128 v[138:141], v142 offset:2048
	ds_read_b128 v[142:145], v142 offset:3072
	ds_read_b128 v[164:167], v176
	ds_read_b128 v[168:171], v176 offset:1024
	ds_read_b128 v[172:175], v176 offset:2048
	ds_read_b128 v[176:179], v176 offset:3072
	s_add_u32 s20, s20, 0x100000
	s_addc_u32 s21, s21, 0
	s_mov_b32 m0, s27
	v_lshl_add_u64 v[238:239], s[20:21], 0, v[158:159]
	ds_read_b128 v[204:207], v203 offset:32768
	ds_read_b128 v[208:211], v203 offset:33792
	ds_read_b128 v[212:215], v203 offset:34816
	ds_read_b128 v[216:219], v203 offset:35840
	ds_read_b128 v[220:223], v203 offset:36864
	ds_read_b128 v[224:227], v203 offset:37888
	ds_read_b128 v[228:231], v203 offset:38912
	ds_read_b128 v[232:235], v203 offset:39936
	global_load_lds_dwordx4 v[238:239], off
	v_lshl_add_u64 v[238:239], s[20:21], 0, v[156:157]
	s_mov_b32 m0, s28
	s_nop 0
	global_load_lds_dwordx4 v[238:239], off
	s_waitcnt vmcnt(8)
	s_waitcnt lgkmcnt(0)
	s_barrier
	s_setprio 1
	s_waitcnt lgkmcnt(0)
	v_mfma_f32_16x16x32_bf16 v[126:129], v[130:133], v[204:207], v[126:129]
	v_mfma_f32_16x16x32_bf16 v[122:125], v[138:141], v[204:207], v[122:125]
	v_mfma_f32_16x16x32_bf16 v[118:121], v[130:133], v[212:215], v[118:121]
	v_mfma_f32_16x16x32_bf16 v[114:117], v[138:141], v[212:215], v[114:117]
	v_mfma_f32_16x16x32_bf16 v[110:113], v[130:133], v[220:223], v[110:113]
	v_mfma_f32_16x16x32_bf16 v[106:109], v[138:141], v[220:223], v[106:109]
	v_mfma_f32_16x16x32_bf16 v[102:105], v[130:133], v[228:231], v[102:105]
	v_mfma_f32_16x16x32_bf16 v[98:101], v[138:141], v[228:231], v[98:101]
	v_mfma_f32_16x16x32_bf16 v[126:129], v[134:137], v[208:211], v[126:129]
	v_mfma_f32_16x16x32_bf16 v[122:125], v[142:145], v[208:211], v[122:125]
	v_mfma_f32_16x16x32_bf16 v[118:121], v[134:137], v[216:219], v[118:121]
	v_mfma_f32_16x16x32_bf16 v[114:117], v[142:145], v[216:219], v[114:117]
	v_mfma_f32_16x16x32_bf16 v[110:113], v[134:137], v[224:227], v[110:113]
	v_mfma_f32_16x16x32_bf16 v[106:109], v[142:145], v[224:227], v[106:109]
	v_mfma_f32_16x16x32_bf16 v[102:105], v[134:137], v[232:235], v[102:105]
	v_mfma_f32_16x16x32_bf16 v[98:101], v[142:145], v[232:235], v[98:101]
	s_setprio 0
	s_setprio 1
	v_mfma_f32_16x16x32_bf16 v[62:65], v[164:167], v[204:207], v[62:65]
	v_mfma_f32_16x16x32_bf16 v[58:61], v[172:175], v[204:207], v[58:61]
	v_mfma_f32_16x16x32_bf16 v[54:57], v[164:167], v[212:215], v[54:57]
	v_mfma_f32_16x16x32_bf16 v[50:53], v[172:175], v[212:215], v[50:53]
	v_mfma_f32_16x16x32_bf16 v[46:49], v[164:167], v[220:223], v[46:49]
	v_mfma_f32_16x16x32_bf16 v[42:45], v[172:175], v[220:223], v[42:45]
	v_mfma_f32_16x16x32_bf16 v[38:41], v[164:167], v[228:231], v[38:41]
	v_mfma_f32_16x16x32_bf16 v[34:37], v[172:175], v[228:231], v[34:37]
	v_mfma_f32_16x16x32_bf16 v[62:65], v[168:171], v[208:211], v[62:65]
	v_mfma_f32_16x16x32_bf16 v[58:61], v[176:179], v[208:211], v[58:61]
	v_mfma_f32_16x16x32_bf16 v[54:57], v[168:171], v[216:219], v[54:57]
	v_mfma_f32_16x16x32_bf16 v[50:53], v[176:179], v[216:219], v[50:53]
	v_mfma_f32_16x16x32_bf16 v[46:49], v[168:171], v[224:227], v[46:49]
	v_mfma_f32_16x16x32_bf16 v[42:45], v[176:179], v[224:227], v[42:45]
	v_mfma_f32_16x16x32_bf16 v[38:41], v[168:171], v[232:235], v[38:41]
	v_mfma_f32_16x16x32_bf16 v[34:37], v[176:179], v[232:235], v[34:37]
	s_barrier
	s_setprio 0
	s_add_i32 s20, s56, s24
	v_lshl_add_u64 v[146:147], v[146:147], 0, s[38:39]
	s_mov_b32 m0, s20
	ds_read_b128 v[204:207], v203 offset:49152
	ds_read_b128 v[208:211], v203 offset:50176
	ds_read_b128 v[212:215], v203 offset:51200
	ds_read_b128 v[216:219], v203 offset:52224
	ds_read_b128 v[220:223], v203 offset:53248
	ds_read_b128 v[224:227], v203 offset:54272
	ds_read_b128 v[228:231], v203 offset:55296
	ds_read_b128 v[232:235], v203 offset:56320
	global_load_lds_dwordx4 v[146:147], off
	s_add_i32 m0, s20, 0x2000
	s_add_u32 s18, s18, 0x100080
	v_lshl_add_u64 v[146:147], v[148:149], 0, s[38:39]
	s_addc_u32 s19, s19, 0
	s_add_i32 s20, s57, s24
	global_load_lds_dwordx4 v[146:147], off
	v_lshl_add_u64 v[146:147], s[18:19], 0, v[0:1]
	s_mov_b32 m0, s20
	s_nop 0
	global_load_lds_dwordx4 v[146:147], off
	v_lshl_add_u64 v[146:147], s[18:19], 0, v[154:155]
	s_add_i32 m0, s20, 0x2000
	s_nop 0
	global_load_lds_dwordx4 v[146:147], off
	v_lshl_add_u64 v[146:147], v[180:181], 0, s[38:39]
	s_mov_b32 m0, s31
	s_nop 0
	global_load_lds_dwordx4 v[146:147], off
	v_lshl_add_u64 v[146:147], v[236:237], 0, s[38:39]
	s_mov_b32 m0, s33
	s_nop 0
	global_load_lds_dwordx4 v[146:147], off
	s_waitcnt vmcnt(8)
	s_waitcnt lgkmcnt(0)
	s_barrier
; #define PG8_STAGE(bufoff, gbase, voff) do { _Pragma("unroll") for (int _i = 0; _i < 2; ++_i) \
;         __builtin_amdgcn_global_load_lds((const unsigned*)((const char*)(gbase) + (voff)[_i]), (PG8_LAS unsigned*)(lds + (bufoff) + ldsw + _i * 8192), 16, 0, 0); } while (0)
; #define PG8_LDA(dst, b, h) do { _Pragma("unroll") for (int m = 0; m < 4; ++m) _Pragma("unroll") for (int k = 0; k < 2; ++k) dst[m][k] = *(const PG8_LAS bf16x8*)(lds + PG8_SA(b, h) + aoff + m * 2048 + k * 1024); } while (0)
; #define PG8_LDB(dst, b, h) do { _Pragma("unroll") for (int n = 0; n < 2; ++n) _Pragma("unroll") for (int k = 0; k < 2; ++k) dst[n][k] = *(const PG8_LAS bf16x8*)(lds + PG8_SB(b, h) + boff + n * 2048 + k * 1024); } while (0)
; #define PG8_BAR __builtin_amdgcn_s_barrier()
; template <class Epi, class Sched, bool ALIGN_EPI = false, bool SP2 = false>
; __device__ __forceinline__ void gemm_phase(PG8_LAS unsigned char* lds, const Gemm g, const Sched& S, const Epi& E) {
;     ...
;             const bool last = (t == nt - 2);
;             const char* a1 = cA + (size_t)(t + 1) * kstep;
;             const char* a2 = last ? nA : cA + (size_t)(t + 2) * kstep; const char* b2 = last ? nB : cB + (size_t)(t + 2) * kstep;
;             const char* a3 = a2 + kstep; const char* b3 = b2 + kstep;
;             if (last && has_next) S.a_ready(nxt);
;             if constexpr (SP2) {
;             PG8_LDB(B0, 0, 0); PG8_LDB(B1, 0, 1); PG8_SCHED; PG8_LDA(At, 0, 0); PG8_STAGE(PG8_SA(1, 1), a1 + hstep, voffA);
;             PG8_WAIT_V(8); PG8_WAIT_L(0); PG8_BAR; PG8_MMA(0, 0, At, B0); PG8_MMA(0, 1, At, B1); PG8_BAR; PG8_SCHED;
;             PG8_LDA(At, 0, 1); PG8_STAGE(PG8_SB(0, 0), b2, voffB); PG8_STAGE(PG8_SB(0, 1), b2 + hstep, voffB); PG8_STAGE(PG8_SA(0, 0), a2, voffA);
;             PG8_WAIT_V(8); PG8_WAIT_L(0); PG8_BAR; PG8_MMA(1, 0, At, B0); PG8_MMA(1, 1, At, B1); PG8_BAR; PG8_SCHED;
;             PG8_LDB(B0, 1, 0); PG8_LDB(B1, 1, 1); PG8_SCHED; PG8_LDA(At, 1, 0); PG8_STAGE(PG8_SA(0, 1), a2 + hstep, voffA);
;             PG8_WAIT_V(8); PG8_WAIT_L(0); PG8_BAR; PG8_MMA(0, 0, At, B0); PG8_MMA(0, 1, At, B1); PG8_BAR; PG8_SCHED;
;             PG8_LDA(At, 1, 1); PG8_STAGE(PG8_SB(1, 0), b3, voffB); PG8_STAGE(PG8_SB(1, 1), b3 + hstep, voffB); PG8_STAGE(PG8_SA(1, 0), a3, voffA);
;             PG8_WAIT_V(8); PG8_WAIT_L(0); PG8_BAR; PG8_MMA(1, 0, At, B0); PG8_MMA(1, 1, At, B1); PG8_BAR; PG8_SCHED;
	s_setprio 1
	s_waitcnt lgkmcnt(0)
	v_mfma_f32_16x16x32_bf16 v[94:97], v[130:133], v[204:207], v[94:97]
	v_mfma_f32_16x16x32_bf16 v[90:93], v[138:141], v[204:207], v[90:93]
	v_mfma_f32_16x16x32_bf16 v[86:89], v[130:133], v[212:215], v[86:89]
	v_mfma_f32_16x16x32_bf16 v[82:85], v[138:141], v[212:215], v[82:85]
	v_mfma_f32_16x16x32_bf16 v[78:81], v[130:133], v[220:223], v[78:81]
	v_mfma_f32_16x16x32_bf16 v[74:77], v[138:141], v[220:223], v[74:77]
	v_mfma_f32_16x16x32_bf16 v[70:73], v[130:133], v[228:231], v[70:73]
	v_mfma_f32_16x16x32_bf16 v[66:69], v[138:141], v[228:231], v[66:69]
	v_mfma_f32_16x16x32_bf16 v[94:97], v[134:137], v[208:211], v[94:97]
	v_mfma_f32_16x16x32_bf16 v[90:93], v[142:145], v[208:211], v[90:93]
	v_mfma_f32_16x16x32_bf16 v[86:89], v[134:137], v[216:219], v[86:89]
	v_mfma_f32_16x16x32_bf16 v[82:85], v[142:145], v[216:219], v[82:85]
	v_mfma_f32_16x16x32_bf16 v[78:81], v[134:137], v[224:227], v[78:81]
	v_mfma_f32_16x16x32_bf16 v[74:77], v[142:145], v[224:227], v[74:77]
	v_mfma_f32_16x16x32_bf16 v[70:73], v[134:137], v[232:235], v[70:73]
	v_mfma_f32_16x16x32_bf16 v[66:69], v[142:145], v[232:235], v[66:69]
	s_setprio 0
	s_setprio 1
	v_mfma_f32_16x16x32_bf16 v[30:33], v[164:167], v[204:207], v[30:33]
	v_mfma_f32_16x16x32_bf16 v[26:29], v[172:175], v[204:207], v[26:29]
	v_mfma_f32_16x16x32_bf16 v[22:25], v[164:167], v[212:215], v[22:25]
	v_mfma_f32_16x16x32_bf16 v[18:21], v[172:175], v[212:215], v[18:21]
	v_mfma_f32_16x16x32_bf16 v[14:17], v[164:167], v[220:223], v[14:17]
	v_mfma_f32_16x16x32_bf16 v[10:13], v[172:175], v[220:223], v[10:13]
	v_mfma_f32_16x16x32_bf16 v[6:9], v[164:167], v[228:231], v[6:9]
	v_mfma_f32_16x16x32_bf16 v[2:5], v[172:175], v[228:231], v[2:5]
	v_mfma_f32_16x16x32_bf16 v[30:33], v[168:171], v[208:211], v[30:33]
	v_mfma_f32_16x16x32_bf16 v[26:29], v[176:179], v[208:211], v[26:29]
	v_mfma_f32_16x16x32_bf16 v[22:25], v[168:171], v[216:219], v[22:25]
	v_mfma_f32_16x16x32_bf16 v[18:21], v[176:179], v[216:219], v[18:21]
	v_mfma_f32_16x16x32_bf16 v[14:17], v[168:171], v[224:227], v[14:17]
	v_mfma_f32_16x16x32_bf16 v[10:13], v[176:179], v[224:227], v[10:13]
	v_mfma_f32_16x16x32_bf16 v[6:9], v[168:171], v[232:235], v[6:9]
	v_mfma_f32_16x16x32_bf16 v[2:5], v[176:179], v[232:235], v[2:5]
	s_barrier
	s_setprio 0
	s_add_i32 s55, s55, 2
	s_add_u32 s16, s16, 0x100
	s_addc_u32 s17, s17, 0
	s_add_u32 s53, s53, 0x100
	s_addc_u32 s54, s54, 0
.LBB0_432:
	s_add_u32 s18, s16, 0xfff00080
	s_addc_u32 s19, s17, -1
	s_add_i32 s56, 0, 0x10000
	s_cmp_eq_u32 s55, 60
	s_cselect_b32 s21, s11, s19
	s_cselect_b32 s20, s51, s18
	s_cselect_b32 s19, s9, s54
	s_cselect_b32 s18, s52, s53
	s_add_i32 s58, 0, 0x14000
	v_add_u32_e32 v142, s56, v201
	v_add_u32_e32 v146, s58, v201
	ds_read_b128 v[130:133], v142
	ds_read_b128 v[134:137], v142 offset:1024
	ds_read_b128 v[138:141], v142 offset:2048
	ds_read_b128 v[142:145], v142 offset:3072
	ds_read_b128 v[164:167], v146
	ds_read_b128 v[168:171], v146 offset:1024
	ds_read_b128 v[172:175], v146 offset:2048
	ds_read_b128 v[176:179], v146 offset:3072
	v_lshl_add_u64 v[146:147], s[16:17], 0, v[160:161]
	s_add_i32 m0, s25, 0xc000
	ds_read_b128 v[204:207], v203
	ds_read_b128 v[208:211], v203 offset:1024
	ds_read_b128 v[212:215], v203 offset:2048
	ds_read_b128 v[216:219], v203 offset:3072
	ds_read_b128 v[220:223], v203 offset:4096
	ds_read_b128 v[224:227], v203 offset:5120
	ds_read_b128 v[228:231], v203 offset:6144
	ds_read_b128 v[232:235], v203 offset:7168
	global_load_lds_dwordx4 v[146:147], off
	v_lshl_add_u64 v[146:147], s[16:17], 0, v[162:163]
	s_add_i32 m0, s25, 0xe000
	s_nop 0
	global_load_lds_dwordx4 v[146:147], off
	s_waitcnt vmcnt(8)
	s_waitcnt lgkmcnt(0)
	s_barrier
	s_setprio 1
	s_waitcnt lgkmcnt(0)
	v_mfma_f32_16x16x32_bf16 v[126:129], v[130:133], v[204:207], v[126:129]
	v_mfma_f32_16x16x32_bf16 v[122:125], v[138:141], v[204:207], v[122:125]
	v_mfma_f32_16x16x32_bf16 v[118:121], v[130:133], v[212:215], v[118:121]
	v_mfma_f32_16x16x32_bf16 v[114:117], v[138:141], v[212:215], v[114:117]
	v_mfma_f32_16x16x32_bf16 v[110:113], v[130:133], v[220:223], v[110:113]
	v_mfma_f32_16x16x32_bf16 v[106:109], v[138:141], v[220:223], v[106:109]
	v_mfma_f32_16x16x32_bf16 v[102:105], v[130:133], v[228:231], v[102:105]
	v_mfma_f32_16x16x32_bf16 v[98:101], v[138:141], v[228:231], v[98:101]
	v_mfma_f32_16x16x32_bf16 v[126:129], v[134:137], v[208:211], v[126:129]
	v_mfma_f32_16x16x32_bf16 v[122:125], v[142:145], v[208:211], v[122:125]
	v_mfma_f32_16x16x32_bf16 v[118:121], v[134:137], v[216:219], v[118:121]
	v_mfma_f32_16x16x32_bf16 v[114:117], v[142:145], v[216:219], v[114:117]
	v_mfma_f32_16x16x32_bf16 v[110:113], v[134:137], v[224:227], v[110:113]
	v_mfma_f32_16x16x32_bf16 v[106:109], v[142:145], v[224:227], v[106:109]
	v_mfma_f32_16x16x32_bf16 v[102:105], v[134:137], v[232:235], v[102:105]
	v_mfma_f32_16x16x32_bf16 v[98:101], v[142:145], v[232:235], v[98:101]
	s_setprio 0
	s_setprio 1
	v_mfma_f32_16x16x32_bf16 v[62:65], v[164:167], v[204:207], v[62:65]
	v_mfma_f32_16x16x32_bf16 v[58:61], v[172:175], v[204:207], v[58:61]
	v_mfma_f32_16x16x32_bf16 v[54:57], v[164:167], v[212:215], v[54:57]
	v_mfma_f32_16x16x32_bf16 v[50:53], v[172:175], v[212:215], v[50:53]
	v_mfma_f32_16x16x32_bf16 v[46:49], v[164:167], v[220:223], v[46:49]
	v_mfma_f32_16x16x32_bf16 v[42:45], v[172:175], v[220:223], v[42:45]
	v_mfma_f32_16x16x32_bf16 v[38:41], v[164:167], v[228:231], v[38:41]
	v_mfma_f32_16x16x32_bf16 v[34:37], v[172:175], v[228:231], v[34:37]
	v_mfma_f32_16x16x32_bf16 v[62:65], v[168:171], v[208:211], v[62:65]
	v_mfma_f32_16x16x32_bf16 v[58:61], v[176:179], v[208:211], v[58:61]
	v_mfma_f32_16x16x32_bf16 v[54:57], v[168:171], v[216:219], v[54:57]
	v_mfma_f32_16x16x32_bf16 v[50:53], v[176:179], v[216:219], v[50:53]
	v_mfma_f32_16x16x32_bf16 v[46:49], v[168:171], v[224:227], v[46:49]
	v_mfma_f32_16x16x32_bf16 v[42:45], v[176:179], v[224:227], v[42:45]
	v_mfma_f32_16x16x32_bf16 v[38:41], v[168:171], v[232:235], v[38:41]
	v_mfma_f32_16x16x32_bf16 v[34:37], v[176:179], v[232:235], v[34:37]
	s_barrier
; #define PG8_STAGE(bufoff, gbase, voff) do { _Pragma("unroll") for (int _i = 0; _i < 2; ++_i) \
;         __builtin_amdgcn_global_load_lds((const unsigned*)((const char*)(gbase) + (voff)[_i]), (PG8_LAS unsigned*)(lds + (bufoff) + ldsw + _i * 8192), 16, 0, 0); } while (0)
; #define PG8_LDA(dst, b, h) do { _Pragma("unroll") for (int m = 0; m < 4; ++m) _Pragma("unroll") for (int k = 0; k < 2; ++k) dst[m][k] = *(const PG8_LAS bf16x8*)(lds + PG8_SA(b, h) + aoff + m * 2048 + k * 1024); } while (0)
; #define PG8_LDB(dst, b, h) do { _Pragma("unroll") for (int n = 0; n < 2; ++n) _Pragma("unroll") for (int k = 0; k < 2; ++k) dst[n][k] = *(const PG8_LAS bf16x8*)(lds + PG8_SB(b, h) + boff + n * 2048 + k * 1024); } while (0)
; #define PG8_MMA(ai, bj, At, Bt) do { __builtin_amdgcn_s_setprio(1); _Pragma("unroll") for (int m = 0; m < 4; ++m) _Pragma("unroll") for (int n = 0; n < 2; ++n) _Pragma("unroll") for (int k = 0; k < 2; ++k) \
;         acc[ai][bj][m][n] = __builtin_amdgcn_mfma_f32_16x16x32_bf16(Bt[n][k], At[m][k], acc[ai][bj][m][n], 0, 0, 0); __builtin_amdgcn_s_setprio(0); } while (0)
; #define PG8_WAIT_V(n) asm volatile("s_waitcnt vmcnt(" #n ")" ::: "memory")
; #define PG8_WAIT_L(n) asm volatile("s_waitcnt lgkmcnt(" #n ")" ::: "memory")
; #define PG8_BAR __builtin_amdgcn_s_barrier()
; #define PG8_SCHED __builtin_amdgcn_sched_barrier(0)
; template <class Epi, class Sched, bool ALIGN_EPI = false, bool SP2 = false>
; __device__ __forceinline__ void gemm_phase(PG8_LAS unsigned char* lds, const Gemm g, const Sched& S, const Epi& E) {
;     ...
;             PG8_LDA(At, 0, 1); PG8_STAGE(PG8_SB(0, 0), b2, voffB); PG8_STAGE(PG8_SB(0, 1), b2 + hstep, voffB); PG8_STAGE(PG8_SA(0, 0), a2, voffA);
;             PG8_WAIT_V(8); PG8_WAIT_L(0); PG8_BAR; PG8_MMA(1, 0, At, B0); PG8_MMA(1, 1, At, B1); PG8_BAR; PG8_SCHED;
;             PG8_LDB(B0, 1, 0); PG8_LDB(B1, 1, 1); PG8_SCHED; PG8_LDA(At, 1, 0); PG8_STAGE(PG8_SA(0, 1), a2 + hstep, voffA);
;             PG8_WAIT_V(8); PG8_WAIT_L(0); PG8_BAR; PG8_MMA(0, 0, At, B0); PG8_MMA(0, 1, At, B1); PG8_BAR; PG8_SCHED;
	s_setprio 0
	s_add_i32 s56, s56, s24
	v_lshl_add_u64 v[146:147], s[18:19], 0, v[0:1]
	s_mov_b32 m0, s56
	ds_read_b128 v[204:207], v203 offset:16384
	ds_read_b128 v[208:211], v203 offset:17408
	ds_read_b128 v[212:215], v203 offset:18432
	ds_read_b128 v[216:219], v203 offset:19456
	ds_read_b128 v[220:223], v203 offset:20480
	ds_read_b128 v[224:227], v203 offset:21504
	ds_read_b128 v[228:231], v203 offset:22528
	ds_read_b128 v[232:235], v203 offset:23552
	global_load_lds_dwordx4 v[146:147], off
	s_add_i32 m0, s56, 0x2000
	s_add_u32 s56, s18, 0x100000
	v_lshl_add_u64 v[148:149], s[18:19], 0, v[154:155]
	s_addc_u32 s57, s19, 0
	s_add_i32 s58, s58, s24
	global_load_lds_dwordx4 v[148:149], off
	v_lshl_add_u64 v[180:181], s[56:57], 0, v[0:1]
	s_mov_b32 m0, s58
	v_lshl_add_u64 v[236:237], s[20:21], 0, v[156:157]
	global_load_lds_dwordx4 v[180:181], off
	v_lshl_add_u64 v[180:181], s[56:57], 0, v[154:155]
	s_add_i32 m0, s58, 0x2000
	s_nop 0
	global_load_lds_dwordx4 v[180:181], off
	v_lshl_add_u64 v[180:181], s[20:21], 0, v[158:159]
	s_mov_b32 m0, s25
	s_nop 0
	global_load_lds_dwordx4 v[180:181], off
	s_mov_b32 m0, s26
	s_nop 0
	global_load_lds_dwordx4 v[236:237], off
	s_waitcnt vmcnt(8)
	s_waitcnt lgkmcnt(0)
	s_barrier
	s_setprio 1
	s_waitcnt lgkmcnt(0)
	v_mfma_f32_16x16x32_bf16 v[94:97], v[130:133], v[204:207], v[94:97]
	v_mfma_f32_16x16x32_bf16 v[90:93], v[138:141], v[204:207], v[90:93]
	v_mfma_f32_16x16x32_bf16 v[86:89], v[130:133], v[212:215], v[86:89]
	v_mfma_f32_16x16x32_bf16 v[82:85], v[138:141], v[212:215], v[82:85]
	v_mfma_f32_16x16x32_bf16 v[78:81], v[130:133], v[220:223], v[78:81]
	v_mfma_f32_16x16x32_bf16 v[74:77], v[138:141], v[220:223], v[74:77]
	v_mfma_f32_16x16x32_bf16 v[70:73], v[130:133], v[228:231], v[70:73]
	v_mfma_f32_16x16x32_bf16 v[66:69], v[138:141], v[228:231], v[66:69]
	v_mfma_f32_16x16x32_bf16 v[94:97], v[134:137], v[208:211], v[94:97]
	v_mfma_f32_16x16x32_bf16 v[90:93], v[142:145], v[208:211], v[90:93]
	v_mfma_f32_16x16x32_bf16 v[86:89], v[134:137], v[216:219], v[86:89]
	v_mfma_f32_16x16x32_bf16 v[82:85], v[142:145], v[216:219], v[82:85]
	v_mfma_f32_16x16x32_bf16 v[78:81], v[134:137], v[224:227], v[78:81]
	v_mfma_f32_16x16x32_bf16 v[74:77], v[142:145], v[224:227], v[74:77]
	v_mfma_f32_16x16x32_bf16 v[70:73], v[134:137], v[232:235], v[70:73]
	v_mfma_f32_16x16x32_bf16 v[66:69], v[142:145], v[232:235], v[66:69]
	s_setprio 0
	s_setprio 1
	v_mfma_f32_16x16x32_bf16 v[30:33], v[164:167], v[204:207], v[30:33]
	v_mfma_f32_16x16x32_bf16 v[26:29], v[172:175], v[204:207], v[26:29]
	v_mfma_f32_16x16x32_bf16 v[22:25], v[164:167], v[212:215], v[22:25]
	v_mfma_f32_16x16x32_bf16 v[18:21], v[172:175], v[212:215], v[18:21]
	v_mfma_f32_16x16x32_bf16 v[14:17], v[164:167], v[220:223], v[14:17]
	v_mfma_f32_16x16x32_bf16 v[10:13], v[172:175], v[220:223], v[10:13]
	v_mfma_f32_16x16x32_bf16 v[6:9], v[164:167], v[228:231], v[6:9]
	v_mfma_f32_16x16x32_bf16 v[2:5], v[172:175], v[228:231], v[2:5]
	v_mfma_f32_16x16x32_bf16 v[30:33], v[168:171], v[208:211], v[30:33]
	v_mfma_f32_16x16x32_bf16 v[26:29], v[176:179], v[208:211], v[26:29]
	v_mfma_f32_16x16x32_bf16 v[22:25], v[168:171], v[216:219], v[22:25]
	v_mfma_f32_16x16x32_bf16 v[18:21], v[176:179], v[216:219], v[18:21]
	v_mfma_f32_16x16x32_bf16 v[14:17], v[168:171], v[224:227], v[14:17]
	v_mfma_f32_16x16x32_bf16 v[10:13], v[176:179], v[224:227], v[10:13]
	v_mfma_f32_16x16x32_bf16 v[6:9], v[168:171], v[232:235], v[6:9]
	v_mfma_f32_16x16x32_bf16 v[2:5], v[176:179], v[232:235], v[2:5]
	s_barrier
	s_setprio 0
	s_add_i32 s56, 0, 0x18000
	s_add_i32 s57, 0, 0x1c000
	v_add_u32_e32 v142, s56, v201
	v_add_u32_e32 v176, s57, v201
	ds_read_b128 v[130:133], v142
	ds_read_b128 v[134:137], v142 offset:1024
	ds_read_b128 v[138:141], v142 offset:2048
	ds_read_b128 v[142:145], v142 offset:3072
	ds_read_b128 v[164:167], v176
	ds_read_b128 v[168:171], v176 offset:1024
	ds_read_b128 v[172:175], v176 offset:2048
	ds_read_b128 v[176:179], v176 offset:3072
	s_add_u32 s20, s20, 0x100000
	s_addc_u32 s21, s21, 0
	s_mov_b32 m0, s27
	v_lshl_add_u64 v[238:239], s[20:21], 0, v[158:159]
	ds_read_b128 v[204:207], v203 offset:32768
	ds_read_b128 v[208:211], v203 offset:33792
	ds_read_b128 v[212:215], v203 offset:34816
	ds_read_b128 v[216:219], v203 offset:35840
	ds_read_b128 v[220:223], v203 offset:36864
	ds_read_b128 v[224:227], v203 offset:37888
	ds_read_b128 v[228:231], v203 offset:38912
	ds_read_b128 v[232:235], v203 offset:39936
	global_load_lds_dwordx4 v[238:239], off
	v_lshl_add_u64 v[238:239], s[20:21], 0, v[156:157]
	s_mov_b32 m0, s28
	s_nop 0
	global_load_lds_dwordx4 v[238:239], off
	s_waitcnt vmcnt(8)
	s_waitcnt lgkmcnt(0)
	s_barrier
; #define PG8_STAGE(bufoff, gbase, voff) do { _Pragma("unroll") for (int _i = 0; _i < 2; ++_i) \
;         __builtin_amdgcn_global_load_lds((const unsigned*)((const char*)(gbase) + (voff)[_i]), (PG8_LAS unsigned*)(lds + (bufoff) + ldsw + _i * 8192), 16, 0, 0); } while (0)
; #define PG8_LDA(dst, b, h) do { _Pragma("unroll") for (int m = 0; m < 4; ++m) _Pragma("unroll") for (int k = 0; k < 2; ++k) dst[m][k] = *(const PG8_LAS bf16x8*)(lds + PG8_SA(b, h) + aoff + m * 2048 + k * 1024); } while (0)
; #define PG8_MMA(ai, bj, At, Bt) do { __builtin_amdgcn_s_setprio(1); _Pragma("unroll") for (int m = 0; m < 4; ++m) _Pragma("unroll") for (int n = 0; n < 2; ++n) _Pragma("unroll") for (int k = 0; k < 2; ++k) \
;         acc[ai][bj][m][n] = __builtin_amdgcn_mfma_f32_16x16x32_bf16(Bt[n][k], At[m][k], acc[ai][bj][m][n], 0, 0, 0); __builtin_amdgcn_s_setprio(0); } while (0)
; #define PG8_WAIT_V(n) asm volatile("s_waitcnt vmcnt(" #n ")" ::: "memory")
; #define PG8_WAIT_L(n) asm volatile("s_waitcnt lgkmcnt(" #n ")" ::: "memory")
; #define PG8_BAR __builtin_amdgcn_s_barrier()
; #define PG8_SCHED __builtin_amdgcn_sched_barrier(0)
; template <class Epi, class Sched, bool ALIGN_EPI = false, bool SP2 = false>
; __device__ __forceinline__ void gemm_phase(PG8_LAS unsigned char* lds, const Gemm g, const Sched& S, const Epi& E) {
;     ...
;             PG8_WAIT_V(8); PG8_WAIT_L(0); PG8_BAR; PG8_MMA(0, 0, At, B0); PG8_MMA(0, 1, At, B1); PG8_BAR; PG8_SCHED;
;             PG8_LDA(At, 1, 1); PG8_STAGE(PG8_SB(1, 0), b3, voffB); PG8_STAGE(PG8_SB(1, 1), b3 + hstep, voffB); PG8_STAGE(PG8_SA(1, 0), a3, voffA);
;             PG8_WAIT_V(8); PG8_WAIT_L(0); PG8_BAR; PG8_MMA(1, 0, At, B0); PG8_MMA(1, 1, At, B1); PG8_BAR; PG8_SCHED;
;     ...
;         if constexpr (ALIGN_EPI) { if (wr == 0) PG8_BAR; }
	s_setprio 1
	s_waitcnt lgkmcnt(0)
	v_mfma_f32_16x16x32_bf16 v[126:129], v[130:133], v[204:207], v[126:129]
	v_mfma_f32_16x16x32_bf16 v[122:125], v[138:141], v[204:207], v[122:125]
	v_mfma_f32_16x16x32_bf16 v[118:121], v[130:133], v[212:215], v[118:121]
	v_mfma_f32_16x16x32_bf16 v[114:117], v[138:141], v[212:215], v[114:117]
	v_mfma_f32_16x16x32_bf16 v[110:113], v[130:133], v[220:223], v[110:113]
	v_mfma_f32_16x16x32_bf16 v[106:109], v[138:141], v[220:223], v[106:109]
	v_mfma_f32_16x16x32_bf16 v[102:105], v[130:133], v[228:231], v[102:105]
	v_mfma_f32_16x16x32_bf16 v[98:101], v[138:141], v[228:231], v[98:101]
	v_mfma_f32_16x16x32_bf16 v[126:129], v[134:137], v[208:211], v[126:129]
	v_mfma_f32_16x16x32_bf16 v[122:125], v[142:145], v[208:211], v[122:125]
	v_mfma_f32_16x16x32_bf16 v[118:121], v[134:137], v[216:219], v[118:121]
	v_mfma_f32_16x16x32_bf16 v[114:117], v[142:145], v[216:219], v[114:117]
	v_mfma_f32_16x16x32_bf16 v[110:113], v[134:137], v[224:227], v[110:113]
	v_mfma_f32_16x16x32_bf16 v[106:109], v[142:145], v[224:227], v[106:109]
	v_mfma_f32_16x16x32_bf16 v[102:105], v[134:137], v[232:235], v[102:105]
	v_mfma_f32_16x16x32_bf16 v[98:101], v[142:145], v[232:235], v[98:101]
	s_setprio 0
	s_setprio 1
	v_mfma_f32_16x16x32_bf16 v[62:65], v[164:167], v[204:207], v[62:65]
	v_mfma_f32_16x16x32_bf16 v[58:61], v[172:175], v[204:207], v[58:61]
	v_mfma_f32_16x16x32_bf16 v[54:57], v[164:167], v[212:215], v[54:57]
	v_mfma_f32_16x16x32_bf16 v[50:53], v[172:175], v[212:215], v[50:53]
	v_mfma_f32_16x16x32_bf16 v[46:49], v[164:167], v[220:223], v[46:49]
	v_mfma_f32_16x16x32_bf16 v[42:45], v[172:175], v[220:223], v[42:45]
	v_mfma_f32_16x16x32_bf16 v[38:41], v[164:167], v[228:231], v[38:41]
	v_mfma_f32_16x16x32_bf16 v[34:37], v[172:175], v[228:231], v[34:37]
	v_mfma_f32_16x16x32_bf16 v[62:65], v[168:171], v[208:211], v[62:65]
	v_mfma_f32_16x16x32_bf16 v[58:61], v[176:179], v[208:211], v[58:61]
	v_mfma_f32_16x16x32_bf16 v[54:57], v[168:171], v[216:219], v[54:57]
	v_mfma_f32_16x16x32_bf16 v[50:53], v[176:179], v[216:219], v[50:53]
	v_mfma_f32_16x16x32_bf16 v[46:49], v[168:171], v[224:227], v[46:49]
	v_mfma_f32_16x16x32_bf16 v[42:45], v[176:179], v[224:227], v[42:45]
	v_mfma_f32_16x16x32_bf16 v[38:41], v[168:171], v[232:235], v[38:41]
	v_mfma_f32_16x16x32_bf16 v[34:37], v[176:179], v[232:235], v[34:37]
	s_barrier
	s_setprio 0
	s_add_i32 s20, s56, s24
	v_lshl_add_u64 v[146:147], v[146:147], 0, s[38:39]
	s_mov_b32 m0, s20
	ds_read_b128 v[204:207], v203 offset:49152
	ds_read_b128 v[208:211], v203 offset:50176
	ds_read_b128 v[212:215], v203 offset:51200
	ds_read_b128 v[216:219], v203 offset:52224
	ds_read_b128 v[220:223], v203 offset:53248
	ds_read_b128 v[224:227], v203 offset:54272
	ds_read_b128 v[228:231], v203 offset:55296
	ds_read_b128 v[232:235], v203 offset:56320
	global_load_lds_dwordx4 v[146:147], off
	s_add_i32 m0, s20, 0x2000
	s_add_u32 s18, s18, 0x100080
	v_lshl_add_u64 v[146:147], v[148:149], 0, s[38:39]
	s_addc_u32 s19, s19, 0
	s_add_i32 s20, s57, s24
	global_load_lds_dwordx4 v[146:147], off
	v_lshl_add_u64 v[146:147], s[18:19], 0, v[0:1]
	s_mov_b32 m0, s20
	s_nop 0
	global_load_lds_dwordx4 v[146:147], off
	v_lshl_add_u64 v[146:147], s[18:19], 0, v[154:155]
	s_add_i32 m0, s20, 0x2000
	s_nop 0
	global_load_lds_dwordx4 v[146:147], off
	v_lshl_add_u64 v[146:147], v[180:181], 0, s[38:39]
	s_mov_b32 m0, s31
	s_nop 0
	global_load_lds_dwordx4 v[146:147], off
	v_lshl_add_u64 v[146:147], v[236:237], 0, s[38:39]
	s_mov_b32 m0, s33
	s_nop 0
	global_load_lds_dwordx4 v[146:147], off
	s_waitcnt vmcnt(8)
	s_waitcnt lgkmcnt(0)
	s_barrier
	s_setprio 1
	s_waitcnt lgkmcnt(0)
	v_mfma_f32_16x16x32_bf16 v[94:97], v[130:133], v[204:207], v[94:97]
	v_mfma_f32_16x16x32_bf16 v[90:93], v[138:141], v[204:207], v[90:93]
	v_mfma_f32_16x16x32_bf16 v[86:89], v[130:133], v[212:215], v[86:89]
	v_mfma_f32_16x16x32_bf16 v[82:85], v[138:141], v[212:215], v[82:85]
	v_mfma_f32_16x16x32_bf16 v[78:81], v[130:133], v[220:223], v[78:81]
	v_mfma_f32_16x16x32_bf16 v[74:77], v[138:141], v[220:223], v[74:77]
	v_mfma_f32_16x16x32_bf16 v[70:73], v[130:133], v[228:231], v[70:73]
	v_mfma_f32_16x16x32_bf16 v[66:69], v[138:141], v[228:231], v[66:69]
	v_mfma_f32_16x16x32_bf16 v[94:97], v[134:137], v[208:211], v[94:97]
	v_mfma_f32_16x16x32_bf16 v[90:93], v[142:145], v[208:211], v[90:93]
	v_mfma_f32_16x16x32_bf16 v[86:89], v[134:137], v[216:219], v[86:89]
	v_mfma_f32_16x16x32_bf16 v[82:85], v[142:145], v[216:219], v[82:85]
	v_mfma_f32_16x16x32_bf16 v[78:81], v[134:137], v[224:227], v[78:81]
	v_mfma_f32_16x16x32_bf16 v[74:77], v[142:145], v[224:227], v[74:77]
	v_mfma_f32_16x16x32_bf16 v[70:73], v[134:137], v[232:235], v[70:73]
	v_mfma_f32_16x16x32_bf16 v[66:69], v[142:145], v[232:235], v[66:69]
	s_setprio 0
	s_setprio 1
	v_mfma_f32_16x16x32_bf16 v[30:33], v[164:167], v[204:207], v[30:33]
	v_mfma_f32_16x16x32_bf16 v[26:29], v[172:175], v[204:207], v[26:29]
	v_mfma_f32_16x16x32_bf16 v[22:25], v[164:167], v[212:215], v[22:25]
	v_mfma_f32_16x16x32_bf16 v[18:21], v[172:175], v[212:215], v[18:21]
	v_mfma_f32_16x16x32_bf16 v[14:17], v[164:167], v[220:223], v[14:17]
	v_mfma_f32_16x16x32_bf16 v[10:13], v[172:175], v[220:223], v[10:13]
	v_mfma_f32_16x16x32_bf16 v[6:9], v[164:167], v[228:231], v[6:9]
	v_mfma_f32_16x16x32_bf16 v[2:5], v[172:175], v[228:231], v[2:5]
	v_mfma_f32_16x16x32_bf16 v[30:33], v[168:171], v[208:211], v[30:33]
	v_mfma_f32_16x16x32_bf16 v[26:29], v[176:179], v[208:211], v[26:29]
	v_mfma_f32_16x16x32_bf16 v[22:25], v[168:171], v[216:219], v[22:25]
	v_mfma_f32_16x16x32_bf16 v[18:21], v[176:179], v[216:219], v[18:21]
	v_mfma_f32_16x16x32_bf16 v[14:17], v[168:171], v[224:227], v[14:17]
	v_mfma_f32_16x16x32_bf16 v[10:13], v[176:179], v[224:227], v[10:13]
	v_mfma_f32_16x16x32_bf16 v[6:9], v[168:171], v[232:235], v[6:9]
	v_mfma_f32_16x16x32_bf16 v[2:5], v[176:179], v[232:235], v[2:5]
	s_barrier
	s_setprio 0
	s_add_i32 s55, s55, 2
	s_add_u32 s16, s16, 0x100
	s_addc_u32 s17, s17, 0
	s_add_u32 s53, s53, 0x100
	s_addc_u32 s54, s54, 0
	s_cmp_gt_u32 s55, 61
	s_cbranch_scc0 .LBB0_432
	s_and_b64 vcc, exec, s[6:7]
	s_cbranch_vccz .LBB0_435
	s_barrier

; #define PG8_STAGE(bufoff, gbase, voff) do { _Pragma("unroll") for (int _i = 0; _i < 2; ++_i) \
;         __builtin_amdgcn_global_load_lds((const unsigned*)((const char*)(gbase) + (voff)[_i]), (PG8_LAS unsigned*)(lds + (bufoff) + ldsw + _i * 8192), 16, 0, 0); } while (0)
; #define PG8_LDA(dst, b, h) do { _Pragma("unroll") for (int m = 0; m < 4; ++m) _Pragma("unroll") for (int k = 0; k < 2; ++k) dst[m][k] = *(const PG8_LAS bf16x8*)(lds + PG8_SA(b, h) + aoff + m * 2048 + k * 1024); } while (0)
; #define PG8_LDB(dst, b, h) do { _Pragma("unroll") for (int n = 0; n < 2; ++n) _Pragma("unroll") for (int k = 0; k < 2; ++k) dst[n][k] = *(const PG8_LAS bf16x8*)(lds + PG8_SB(b, h) + boff + n * 2048 + k * 1024); } while (0)
; #define PG8_WAIT_V(n) asm volatile("s_waitcnt vmcnt(" #n ")" ::: "memory")
; #define PG8_WAIT_L(n) asm volatile("s_waitcnt lgkmcnt(" #n ")" ::: "memory")
; #define PG8_BAR __builtin_amdgcn_s_barrier()
; #define PG8_SCHED __builtin_amdgcn_sched_barrier(0)
; template <class Epi, class Sched, bool ALIGN_EPI = false, bool SP2 = false>
; __device__ __forceinline__ void gemm_phase(PG8_LAS unsigned char* lds, const Gemm g, const Sched& S, const Epi& E) {
;     ...
;         const char* nA = has_next ? (const char*)g.A + (size_t)nxt.pm * tstep : cA; const char* nB = has_next ? (const char*)g.Bt + (size_t)nxt.pn * tstep : cB;
;         for (int t = 0; t < nt; t += 2) {
;             const bool last = (t == nt - 2);
;             const char* a1 = cA + (size_t)(t + 1) * kstep;
;             const char* a2 = last ? nA : cA + (size_t)(t + 2) * kstep; const char* b2 = last ? nB : cB + (size_t)(t + 2) * kstep;
;             const char* a3 = a2 + kstep; const char* b3 = b2 + kstep;
;             if (last && has_next) S.a_ready(nxt);
;             if constexpr (SP2) {
;             PG8_LDB(B0, 0, 0); PG8_LDB(B1, 0, 1); PG8_SCHED; PG8_LDA(At, 0, 0); PG8_STAGE(PG8_SA(1, 1), a1 + hstep, voffA);
;             PG8_WAIT_V(8); PG8_WAIT_L(0); PG8_BAR; PG8_MMA(0, 0, At, B0); PG8_MMA(0, 1, At, B1); PG8_BAR; PG8_SCHED;
;             PG8_LDA(At, 0, 1); PG8_STAGE(PG8_SB(0, 0), b2, voffB); PG8_STAGE(PG8_SB(0, 1), b2 + hstep, voffB); PG8_STAGE(PG8_SA(0, 0), a2, voffA);
;             PG8_WAIT_V(8); PG8_WAIT_L(0); PG8_BAR; PG8_MMA(1, 0, At, B0); PG8_MMA(1, 1, At, B1); PG8_BAR; PG8_SCHED;
.LBB0_557:
	s_ashr_i32 s15, s14, 31
	s_lshl_b64 s[16:17], s[14:15], 19
	s_add_u32 s16, s90, s16
	s_addc_u32 s17, s91, s17
	s_and_b64 s[18:19], s[6:7], exec
	s_cselect_b32 s15, s17, s23
	s_cselect_b32 s21, s16, s22
	s_ashr_i32 s13, s12, 31
	s_lshl_b64 s[18:19], s[12:13], 19
	s_add_u32 s18, s28, s18
	s_addc_u32 s19, s29, s19
	s_and_b64 s[26:27], s[6:7], exec
	s_cselect_b32 s13, s19, s25
	s_cselect_b32 s60, s18, s24
	s_add_u32 s22, s22, 0x40080
	s_addc_u32 s23, s23, 0
	s_add_u32 s61, s24, 0x100
	s_addc_u32 s62, s25, 0
	s_mov_b32 s63, -2
	s_add_u32 s24, s22, 0xfffc0080
	s_addc_u32 s25, s23, -1
	s_add_i32 s64, 0, 0x10000
	s_cmp_eq_u32 s63, 12
	s_cselect_b32 s27, s15, s25
	s_cselect_b32 s26, s21, s24
	s_cselect_b32 s25, s13, s62
	s_cselect_b32 s24, s60, s61
	s_add_i32 s66, 0, 0x14000
	v_lshl_add_u64 v[146:147], s[22:23], 0, v[164:165]
	s_add_i32 m0, s50, 0xc000
	global_load_lds_dwordx4 v[146:147], off
	v_lshl_add_u64 v[146:147], s[22:23], 0, v[166:167]
	s_add_i32 m0, s50, 0xe000
	s_nop 0
	global_load_lds_dwordx4 v[146:147], off
	s_waitcnt vmcnt(24)
	s_waitcnt lgkmcnt(0)
	s_barrier
	s_setprio 1
	s_waitcnt lgkmcnt(0)
	v_mfma_f32_16x16x32_bf16 v[126:129], v[130:133], v[212:215], 0
	v_mfma_f32_16x16x32_bf16 v[122:125], v[138:141], v[212:215], 0
	v_mfma_f32_16x16x32_bf16 v[114:117], v[130:133], v[220:223], 0
	v_mfma_f32_16x16x32_bf16 v[106:109], v[138:141], v[220:223], 0
	v_mfma_f32_16x16x32_bf16 v[94:97], v[130:133], v[228:231], 0
	v_mfma_f32_16x16x32_bf16 v[90:93], v[138:141], v[228:231], 0
	v_mfma_f32_16x16x32_bf16 v[82:85], v[130:133], v[236:239], 0
	v_mfma_f32_16x16x32_bf16 v[74:77], v[138:141], v[236:239], 0
	v_mfma_f32_16x16x32_bf16 v[126:129], v[134:137], v[216:219], v[126:129]
	v_mfma_f32_16x16x32_bf16 v[122:125], v[142:145], v[216:219], v[122:125]
	v_mfma_f32_16x16x32_bf16 v[114:117], v[134:137], v[224:227], v[114:117]
	v_mfma_f32_16x16x32_bf16 v[106:109], v[142:145], v[224:227], v[106:109]
	v_mfma_f32_16x16x32_bf16 v[94:97], v[134:137], v[232:235], v[94:97]
	v_mfma_f32_16x16x32_bf16 v[90:93], v[142:145], v[232:235], v[90:93]
	v_mfma_f32_16x16x32_bf16 v[82:85], v[134:137], v[240:243], v[82:85]
	v_mfma_f32_16x16x32_bf16 v[74:77], v[142:145], v[240:243], v[74:77]
	s_setprio 0
	s_setprio 1
	v_mfma_f32_16x16x32_bf16 v[118:121], v[168:171], v[212:215], 0
	v_mfma_f32_16x16x32_bf16 v[110:113], v[204:207], v[212:215], 0
	v_mfma_f32_16x16x32_bf16 v[102:105], v[168:171], v[220:223], 0
	v_mfma_f32_16x16x32_bf16 v[98:101], v[204:207], v[220:223], 0
	v_mfma_f32_16x16x32_bf16 v[86:89], v[168:171], v[228:231], 0
	v_mfma_f32_16x16x32_bf16 v[78:81], v[204:207], v[228:231], 0
	v_mfma_f32_16x16x32_bf16 v[70:73], v[168:171], v[236:239], 0
	v_mfma_f32_16x16x32_bf16 v[66:69], v[204:207], v[236:239], 0
	v_mfma_f32_16x16x32_bf16 v[118:121], v[200:203], v[216:219], v[118:121]
	v_mfma_f32_16x16x32_bf16 v[110:113], v[208:211], v[216:219], v[110:113]
	v_mfma_f32_16x16x32_bf16 v[102:105], v[200:203], v[224:227], v[102:105]
	v_mfma_f32_16x16x32_bf16 v[98:101], v[208:211], v[224:227], v[98:101]
	v_mfma_f32_16x16x32_bf16 v[86:89], v[200:203], v[232:235], v[86:89]
	v_mfma_f32_16x16x32_bf16 v[78:81], v[208:211], v[232:235], v[78:81]
	v_mfma_f32_16x16x32_bf16 v[70:73], v[200:203], v[240:243], v[70:73]
	v_mfma_f32_16x16x32_bf16 v[66:69], v[208:211], v[240:243], v[66:69]
	s_barrier
	s_setprio 0
	s_add_i32 s64, s64, s30
	v_lshl_add_u64 v[146:147], s[24:25], 0, v[158:159]
	s_mov_b32 m0, s64
	ds_read_b128 v[212:215], v177 offset:16384
	ds_read_b128 v[216:219], v177 offset:17408
	ds_read_b128 v[220:223], v177 offset:18432
	ds_read_b128 v[224:227], v177 offset:19456
	ds_read_b128 v[228:231], v177 offset:20480
	ds_read_b128 v[232:235], v177 offset:21504
	ds_read_b128 v[236:239], v177 offset:22528
	ds_read_b128 v[240:243], v177 offset:23552
	global_load_lds_dwordx4 v[146:147], off
	s_add_i32 m0, s64, 0x2000
	s_add_u32 s64, s24, 0x40000
	v_lshl_add_u64 v[148:149], s[24:25], 0, v[154:155]
	s_addc_u32 s65, s25, 0
	s_add_i32 s66, s66, s30
	global_load_lds_dwordx4 v[148:149], off
	v_lshl_add_u64 v[172:173], s[64:65], 0, v[158:159]
	s_mov_b32 m0, s66
	v_lshl_add_u64 v[180:181], s[26:27], 0, v[156:157]
	global_load_lds_dwordx4 v[172:173], off
	v_lshl_add_u64 v[172:173], s[64:65], 0, v[154:155]
	s_add_i32 m0, s66, 0x2000
	s_nop 0
	global_load_lds_dwordx4 v[172:173], off
	v_lshl_add_u64 v[172:173], s[26:27], 0, v[160:161]
	s_mov_b32 m0, s50
	s_nop 0
	global_load_lds_dwordx4 v[172:173], off
	s_mov_b32 m0, s51
	s_nop 0
	global_load_lds_dwordx4 v[180:181], off
	s_waitcnt vmcnt(24)
	s_waitcnt lgkmcnt(0)
	s_barrier
	s_setprio 1
	s_waitcnt lgkmcnt(0)
	v_mfma_f32_16x16x32_bf16 v[62:65], v[130:133], v[212:215], 0
	v_mfma_f32_16x16x32_bf16 v[58:61], v[138:141], v[212:215], 0
	v_mfma_f32_16x16x32_bf16 v[50:53], v[130:133], v[220:223], 0
	v_mfma_f32_16x16x32_bf16 v[42:45], v[138:141], v[220:223], 0
	v_mfma_f32_16x16x32_bf16 v[30:33], v[130:133], v[228:231], 0
	v_mfma_f32_16x16x32_bf16 v[26:29], v[138:141], v[228:231], 0
	v_mfma_f32_16x16x32_bf16 v[18:21], v[130:133], v[236:239], 0
	v_mfma_f32_16x16x32_bf16 v[10:13], v[138:141], v[236:239], 0
	v_mfma_f32_16x16x32_bf16 v[62:65], v[134:137], v[216:219], v[62:65]
	v_mfma_f32_16x16x32_bf16 v[58:61], v[142:145], v[216:219], v[58:61]
	v_mfma_f32_16x16x32_bf16 v[50:53], v[134:137], v[224:227], v[50:53]
	v_mfma_f32_16x16x32_bf16 v[42:45], v[142:145], v[224:227], v[42:45]
	v_mfma_f32_16x16x32_bf16 v[30:33], v[134:137], v[232:235], v[30:33]
	v_mfma_f32_16x16x32_bf16 v[26:29], v[142:145], v[232:235], v[26:29]
	v_mfma_f32_16x16x32_bf16 v[18:21], v[134:137], v[240:243], v[18:21]
	v_mfma_f32_16x16x32_bf16 v[10:13], v[142:145], v[240:243], v[10:13]
	s_setprio 0
	s_setprio 1
	v_mfma_f32_16x16x32_bf16 v[54:57], v[168:171], v[212:215], 0
	v_mfma_f32_16x16x32_bf16 v[46:49], v[204:207], v[212:215], 0
	v_mfma_f32_16x16x32_bf16 v[38:41], v[168:171], v[220:223], 0
	v_mfma_f32_16x16x32_bf16 v[34:37], v[204:207], v[220:223], 0
	v_mfma_f32_16x16x32_bf16 v[22:25], v[168:171], v[228:231], 0
	v_mfma_f32_16x16x32_bf16 v[14:17], v[204:207], v[228:231], 0
	v_mfma_f32_16x16x32_bf16 v[6:9], v[168:171], v[236:239], 0
	v_mfma_f32_16x16x32_bf16 v[2:5], v[204:207], v[236:239], 0
	v_mfma_f32_16x16x32_bf16 v[54:57], v[200:203], v[216:219], v[54:57]
	v_mfma_f32_16x16x32_bf16 v[46:49], v[208:211], v[216:219], v[46:49]
	v_mfma_f32_16x16x32_bf16 v[38:41], v[200:203], v[224:227], v[38:41]
	v_mfma_f32_16x16x32_bf16 v[34:37], v[208:211], v[224:227], v[34:37]
	v_mfma_f32_16x16x32_bf16 v[22:25], v[200:203], v[232:235], v[22:25]
	v_mfma_f32_16x16x32_bf16 v[14:17], v[208:211], v[232:235], v[14:17]
	v_mfma_f32_16x16x32_bf16 v[6:9], v[200:203], v[240:243], v[6:9]
	v_mfma_f32_16x16x32_bf16 v[2:5], v[208:211], v[240:243], v[2:5]
	s_barrier
; #define PG8_STAGE(bufoff, gbase, voff) do { _Pragma("unroll") for (int _i = 0; _i < 2; ++_i) \
;         __builtin_amdgcn_global_load_lds((const unsigned*)((const char*)(gbase) + (voff)[_i]), (PG8_LAS unsigned*)(lds + (bufoff) + ldsw + _i * 8192), 16, 0, 0); } while (0)
; #define PG8_LDA(dst, b, h) do { _Pragma("unroll") for (int m = 0; m < 4; ++m) _Pragma("unroll") for (int k = 0; k < 2; ++k) dst[m][k] = *(const PG8_LAS bf16x8*)(lds + PG8_SA(b, h) + aoff + m * 2048 + k * 1024); } while (0)
; #define PG8_LDB(dst, b, h) do { _Pragma("unroll") for (int n = 0; n < 2; ++n) _Pragma("unroll") for (int k = 0; k < 2; ++k) dst[n][k] = *(const PG8_LAS bf16x8*)(lds + PG8_SB(b, h) + boff + n * 2048 + k * 1024); } while (0)
; #define PG8_MMA(ai, bj, At, Bt) do { __builtin_amdgcn_s_setprio(1); _Pragma("unroll") for (int m = 0; m < 4; ++m) _Pragma("unroll") for (int n = 0; n < 2; ++n) _Pragma("unroll") for (int k = 0; k < 2; ++k) \
;         acc[ai][bj][m][n] = __builtin_amdgcn_mfma_f32_16x16x32_bf16(Bt[n][k], At[m][k], acc[ai][bj][m][n], 0, 0, 0); __builtin_amdgcn_s_setprio(0); } while (0)
; #define PG8_WAIT_V(n) asm volatile("s_waitcnt vmcnt(" #n ")" ::: "memory")
; #define PG8_WAIT_L(n) asm volatile("s_waitcnt lgkmcnt(" #n ")" ::: "memory")
; #define PG8_BAR __builtin_amdgcn_s_barrier()
; #define PG8_SCHED __builtin_amdgcn_sched_barrier(0)
; template <class Epi, class Sched, bool ALIGN_EPI = false, bool SP2 = false>
; __device__ __forceinline__ void gemm_phase(PG8_LAS unsigned char* lds, const Gemm g, const Sched& S, const Epi& E) {
;     ...
;             PG8_LDB(B0, 1, 0); PG8_LDB(B1, 1, 1); PG8_SCHED; PG8_LDA(At, 1, 0); PG8_STAGE(PG8_SA(0, 1), a2 + hstep, voffA);
;             PG8_WAIT_V(8); PG8_WAIT_L(0); PG8_BAR; PG8_MMA(0, 0, At, B0); PG8_MMA(0, 1, At, B1); PG8_BAR; PG8_SCHED;
;             PG8_LDA(At, 1, 1); PG8_STAGE(PG8_SB(1, 0), b3, voffB); PG8_STAGE(PG8_SB(1, 1), b3 + hstep, voffB); PG8_STAGE(PG8_SA(1, 0), a3, voffA);
;             PG8_WAIT_V(8); PG8_WAIT_L(0); PG8_BAR; PG8_MMA(1, 0, At, B0); PG8_MMA(1, 1, At, B1); PG8_BAR; PG8_SCHED;
	s_setprio 0
	s_add_i32 s64, 0, 0x18000
	v_add_u32_e32 v0, s64, v175
	s_add_i32 s65, 0, 0x1c000
	ds_read_b128 v[130:133], v0
	ds_read_b128 v[134:137], v0 offset:1024
	ds_read_b128 v[138:141], v0 offset:2048
	ds_read_b128 v[142:145], v0 offset:3072
	v_add_u32_e32 v0, s65, v175
	ds_read_b128 v[168:171], v0
	ds_read_b128 v[200:203], v0 offset:1024
	ds_read_b128 v[204:207], v0 offset:2048
	ds_read_b128 v[208:211], v0 offset:3072
	s_add_u32 s26, s26, 0x40000
	s_addc_u32 s27, s27, 0
	s_mov_b32 m0, s52
	v_lshl_add_u64 v[244:245], s[26:27], 0, v[160:161]
	ds_read_b128 v[212:215], v177 offset:32768
	ds_read_b128 v[216:219], v177 offset:33792
	ds_read_b128 v[220:223], v177 offset:34816
	ds_read_b128 v[224:227], v177 offset:35840
	ds_read_b128 v[228:231], v177 offset:36864
	ds_read_b128 v[232:235], v177 offset:37888
	ds_read_b128 v[236:239], v177 offset:38912
	ds_read_b128 v[240:243], v177 offset:39936
	global_load_lds_dwordx4 v[244:245], off
	v_lshl_add_u64 v[244:245], s[26:27], 0, v[156:157]
	s_mov_b32 m0, s53
	s_nop 0
	global_load_lds_dwordx4 v[244:245], off
	s_waitcnt vmcnt(8)
	s_waitcnt lgkmcnt(0)
	s_barrier
	s_setprio 1
	s_waitcnt lgkmcnt(0)
	v_mfma_f32_16x16x32_bf16 v[126:129], v[130:133], v[212:215], v[126:129]
	v_mfma_f32_16x16x32_bf16 v[122:125], v[138:141], v[212:215], v[122:125]
	v_mfma_f32_16x16x32_bf16 v[114:117], v[130:133], v[220:223], v[114:117]
	v_mfma_f32_16x16x32_bf16 v[106:109], v[138:141], v[220:223], v[106:109]
	v_mfma_f32_16x16x32_bf16 v[94:97], v[130:133], v[228:231], v[94:97]
	v_mfma_f32_16x16x32_bf16 v[90:93], v[138:141], v[228:231], v[90:93]
	v_mfma_f32_16x16x32_bf16 v[82:85], v[130:133], v[236:239], v[82:85]
	v_mfma_f32_16x16x32_bf16 v[74:77], v[138:141], v[236:239], v[74:77]
	v_mfma_f32_16x16x32_bf16 v[126:129], v[134:137], v[216:219], v[126:129]
	v_mfma_f32_16x16x32_bf16 v[122:125], v[142:145], v[216:219], v[122:125]
	v_mfma_f32_16x16x32_bf16 v[114:117], v[134:137], v[224:227], v[114:117]
	v_mfma_f32_16x16x32_bf16 v[106:109], v[142:145], v[224:227], v[106:109]
	v_mfma_f32_16x16x32_bf16 v[94:97], v[134:137], v[232:235], v[94:97]
	v_mfma_f32_16x16x32_bf16 v[90:93], v[142:145], v[232:235], v[90:93]
	v_mfma_f32_16x16x32_bf16 v[82:85], v[134:137], v[240:243], v[82:85]
	v_mfma_f32_16x16x32_bf16 v[74:77], v[142:145], v[240:243], v[74:77]
	s_setprio 0
	s_setprio 1
	v_mfma_f32_16x16x32_bf16 v[118:121], v[168:171], v[212:215], v[118:121]
	v_mfma_f32_16x16x32_bf16 v[110:113], v[204:207], v[212:215], v[110:113]
	v_mfma_f32_16x16x32_bf16 v[102:105], v[168:171], v[220:223], v[102:105]
	v_mfma_f32_16x16x32_bf16 v[98:101], v[204:207], v[220:223], v[98:101]
	v_mfma_f32_16x16x32_bf16 v[86:89], v[168:171], v[228:231], v[86:89]
	v_mfma_f32_16x16x32_bf16 v[78:81], v[204:207], v[228:231], v[78:81]
	v_mfma_f32_16x16x32_bf16 v[70:73], v[168:171], v[236:239], v[70:73]
	v_mfma_f32_16x16x32_bf16 v[66:69], v[204:207], v[236:239], v[66:69]
	v_mfma_f32_16x16x32_bf16 v[118:121], v[200:203], v[216:219], v[118:121]
	v_mfma_f32_16x16x32_bf16 v[110:113], v[208:211], v[216:219], v[110:113]
	v_mfma_f32_16x16x32_bf16 v[102:105], v[200:203], v[224:227], v[102:105]
	v_mfma_f32_16x16x32_bf16 v[98:101], v[208:211], v[224:227], v[98:101]
	v_mfma_f32_16x16x32_bf16 v[86:89], v[200:203], v[232:235], v[86:89]
	v_mfma_f32_16x16x32_bf16 v[78:81], v[208:211], v[232:235], v[78:81]
	v_mfma_f32_16x16x32_bf16 v[70:73], v[200:203], v[240:243], v[70:73]
	v_mfma_f32_16x16x32_bf16 v[66:69], v[208:211], v[240:243], v[66:69]
	s_barrier
	s_setprio 0
	s_add_i32 s26, s64, s30
	v_lshl_add_u64 v[146:147], v[146:147], 0, s[38:39]
	s_mov_b32 m0, s26
	ds_read_b128 v[212:215], v177 offset:49152
	ds_read_b128 v[216:219], v177 offset:50176
	ds_read_b128 v[220:223], v177 offset:51200
	ds_read_b128 v[224:227], v177 offset:52224
	ds_read_b128 v[228:231], v177 offset:53248
	ds_read_b128 v[232:235], v177 offset:54272
	ds_read_b128 v[236:239], v177 offset:55296
	ds_read_b128 v[240:243], v177 offset:56320
	global_load_lds_dwordx4 v[146:147], off
	s_add_i32 m0, s26, 0x2000
	s_add_u32 s24, s24, 0x40080
	v_lshl_add_u64 v[146:147], v[148:149], 0, s[38:39]
	s_addc_u32 s25, s25, 0
	s_add_i32 s26, s65, s30
	global_load_lds_dwordx4 v[146:147], off
	v_lshl_add_u64 v[146:147], s[24:25], 0, v[158:159]
	s_mov_b32 m0, s26
	s_nop 0
	global_load_lds_dwordx4 v[146:147], off
	v_lshl_add_u64 v[146:147], s[24:25], 0, v[154:155]
	s_add_i32 m0, s26, 0x2000
	s_nop 0
	global_load_lds_dwordx4 v[146:147], off
	v_lshl_add_u64 v[146:147], v[172:173], 0, s[38:39]
	s_mov_b32 m0, s55
	s_nop 0
	global_load_lds_dwordx4 v[146:147], off
	v_lshl_add_u64 v[146:147], v[180:181], 0, s[38:39]
	s_mov_b32 m0, s56
	s_nop 0
	global_load_lds_dwordx4 v[146:147], off
	s_waitcnt vmcnt(8)
	s_waitcnt lgkmcnt(0)
	s_barrier
; #define PG8_STAGE(bufoff, gbase, voff) do { _Pragma("unroll") for (int _i = 0; _i < 2; ++_i) \
;         __builtin_amdgcn_global_load_lds((const unsigned*)((const char*)(gbase) + (voff)[_i]), (PG8_LAS unsigned*)(lds + (bufoff) + ldsw + _i * 8192), 16, 0, 0); } while (0)
; #define PG8_LDA(dst, b, h) do { _Pragma("unroll") for (int m = 0; m < 4; ++m) _Pragma("unroll") for (int k = 0; k < 2; ++k) dst[m][k] = *(const PG8_LAS bf16x8*)(lds + PG8_SA(b, h) + aoff + m * 2048 + k * 1024); } while (0)
; #define PG8_LDB(dst, b, h) do { _Pragma("unroll") for (int n = 0; n < 2; ++n) _Pragma("unroll") for (int k = 0; k < 2; ++k) dst[n][k] = *(const PG8_LAS bf16x8*)(lds + PG8_SB(b, h) + boff + n * 2048 + k * 1024); } while (0)
; #define PG8_BAR __builtin_amdgcn_s_barrier()
; template <class Epi, class Sched, bool ALIGN_EPI = false, bool SP2 = false>
; __device__ __forceinline__ void gemm_phase(PG8_LAS unsigned char* lds, const Gemm g, const Sched& S, const Epi& E) {
;     ...
;             const bool last = (t == nt - 2);
;             const char* a1 = cA + (size_t)(t + 1) * kstep;
;             const char* a2 = last ? nA : cA + (size_t)(t + 2) * kstep; const char* b2 = last ? nB : cB + (size_t)(t + 2) * kstep;
;             const char* a3 = a2 + kstep; const char* b3 = b2 + kstep;
;             if (last && has_next) S.a_ready(nxt);
;             if constexpr (SP2) {
;             PG8_LDB(B0, 0, 0); PG8_LDB(B1, 0, 1); PG8_SCHED; PG8_LDA(At, 0, 0); PG8_STAGE(PG8_SA(1, 1), a1 + hstep, voffA);
;             PG8_WAIT_V(8); PG8_WAIT_L(0); PG8_BAR; PG8_MMA(0, 0, At, B0); PG8_MMA(0, 1, At, B1); PG8_BAR; PG8_SCHED;
;             PG8_LDA(At, 0, 1); PG8_STAGE(PG8_SB(0, 0), b2, voffB); PG8_STAGE(PG8_SB(0, 1), b2 + hstep, voffB); PG8_STAGE(PG8_SA(0, 0), a2, voffA);
;             PG8_WAIT_V(8); PG8_WAIT_L(0); PG8_BAR; PG8_MMA(1, 0, At, B0); PG8_MMA(1, 1, At, B1); PG8_BAR; PG8_SCHED;
;             PG8_LDB(B0, 1, 0); PG8_LDB(B1, 1, 1); PG8_SCHED; PG8_LDA(At, 1, 0); PG8_STAGE(PG8_SA(0, 1), a2 + hstep, voffA);
;             PG8_WAIT_V(8); PG8_WAIT_L(0); PG8_BAR; PG8_MMA(0, 0, At, B0); PG8_MMA(0, 1, At, B1); PG8_BAR; PG8_SCHED;
;             PG8_LDA(At, 1, 1); PG8_STAGE(PG8_SB(1, 0), b3, voffB); PG8_STAGE(PG8_SB(1, 1), b3 + hstep, voffB); PG8_STAGE(PG8_SA(1, 0), a3, voffA);
;             PG8_WAIT_V(8); PG8_WAIT_L(0); PG8_BAR; PG8_MMA(1, 0, At, B0); PG8_MMA(1, 1, At, B1); PG8_BAR; PG8_SCHED;
	s_setprio 1
	s_waitcnt lgkmcnt(0)
	v_mfma_f32_16x16x32_bf16 v[62:65], v[130:133], v[212:215], v[62:65]
	v_mfma_f32_16x16x32_bf16 v[58:61], v[138:141], v[212:215], v[58:61]
	v_mfma_f32_16x16x32_bf16 v[50:53], v[130:133], v[220:223], v[50:53]
	v_mfma_f32_16x16x32_bf16 v[42:45], v[138:141], v[220:223], v[42:45]
	v_mfma_f32_16x16x32_bf16 v[30:33], v[130:133], v[228:231], v[30:33]
	v_mfma_f32_16x16x32_bf16 v[26:29], v[138:141], v[228:231], v[26:29]
	v_mfma_f32_16x16x32_bf16 v[18:21], v[130:133], v[236:239], v[18:21]
	v_mfma_f32_16x16x32_bf16 v[10:13], v[138:141], v[236:239], v[10:13]
	v_mfma_f32_16x16x32_bf16 v[62:65], v[134:137], v[216:219], v[62:65]
	v_mfma_f32_16x16x32_bf16 v[58:61], v[142:145], v[216:219], v[58:61]
	v_mfma_f32_16x16x32_bf16 v[50:53], v[134:137], v[224:227], v[50:53]
	v_mfma_f32_16x16x32_bf16 v[42:45], v[142:145], v[224:227], v[42:45]
	v_mfma_f32_16x16x32_bf16 v[30:33], v[134:137], v[232:235], v[30:33]
	v_mfma_f32_16x16x32_bf16 v[26:29], v[142:145], v[232:235], v[26:29]
	v_mfma_f32_16x16x32_bf16 v[18:21], v[134:137], v[240:243], v[18:21]
	v_mfma_f32_16x16x32_bf16 v[10:13], v[142:145], v[240:243], v[10:13]
	s_setprio 0
	s_setprio 1
	v_mfma_f32_16x16x32_bf16 v[54:57], v[168:171], v[212:215], v[54:57]
	v_mfma_f32_16x16x32_bf16 v[46:49], v[204:207], v[212:215], v[46:49]
	v_mfma_f32_16x16x32_bf16 v[38:41], v[168:171], v[220:223], v[38:41]
	v_mfma_f32_16x16x32_bf16 v[34:37], v[204:207], v[220:223], v[34:37]
	v_mfma_f32_16x16x32_bf16 v[22:25], v[168:171], v[228:231], v[22:25]
	v_mfma_f32_16x16x32_bf16 v[14:17], v[204:207], v[228:231], v[14:17]
	v_mfma_f32_16x16x32_bf16 v[6:9], v[168:171], v[236:239], v[6:9]
	v_mfma_f32_16x16x32_bf16 v[2:5], v[204:207], v[236:239], v[2:5]
	v_mfma_f32_16x16x32_bf16 v[54:57], v[200:203], v[216:219], v[54:57]
	v_mfma_f32_16x16x32_bf16 v[46:49], v[208:211], v[216:219], v[46:49]
	v_mfma_f32_16x16x32_bf16 v[38:41], v[200:203], v[224:227], v[38:41]
	v_mfma_f32_16x16x32_bf16 v[34:37], v[208:211], v[224:227], v[34:37]
	v_mfma_f32_16x16x32_bf16 v[22:25], v[200:203], v[232:235], v[22:25]
	v_mfma_f32_16x16x32_bf16 v[14:17], v[208:211], v[232:235], v[14:17]
	v_mfma_f32_16x16x32_bf16 v[6:9], v[200:203], v[240:243], v[6:9]
	v_mfma_f32_16x16x32_bf16 v[2:5], v[208:211], v[240:243], v[2:5]
	s_barrier
	s_setprio 0
	s_add_i32 s63, s63, 2
	s_add_u32 s22, s22, 0x100
	s_addc_u32 s23, s23, 0
	s_add_u32 s61, s61, 0x100
	s_addc_u32 s62, s62, 0
.LBB0_558:
	s_add_u32 s24, s22, 0xfffc0080
	s_addc_u32 s25, s23, -1
	s_add_i32 s64, 0, 0x10000
	s_cmp_eq_u32 s63, 12
	s_cselect_b32 s27, s15, s25
	s_cselect_b32 s26, s21, s24
	v_add_u32_e32 v0, s64, v175
	s_cselect_b32 s25, s13, s62
	s_cselect_b32 s24, s60, s61
	s_add_i32 s66, 0, 0x14000
	ds_read_b128 v[130:133], v0
	ds_read_b128 v[134:137], v0 offset:1024
	ds_read_b128 v[138:141], v0 offset:2048
	ds_read_b128 v[142:145], v0 offset:3072
	v_add_u32_e32 v0, s66, v175
	ds_read_b128 v[168:171], v0
	ds_read_b128 v[200:203], v0 offset:1024
	ds_read_b128 v[204:207], v0 offset:2048
	ds_read_b128 v[208:211], v0 offset:3072
	v_lshl_add_u64 v[146:147], s[22:23], 0, v[164:165]
	s_add_i32 m0, s50, 0xc000
	ds_read_b128 v[212:215], v177
	ds_read_b128 v[216:219], v177 offset:1024
	ds_read_b128 v[220:223], v177 offset:2048
	ds_read_b128 v[224:227], v177 offset:3072
	ds_read_b128 v[228:231], v177 offset:4096
	ds_read_b128 v[232:235], v177 offset:5120
	ds_read_b128 v[236:239], v177 offset:6144
	ds_read_b128 v[240:243], v177 offset:7168
	global_load_lds_dwordx4 v[146:147], off
	v_lshl_add_u64 v[146:147], s[22:23], 0, v[166:167]
	s_add_i32 m0, s50, 0xe000
	s_nop 0
	global_load_lds_dwordx4 v[146:147], off
	s_waitcnt vmcnt(8)
	s_waitcnt lgkmcnt(0)
	s_barrier
	s_setprio 1
	s_waitcnt lgkmcnt(0)
	v_mfma_f32_16x16x32_bf16 v[126:129], v[130:133], v[212:215], v[126:129]
	v_mfma_f32_16x16x32_bf16 v[122:125], v[138:141], v[212:215], v[122:125]
	v_mfma_f32_16x16x32_bf16 v[114:117], v[130:133], v[220:223], v[114:117]
	v_mfma_f32_16x16x32_bf16 v[106:109], v[138:141], v[220:223], v[106:109]
	v_mfma_f32_16x16x32_bf16 v[94:97], v[130:133], v[228:231], v[94:97]
	v_mfma_f32_16x16x32_bf16 v[90:93], v[138:141], v[228:231], v[90:93]
	v_mfma_f32_16x16x32_bf16 v[82:85], v[130:133], v[236:239], v[82:85]
	v_mfma_f32_16x16x32_bf16 v[74:77], v[138:141], v[236:239], v[74:77]
	v_mfma_f32_16x16x32_bf16 v[126:129], v[134:137], v[216:219], v[126:129]
	v_mfma_f32_16x16x32_bf16 v[122:125], v[142:145], v[216:219], v[122:125]
	v_mfma_f32_16x16x32_bf16 v[114:117], v[134:137], v[224:227], v[114:117]
	v_mfma_f32_16x16x32_bf16 v[106:109], v[142:145], v[224:227], v[106:109]
	v_mfma_f32_16x16x32_bf16 v[94:97], v[134:137], v[232:235], v[94:97]
	v_mfma_f32_16x16x32_bf16 v[90:93], v[142:145], v[232:235], v[90:93]
	v_mfma_f32_16x16x32_bf16 v[82:85], v[134:137], v[240:243], v[82:85]
	v_mfma_f32_16x16x32_bf16 v[74:77], v[142:145], v[240:243], v[74:77]
	s_setprio 0
	s_setprio 1
	v_mfma_f32_16x16x32_bf16 v[118:121], v[168:171], v[212:215], v[118:121]
	v_mfma_f32_16x16x32_bf16 v[110:113], v[204:207], v[212:215], v[110:113]
	v_mfma_f32_16x16x32_bf16 v[102:105], v[168:171], v[220:223], v[102:105]
	v_mfma_f32_16x16x32_bf16 v[98:101], v[204:207], v[220:223], v[98:101]
	v_mfma_f32_16x16x32_bf16 v[86:89], v[168:171], v[228:231], v[86:89]
	v_mfma_f32_16x16x32_bf16 v[78:81], v[204:207], v[228:231], v[78:81]
	v_mfma_f32_16x16x32_bf16 v[70:73], v[168:171], v[236:239], v[70:73]
	v_mfma_f32_16x16x32_bf16 v[66:69], v[204:207], v[236:239], v[66:69]
	v_mfma_f32_16x16x32_bf16 v[118:121], v[200:203], v[216:219], v[118:121]
	v_mfma_f32_16x16x32_bf16 v[110:113], v[208:211], v[216:219], v[110:113]
	v_mfma_f32_16x16x32_bf16 v[102:105], v[200:203], v[224:227], v[102:105]
	v_mfma_f32_16x16x32_bf16 v[98:101], v[208:211], v[224:227], v[98:101]
	v_mfma_f32_16x16x32_bf16 v[86:89], v[200:203], v[232:235], v[86:89]
	v_mfma_f32_16x16x32_bf16 v[78:81], v[208:211], v[232:235], v[78:81]
	v_mfma_f32_16x16x32_bf16 v[70:73], v[200:203], v[240:243], v[70:73]
	v_mfma_f32_16x16x32_bf16 v[66:69], v[208:211], v[240:243], v[66:69]
	s_barrier
; #define PG8_STAGE(bufoff, gbase, voff) do { _Pragma("unroll") for (int _i = 0; _i < 2; ++_i) \
;         __builtin_amdgcn_global_load_lds((const unsigned*)((const char*)(gbase) + (voff)[_i]), (PG8_LAS unsigned*)(lds + (bufoff) + ldsw + _i * 8192), 16, 0, 0); } while (0)
; #define PG8_LDA(dst, b, h) do { _Pragma("unroll") for (int m = 0; m < 4; ++m) _Pragma("unroll") for (int k = 0; k < 2; ++k) dst[m][k] = *(const PG8_LAS bf16x8*)(lds + PG8_SA(b, h) + aoff + m * 2048 + k * 1024); } while (0)
; #define PG8_LDB(dst, b, h) do { _Pragma("unroll") for (int n = 0; n < 2; ++n) _Pragma("unroll") for (int k = 0; k < 2; ++k) dst[n][k] = *(const PG8_LAS bf16x8*)(lds + PG8_SB(b, h) + boff + n * 2048 + k * 1024); } while (0)
; #define PG8_MMA(ai, bj, At, Bt) do { __builtin_amdgcn_s_setprio(1); _Pragma("unroll") for (int m = 0; m < 4; ++m) _Pragma("unroll") for (int n = 0; n < 2; ++n) _Pragma("unroll") for (int k = 0; k < 2; ++k) \
;         acc[ai][bj][m][n] = __builtin_amdgcn_mfma_f32_16x16x32_bf16(Bt[n][k], At[m][k], acc[ai][bj][m][n], 0, 0, 0); __builtin_amdgcn_s_setprio(0); } while (0)
; #define PG8_WAIT_V(n) asm volatile("s_waitcnt vmcnt(" #n ")" ::: "memory")
; #define PG8_WAIT_L(n) asm volatile("s_waitcnt lgkmcnt(" #n ")" ::: "memory")
; #define PG8_BAR __builtin_amdgcn_s_barrier()
; #define PG8_SCHED __builtin_amdgcn_sched_barrier(0)
; template <class Epi, class Sched, bool ALIGN_EPI = false, bool SP2 = false>
; __device__ __forceinline__ void gemm_phase(PG8_LAS unsigned char* lds, const Gemm g, const Sched& S, const Epi& E) {
;     ...
;             PG8_LDA(At, 0, 1); PG8_STAGE(PG8_SB(0, 0), b2, voffB); PG8_STAGE(PG8_SB(0, 1), b2 + hstep, voffB); PG8_STAGE(PG8_SA(0, 0), a2, voffA);
;             PG8_WAIT_V(8); PG8_WAIT_L(0); PG8_BAR; PG8_MMA(1, 0, At, B0); PG8_MMA(1, 1, At, B1); PG8_BAR; PG8_SCHED;
;             PG8_LDB(B0, 1, 0); PG8_LDB(B1, 1, 1); PG8_SCHED; PG8_LDA(At, 1, 0); PG8_STAGE(PG8_SA(0, 1), a2 + hstep, voffA);
;             PG8_WAIT_V(8); PG8_WAIT_L(0); PG8_BAR; PG8_MMA(0, 0, At, B0); PG8_MMA(0, 1, At, B1); PG8_BAR; PG8_SCHED;
	s_setprio 0
	s_add_i32 s64, s64, s30
	v_lshl_add_u64 v[146:147], s[24:25], 0, v[158:159]
	s_mov_b32 m0, s64
	ds_read_b128 v[212:215], v177 offset:16384
	ds_read_b128 v[216:219], v177 offset:17408
	ds_read_b128 v[220:223], v177 offset:18432
	ds_read_b128 v[224:227], v177 offset:19456
	ds_read_b128 v[228:231], v177 offset:20480
	ds_read_b128 v[232:235], v177 offset:21504
	ds_read_b128 v[236:239], v177 offset:22528
	ds_read_b128 v[240:243], v177 offset:23552
	global_load_lds_dwordx4 v[146:147], off
	s_add_i32 m0, s64, 0x2000
	s_add_u32 s64, s24, 0x40000
	v_lshl_add_u64 v[148:149], s[24:25], 0, v[154:155]
	s_addc_u32 s65, s25, 0
	s_add_i32 s66, s66, s30
	global_load_lds_dwordx4 v[148:149], off
	v_lshl_add_u64 v[172:173], s[64:65], 0, v[158:159]
	s_mov_b32 m0, s66
	v_lshl_add_u64 v[180:181], s[26:27], 0, v[156:157]
	global_load_lds_dwordx4 v[172:173], off
	v_lshl_add_u64 v[172:173], s[64:65], 0, v[154:155]
	s_add_i32 m0, s66, 0x2000
	s_nop 0
	global_load_lds_dwordx4 v[172:173], off
	v_lshl_add_u64 v[172:173], s[26:27], 0, v[160:161]
	s_mov_b32 m0, s50
	s_nop 0
	global_load_lds_dwordx4 v[172:173], off
	s_mov_b32 m0, s51
	s_nop 0
	global_load_lds_dwordx4 v[180:181], off
	s_waitcnt vmcnt(8)
	s_waitcnt lgkmcnt(0)
	s_barrier
	s_setprio 1
	s_waitcnt lgkmcnt(0)
	v_mfma_f32_16x16x32_bf16 v[62:65], v[130:133], v[212:215], v[62:65]
	v_mfma_f32_16x16x32_bf16 v[58:61], v[138:141], v[212:215], v[58:61]
	v_mfma_f32_16x16x32_bf16 v[50:53], v[130:133], v[220:223], v[50:53]
	v_mfma_f32_16x16x32_bf16 v[42:45], v[138:141], v[220:223], v[42:45]
	v_mfma_f32_16x16x32_bf16 v[30:33], v[130:133], v[228:231], v[30:33]
	v_mfma_f32_16x16x32_bf16 v[26:29], v[138:141], v[228:231], v[26:29]
	v_mfma_f32_16x16x32_bf16 v[18:21], v[130:133], v[236:239], v[18:21]
	v_mfma_f32_16x16x32_bf16 v[10:13], v[138:141], v[236:239], v[10:13]
	v_mfma_f32_16x16x32_bf16 v[62:65], v[134:137], v[216:219], v[62:65]
	v_mfma_f32_16x16x32_bf16 v[58:61], v[142:145], v[216:219], v[58:61]
	v_mfma_f32_16x16x32_bf16 v[50:53], v[134:137], v[224:227], v[50:53]
	v_mfma_f32_16x16x32_bf16 v[42:45], v[142:145], v[224:227], v[42:45]
	v_mfma_f32_16x16x32_bf16 v[30:33], v[134:137], v[232:235], v[30:33]
	v_mfma_f32_16x16x32_bf16 v[26:29], v[142:145], v[232:235], v[26:29]
	v_mfma_f32_16x16x32_bf16 v[18:21], v[134:137], v[240:243], v[18:21]
	v_mfma_f32_16x16x32_bf16 v[10:13], v[142:145], v[240:243], v[10:13]
	s_setprio 0
	s_setprio 1
	v_mfma_f32_16x16x32_bf16 v[54:57], v[168:171], v[212:215], v[54:57]
	v_mfma_f32_16x16x32_bf16 v[46:49], v[204:207], v[212:215], v[46:49]
	v_mfma_f32_16x16x32_bf16 v[38:41], v[168:171], v[220:223], v[38:41]
	v_mfma_f32_16x16x32_bf16 v[34:37], v[204:207], v[220:223], v[34:37]
	v_mfma_f32_16x16x32_bf16 v[22:25], v[168:171], v[228:231], v[22:25]
	v_mfma_f32_16x16x32_bf16 v[14:17], v[204:207], v[228:231], v[14:17]
	v_mfma_f32_16x16x32_bf16 v[6:9], v[168:171], v[236:239], v[6:9]
	v_mfma_f32_16x16x32_bf16 v[2:5], v[204:207], v[236:239], v[2:5]
	v_mfma_f32_16x16x32_bf16 v[54:57], v[200:203], v[216:219], v[54:57]
	v_mfma_f32_16x16x32_bf16 v[46:49], v[208:211], v[216:219], v[46:49]
	v_mfma_f32_16x16x32_bf16 v[38:41], v[200:203], v[224:227], v[38:41]
	v_mfma_f32_16x16x32_bf16 v[34:37], v[208:211], v[224:227], v[34:37]
	v_mfma_f32_16x16x32_bf16 v[22:25], v[200:203], v[232:235], v[22:25]
	v_mfma_f32_16x16x32_bf16 v[14:17], v[208:211], v[232:235], v[14:17]
	v_mfma_f32_16x16x32_bf16 v[6:9], v[200:203], v[240:243], v[6:9]
	v_mfma_f32_16x16x32_bf16 v[2:5], v[208:211], v[240:243], v[2:5]
	s_barrier
	s_setprio 0
	s_add_i32 s64, 0, 0x18000
	v_add_u32_e32 v0, s64, v175
	s_add_i32 s65, 0, 0x1c000
	ds_read_b128 v[130:133], v0
	ds_read_b128 v[134:137], v0 offset:1024
	ds_read_b128 v[138:141], v0 offset:2048
	ds_read_b128 v[142:145], v0 offset:3072
	v_add_u32_e32 v0, s65, v175
	ds_read_b128 v[168:171], v0
	ds_read_b128 v[200:203], v0 offset:1024
	ds_read_b128 v[204:207], v0 offset:2048
	ds_read_b128 v[208:211], v0 offset:3072
	s_add_u32 s26, s26, 0x40000
	s_addc_u32 s27, s27, 0
	s_mov_b32 m0, s52
	v_lshl_add_u64 v[244:245], s[26:27], 0, v[160:161]
	ds_read_b128 v[212:215], v177 offset:32768
	ds_read_b128 v[216:219], v177 offset:33792
	ds_read_b128 v[220:223], v177 offset:34816
	ds_read_b128 v[224:227], v177 offset:35840
	ds_read_b128 v[228:231], v177 offset:36864
	ds_read_b128 v[232:235], v177 offset:37888
	ds_read_b128 v[236:239], v177 offset:38912
	ds_read_b128 v[240:243], v177 offset:39936
	global_load_lds_dwordx4 v[244:245], off
	v_lshl_add_u64 v[244:245], s[26:27], 0, v[156:157]
	s_mov_b32 m0, s53
	s_nop 0
	global_load_lds_dwordx4 v[244:245], off
	s_waitcnt vmcnt(8)
	s_waitcnt lgkmcnt(0)
	s_barrier
; #define PG8_STAGE(bufoff, gbase, voff) do { _Pragma("unroll") for (int _i = 0; _i < 2; ++_i) \
;         __builtin_amdgcn_global_load_lds((const unsigned*)((const char*)(gbase) + (voff)[_i]), (PG8_LAS unsigned*)(lds + (bufoff) + ldsw + _i * 8192), 16, 0, 0); } while (0)
; #define PG8_LDA(dst, b, h) do { _Pragma("unroll") for (int m = 0; m < 4; ++m) _Pragma("unroll") for (int k = 0; k < 2; ++k) dst[m][k] = *(const PG8_LAS bf16x8*)(lds + PG8_SA(b, h) + aoff + m * 2048 + k * 1024); } while (0)
; #define PG8_MMA(ai, bj, At, Bt) do { __builtin_amdgcn_s_setprio(1); _Pragma("unroll") for (int m = 0; m < 4; ++m) _Pragma("unroll") for (int n = 0; n < 2; ++n) _Pragma("unroll") for (int k = 0; k < 2; ++k) \
;         acc[ai][bj][m][n] = __builtin_amdgcn_mfma_f32_16x16x32_bf16(Bt[n][k], At[m][k], acc[ai][bj][m][n], 0, 0, 0); __builtin_amdgcn_s_setprio(0); } while (0)
; #define PG8_WAIT_V(n) asm volatile("s_waitcnt vmcnt(" #n ")" ::: "memory")
; #define PG8_WAIT_L(n) asm volatile("s_waitcnt lgkmcnt(" #n ")" ::: "memory")
; #define PG8_BAR __builtin_amdgcn_s_barrier()
; #define PG8_SCHED __builtin_amdgcn_sched_barrier(0)
; template <class Epi, class Sched, bool ALIGN_EPI = false, bool SP2 = false>
; __device__ __forceinline__ void gemm_phase(PG8_LAS unsigned char* lds, const Gemm g, const Sched& S, const Epi& E) {
;     ...
;             PG8_WAIT_V(8); PG8_WAIT_L(0); PG8_BAR; PG8_MMA(0, 0, At, B0); PG8_MMA(0, 1, At, B1); PG8_BAR; PG8_SCHED;
;             PG8_LDA(At, 1, 1); PG8_STAGE(PG8_SB(1, 0), b3, voffB); PG8_STAGE(PG8_SB(1, 1), b3 + hstep, voffB); PG8_STAGE(PG8_SA(1, 0), a3, voffA);
;             PG8_WAIT_V(8); PG8_WAIT_L(0); PG8_BAR; PG8_MMA(1, 0, At, B0); PG8_MMA(1, 1, At, B1); PG8_BAR; PG8_SCHED;
;     ...
;         if constexpr (ALIGN_EPI) { if (wr == 0) PG8_BAR; }
	s_setprio 1
	s_waitcnt lgkmcnt(0)
	v_mfma_f32_16x16x32_bf16 v[126:129], v[130:133], v[212:215], v[126:129]
	v_mfma_f32_16x16x32_bf16 v[122:125], v[138:141], v[212:215], v[122:125]
	v_mfma_f32_16x16x32_bf16 v[114:117], v[130:133], v[220:223], v[114:117]
	v_mfma_f32_16x16x32_bf16 v[106:109], v[138:141], v[220:223], v[106:109]
	v_mfma_f32_16x16x32_bf16 v[94:97], v[130:133], v[228:231], v[94:97]
	v_mfma_f32_16x16x32_bf16 v[90:93], v[138:141], v[228:231], v[90:93]
	v_mfma_f32_16x16x32_bf16 v[82:85], v[130:133], v[236:239], v[82:85]
	v_mfma_f32_16x16x32_bf16 v[74:77], v[138:141], v[236:239], v[74:77]
	v_mfma_f32_16x16x32_bf16 v[126:129], v[134:137], v[216:219], v[126:129]
	v_mfma_f32_16x16x32_bf16 v[122:125], v[142:145], v[216:219], v[122:125]
	v_mfma_f32_16x16x32_bf16 v[114:117], v[134:137], v[224:227], v[114:117]
	v_mfma_f32_16x16x32_bf16 v[106:109], v[142:145], v[224:227], v[106:109]
	v_mfma_f32_16x16x32_bf16 v[94:97], v[134:137], v[232:235], v[94:97]
	v_mfma_f32_16x16x32_bf16 v[90:93], v[142:145], v[232:235], v[90:93]
	v_mfma_f32_16x16x32_bf16 v[82:85], v[134:137], v[240:243], v[82:85]
	v_mfma_f32_16x16x32_bf16 v[74:77], v[142:145], v[240:243], v[74:77]
	s_setprio 0
	s_setprio 1
	v_mfma_f32_16x16x32_bf16 v[118:121], v[168:171], v[212:215], v[118:121]
	v_mfma_f32_16x16x32_bf16 v[110:113], v[204:207], v[212:215], v[110:113]
	v_mfma_f32_16x16x32_bf16 v[102:105], v[168:171], v[220:223], v[102:105]
	v_mfma_f32_16x16x32_bf16 v[98:101], v[204:207], v[220:223], v[98:101]
	v_mfma_f32_16x16x32_bf16 v[86:89], v[168:171], v[228:231], v[86:89]
	v_mfma_f32_16x16x32_bf16 v[78:81], v[204:207], v[228:231], v[78:81]
	v_mfma_f32_16x16x32_bf16 v[70:73], v[168:171], v[236:239], v[70:73]
	v_mfma_f32_16x16x32_bf16 v[66:69], v[204:207], v[236:239], v[66:69]
	v_mfma_f32_16x16x32_bf16 v[118:121], v[200:203], v[216:219], v[118:121]
	v_mfma_f32_16x16x32_bf16 v[110:113], v[208:211], v[216:219], v[110:113]
	v_mfma_f32_16x16x32_bf16 v[102:105], v[200:203], v[224:227], v[102:105]
	v_mfma_f32_16x16x32_bf16 v[98:101], v[208:211], v[224:227], v[98:101]
	v_mfma_f32_16x16x32_bf16 v[86:89], v[200:203], v[232:235], v[86:89]
	v_mfma_f32_16x16x32_bf16 v[78:81], v[208:211], v[232:235], v[78:81]
	v_mfma_f32_16x16x32_bf16 v[70:73], v[200:203], v[240:243], v[70:73]
	v_mfma_f32_16x16x32_bf16 v[66:69], v[208:211], v[240:243], v[66:69]
	s_barrier
	s_setprio 0
	s_add_i32 s26, s64, s30
	v_lshl_add_u64 v[146:147], v[146:147], 0, s[38:39]
	s_mov_b32 m0, s26
	ds_read_b128 v[212:215], v177 offset:49152
	ds_read_b128 v[216:219], v177 offset:50176
	ds_read_b128 v[220:223], v177 offset:51200
	ds_read_b128 v[224:227], v177 offset:52224
	ds_read_b128 v[228:231], v177 offset:53248
	ds_read_b128 v[232:235], v177 offset:54272
	ds_read_b128 v[236:239], v177 offset:55296
	ds_read_b128 v[240:243], v177 offset:56320
	global_load_lds_dwordx4 v[146:147], off
	s_add_i32 m0, s26, 0x2000
	s_add_u32 s24, s24, 0x40080
	v_lshl_add_u64 v[146:147], v[148:149], 0, s[38:39]
	s_addc_u32 s25, s25, 0
	s_add_i32 s26, s65, s30
	global_load_lds_dwordx4 v[146:147], off
	v_lshl_add_u64 v[146:147], s[24:25], 0, v[158:159]
	s_mov_b32 m0, s26
	s_nop 0
	global_load_lds_dwordx4 v[146:147], off
	v_lshl_add_u64 v[146:147], s[24:25], 0, v[154:155]
	s_add_i32 m0, s26, 0x2000
	s_nop 0
	global_load_lds_dwordx4 v[146:147], off
	v_lshl_add_u64 v[146:147], v[172:173], 0, s[38:39]
	s_mov_b32 m0, s55
	s_nop 0
	global_load_lds_dwordx4 v[146:147], off
	v_lshl_add_u64 v[146:147], v[180:181], 0, s[38:39]
	s_mov_b32 m0, s56
	s_nop 0
	global_load_lds_dwordx4 v[146:147], off
	s_waitcnt vmcnt(8)
	s_waitcnt lgkmcnt(0)
	s_barrier
	s_setprio 1
	s_waitcnt lgkmcnt(0)
	v_mfma_f32_16x16x32_bf16 v[62:65], v[130:133], v[212:215], v[62:65]
	v_mfma_f32_16x16x32_bf16 v[58:61], v[138:141], v[212:215], v[58:61]
	v_mfma_f32_16x16x32_bf16 v[50:53], v[130:133], v[220:223], v[50:53]
	v_mfma_f32_16x16x32_bf16 v[42:45], v[138:141], v[220:223], v[42:45]
	v_mfma_f32_16x16x32_bf16 v[30:33], v[130:133], v[228:231], v[30:33]
	v_mfma_f32_16x16x32_bf16 v[26:29], v[138:141], v[228:231], v[26:29]
	v_mfma_f32_16x16x32_bf16 v[18:21], v[130:133], v[236:239], v[18:21]
	v_mfma_f32_16x16x32_bf16 v[10:13], v[138:141], v[236:239], v[10:13]
	v_mfma_f32_16x16x32_bf16 v[62:65], v[134:137], v[216:219], v[62:65]
	v_mfma_f32_16x16x32_bf16 v[58:61], v[142:145], v[216:219], v[58:61]
	v_mfma_f32_16x16x32_bf16 v[50:53], v[134:137], v[224:227], v[50:53]
	v_mfma_f32_16x16x32_bf16 v[42:45], v[142:145], v[224:227], v[42:45]
	v_mfma_f32_16x16x32_bf16 v[30:33], v[134:137], v[232:235], v[30:33]
	v_mfma_f32_16x16x32_bf16 v[26:29], v[142:145], v[232:235], v[26:29]
	v_mfma_f32_16x16x32_bf16 v[18:21], v[134:137], v[240:243], v[18:21]
	v_mfma_f32_16x16x32_bf16 v[10:13], v[142:145], v[240:243], v[10:13]
	s_setprio 0
	s_setprio 1
	v_mfma_f32_16x16x32_bf16 v[54:57], v[168:171], v[212:215], v[54:57]
	v_mfma_f32_16x16x32_bf16 v[46:49], v[204:207], v[212:215], v[46:49]
	v_mfma_f32_16x16x32_bf16 v[38:41], v[168:171], v[220:223], v[38:41]
	v_mfma_f32_16x16x32_bf16 v[34:37], v[204:207], v[220:223], v[34:37]
	v_mfma_f32_16x16x32_bf16 v[22:25], v[168:171], v[228:231], v[22:25]
	v_mfma_f32_16x16x32_bf16 v[14:17], v[204:207], v[228:231], v[14:17]
	v_mfma_f32_16x16x32_bf16 v[6:9], v[168:171], v[236:239], v[6:9]
	v_mfma_f32_16x16x32_bf16 v[2:5], v[204:207], v[236:239], v[2:5]
	v_mfma_f32_16x16x32_bf16 v[54:57], v[200:203], v[216:219], v[54:57]
	v_mfma_f32_16x16x32_bf16 v[46:49], v[208:211], v[216:219], v[46:49]
	v_mfma_f32_16x16x32_bf16 v[38:41], v[200:203], v[224:227], v[38:41]
	v_mfma_f32_16x16x32_bf16 v[34:37], v[208:211], v[224:227], v[34:37]
	v_mfma_f32_16x16x32_bf16 v[22:25], v[200:203], v[232:235], v[22:25]
	v_mfma_f32_16x16x32_bf16 v[14:17], v[208:211], v[232:235], v[14:17]
	v_mfma_f32_16x16x32_bf16 v[6:9], v[200:203], v[240:243], v[6:9]
	v_mfma_f32_16x16x32_bf16 v[2:5], v[208:211], v[240:243], v[2:5]
	s_barrier
	s_setprio 0
	s_add_i32 s63, s63, 2
	s_add_u32 s22, s22, 0x100
	s_addc_u32 s23, s23, 0
	s_add_u32 s61, s61, 0x100
	s_addc_u32 s62, s62, 0
	s_cmp_gt_u32 s63, 13
	s_cbranch_scc0 .LBB0_558
	s_and_b64 vcc, exec, s[8:9]
	s_cbranch_vccnz .LBB0_563
	v_lshl_add_u32 v168, s20, 8, v174
	s_cmp_ge_i32 s59, s54
	s_mov_b64 s[20:21], -1
	s_cbranch_scc1 .LBB0_564

; #define PG8_STAGE(bufoff, gbase, voff) do { _Pragma("unroll") for (int _i = 0; _i < 2; ++_i) \
;         __builtin_amdgcn_global_load_lds((const unsigned*)((const char*)(gbase) + (voff)[_i]), (PG8_LAS unsigned*)(lds + (bufoff) + ldsw + _i * 8192), 16, 0, 0); } while (0)
; #define PG8_LDA(dst, b, h) do { _Pragma("unroll") for (int m = 0; m < 4; ++m) _Pragma("unroll") for (int k = 0; k < 2; ++k) dst[m][k] = *(const PG8_LAS bf16x8*)(lds + PG8_SA(b, h) + aoff + m * 2048 + k * 1024); } while (0)
; #define PG8_LDB(dst, b, h) do { _Pragma("unroll") for (int n = 0; n < 2; ++n) _Pragma("unroll") for (int k = 0; k < 2; ++k) dst[n][k] = *(const PG8_LAS bf16x8*)(lds + PG8_SB(b, h) + boff + n * 2048 + k * 1024); } while (0)
; #define PG8_WAIT_V(n) asm volatile("s_waitcnt vmcnt(" #n ")" ::: "memory")
; #define PG8_WAIT_L(n) asm volatile("s_waitcnt lgkmcnt(" #n ")" ::: "memory")
; #define PG8_BAR __builtin_amdgcn_s_barrier()
; #define PG8_SCHED __builtin_amdgcn_sched_barrier(0)
; template <class Epi, class Sched, bool ALIGN_EPI = false, bool SP2 = false>
; __device__ __forceinline__ void gemm_phase(PG8_LAS unsigned char* lds, const Gemm g, const Sched& S, const Epi& E) {
;     ...
;         const char* nA = has_next ? (const char*)g.A + (size_t)nxt.pm * tstep : cA; const char* nB = has_next ? (const char*)g.Bt + (size_t)nxt.pn * tstep : cB;
;         for (int t = 0; t < nt; t += 2) {
;             const bool last = (t == nt - 2);
;             const char* a1 = cA + (size_t)(t + 1) * kstep;
;             const char* a2 = last ? nA : cA + (size_t)(t + 2) * kstep; const char* b2 = last ? nB : cB + (size_t)(t + 2) * kstep;
;             const char* a3 = a2 + kstep; const char* b3 = b2 + kstep;
;             if (last && has_next) S.a_ready(nxt);
;             if constexpr (SP2) {
;             PG8_LDB(B0, 0, 0); PG8_LDB(B1, 0, 1); PG8_SCHED; PG8_LDA(At, 0, 0); PG8_STAGE(PG8_SA(1, 1), a1 + hstep, voffA);
;             PG8_WAIT_V(8); PG8_WAIT_L(0); PG8_BAR; PG8_MMA(0, 0, At, B0); PG8_MMA(0, 1, At, B1); PG8_BAR; PG8_SCHED;
;             PG8_LDA(At, 0, 1); PG8_STAGE(PG8_SB(0, 0), b2, voffB); PG8_STAGE(PG8_SB(0, 1), b2 + hstep, voffB); PG8_STAGE(PG8_SA(0, 0), a2, voffA);
;             PG8_WAIT_V(8); PG8_WAIT_L(0); PG8_BAR; PG8_MMA(1, 0, At, B0); PG8_MMA(1, 1, At, B1); PG8_BAR; PG8_SCHED;
.LBB0_1089:
	s_ashr_i32 s11, s10, 31
	s_lshl_b64 s[12:13], s[10:11], 19
	s_add_u32 s12, s90, s12
	s_addc_u32 s13, s91, s13
	s_and_b64 s[14:15], s[4:5], exec
	s_cselect_b32 s11, s13, s17
	s_cselect_b32 s45, s12, s16
	s_ashr_i32 s9, s8, 31
	s_lshl_b64 s[14:15], s[8:9], 19
	s_add_u32 s14, s22, s14
	s_addc_u32 s15, s23, s15
	s_and_b64 s[20:21], s[4:5], exec
	s_cselect_b32 s9, s15, s19
	s_cselect_b32 s46, s14, s18
	s_add_u32 s16, s16, 0x40080
	s_addc_u32 s17, s17, 0
	s_add_u32 s47, s18, 0x100
	s_addc_u32 s48, s19, 0
	s_mov_b32 s49, -2
	s_add_u32 s18, s16, 0xfffc0080
	s_addc_u32 s19, s17, -1
	s_add_i32 s50, 0, 0x10000
	s_cmp_eq_u32 s49, 12
	s_cselect_b32 s21, s11, s19
	s_cselect_b32 s20, s45, s18
	s_cselect_b32 s19, s9, s48
	s_cselect_b32 s18, s46, s47
	s_add_i32 s52, 0, 0x14000
	v_lshl_add_u64 v[148:149], s[16:17], 0, v[136:137]
	s_add_i32 m0, s25, 0xc000
	global_load_lds_dwordx4 v[148:149], off
	v_lshl_add_u64 v[148:149], s[16:17], 0, v[138:139]
	s_add_i32 m0, s25, 0xe000
	s_nop 0
	global_load_lds_dwordx4 v[148:149], off
	s_waitcnt vmcnt(20)
	s_waitcnt lgkmcnt(0)
	s_barrier
	s_setprio 1
	s_waitcnt lgkmcnt(0)
	v_mfma_f32_16x16x32_bf16 v[126:129], v[140:143], v[200:203], 0
	v_mfma_f32_16x16x32_bf16 v[122:125], v[154:157], v[200:203], 0
	v_mfma_f32_16x16x32_bf16 v[118:121], v[140:143], v[208:211], 0
	v_mfma_f32_16x16x32_bf16 v[114:117], v[154:157], v[208:211], 0
	v_mfma_f32_16x16x32_bf16 v[110:113], v[140:143], v[216:219], 0
	v_mfma_f32_16x16x32_bf16 v[106:109], v[154:157], v[216:219], 0
	v_mfma_f32_16x16x32_bf16 v[102:105], v[140:143], v[224:227], 0
	v_mfma_f32_16x16x32_bf16 v[98:101], v[154:157], v[224:227], 0
	v_mfma_f32_16x16x32_bf16 v[126:129], v[144:147], v[204:207], v[126:129]
	v_mfma_f32_16x16x32_bf16 v[122:125], v[158:161], v[204:207], v[122:125]
	v_mfma_f32_16x16x32_bf16 v[118:121], v[144:147], v[212:215], v[118:121]
	v_mfma_f32_16x16x32_bf16 v[114:117], v[158:161], v[212:215], v[114:117]
	v_mfma_f32_16x16x32_bf16 v[110:113], v[144:147], v[220:223], v[110:113]
	v_mfma_f32_16x16x32_bf16 v[106:109], v[158:161], v[220:223], v[106:109]
	v_mfma_f32_16x16x32_bf16 v[102:105], v[144:147], v[228:231], v[102:105]
	v_mfma_f32_16x16x32_bf16 v[98:101], v[158:161], v[228:231], v[98:101]
	s_setprio 0
	s_setprio 1
	v_mfma_f32_16x16x32_bf16 v[62:65], v[162:165], v[200:203], 0
	v_mfma_f32_16x16x32_bf16 v[58:61], v[174:177], v[200:203], 0
	v_mfma_f32_16x16x32_bf16 v[54:57], v[162:165], v[208:211], 0
	v_mfma_f32_16x16x32_bf16 v[50:53], v[174:177], v[208:211], 0
	v_mfma_f32_16x16x32_bf16 v[46:49], v[162:165], v[216:219], 0
	v_mfma_f32_16x16x32_bf16 v[42:45], v[174:177], v[216:219], 0
	v_mfma_f32_16x16x32_bf16 v[38:41], v[162:165], v[224:227], 0
	v_mfma_f32_16x16x32_bf16 v[34:37], v[174:177], v[224:227], 0
	v_mfma_f32_16x16x32_bf16 v[62:65], v[170:173], v[204:207], v[62:65]
	v_mfma_f32_16x16x32_bf16 v[58:61], v[178:181], v[204:207], v[58:61]
	v_mfma_f32_16x16x32_bf16 v[54:57], v[170:173], v[212:215], v[54:57]
	v_mfma_f32_16x16x32_bf16 v[50:53], v[178:181], v[212:215], v[50:53]
	v_mfma_f32_16x16x32_bf16 v[46:49], v[170:173], v[220:223], v[46:49]
	v_mfma_f32_16x16x32_bf16 v[42:45], v[178:181], v[220:223], v[42:45]
	v_mfma_f32_16x16x32_bf16 v[38:41], v[170:173], v[228:231], v[38:41]
	v_mfma_f32_16x16x32_bf16 v[34:37], v[178:181], v[228:231], v[34:37]
	s_barrier
	s_setprio 0
	s_add_i32 s50, s50, s24
	v_lshl_add_u64 v[148:149], s[18:19], 0, v[0:1]
	s_mov_b32 m0, s50
	ds_read_b128 v[200:203], v169 offset:16384
	ds_read_b128 v[204:207], v169 offset:17408
	ds_read_b128 v[208:211], v169 offset:18432
	ds_read_b128 v[212:215], v169 offset:19456
	ds_read_b128 v[216:219], v169 offset:20480
	ds_read_b128 v[220:223], v169 offset:21504
	ds_read_b128 v[224:227], v169 offset:22528
	ds_read_b128 v[228:231], v169 offset:23552
	global_load_lds_dwordx4 v[148:149], off
	s_add_i32 m0, s50, 0x2000
	s_add_u32 s50, s18, 0x40000
	v_lshl_add_u64 v[232:233], s[18:19], 0, v[130:131]
	s_addc_u32 s51, s19, 0
	s_add_i32 s52, s52, s24
	global_load_lds_dwordx4 v[232:233], off
	v_lshl_add_u64 v[234:235], s[50:51], 0, v[0:1]
	s_mov_b32 m0, s52
	v_lshl_add_u64 v[236:237], s[20:21], 0, v[132:133]
	global_load_lds_dwordx4 v[234:235], off
	v_lshl_add_u64 v[234:235], s[50:51], 0, v[130:131]
	s_add_i32 m0, s52, 0x2000
	s_nop 0
	global_load_lds_dwordx4 v[234:235], off
	v_lshl_add_u64 v[234:235], s[20:21], 0, v[134:135]
	s_mov_b32 m0, s25
	s_nop 0
	global_load_lds_dwordx4 v[234:235], off
	s_mov_b32 m0, s26
	s_nop 0
	global_load_lds_dwordx4 v[236:237], off
	s_waitcnt vmcnt(20)
	s_waitcnt lgkmcnt(0)
	s_barrier
	s_setprio 1
	s_waitcnt lgkmcnt(0)
	v_mfma_f32_16x16x32_bf16 v[94:97], v[140:143], v[200:203], 0
	v_mfma_f32_16x16x32_bf16 v[90:93], v[154:157], v[200:203], 0
	v_mfma_f32_16x16x32_bf16 v[86:89], v[140:143], v[208:211], 0
	v_mfma_f32_16x16x32_bf16 v[82:85], v[154:157], v[208:211], 0
	v_mfma_f32_16x16x32_bf16 v[78:81], v[140:143], v[216:219], 0
	v_mfma_f32_16x16x32_bf16 v[74:77], v[154:157], v[216:219], 0
	v_mfma_f32_16x16x32_bf16 v[70:73], v[140:143], v[224:227], 0
	v_mfma_f32_16x16x32_bf16 v[66:69], v[154:157], v[224:227], 0
	v_mfma_f32_16x16x32_bf16 v[94:97], v[144:147], v[204:207], v[94:97]
	v_mfma_f32_16x16x32_bf16 v[90:93], v[158:161], v[204:207], v[90:93]
	v_mfma_f32_16x16x32_bf16 v[86:89], v[144:147], v[212:215], v[86:89]
	v_mfma_f32_16x16x32_bf16 v[82:85], v[158:161], v[212:215], v[82:85]
	v_mfma_f32_16x16x32_bf16 v[78:81], v[144:147], v[220:223], v[78:81]
	v_mfma_f32_16x16x32_bf16 v[74:77], v[158:161], v[220:223], v[74:77]
	v_mfma_f32_16x16x32_bf16 v[70:73], v[144:147], v[228:231], v[70:73]
	v_mfma_f32_16x16x32_bf16 v[66:69], v[158:161], v[228:231], v[66:69]
	s_setprio 0
	s_setprio 1
	v_mfma_f32_16x16x32_bf16 v[30:33], v[162:165], v[200:203], 0
	v_mfma_f32_16x16x32_bf16 v[26:29], v[174:177], v[200:203], 0
	v_mfma_f32_16x16x32_bf16 v[22:25], v[162:165], v[208:211], 0
	v_mfma_f32_16x16x32_bf16 v[18:21], v[174:177], v[208:211], 0
	v_mfma_f32_16x16x32_bf16 v[14:17], v[162:165], v[216:219], 0
	v_mfma_f32_16x16x32_bf16 v[10:13], v[174:177], v[216:219], 0
	v_mfma_f32_16x16x32_bf16 v[6:9], v[162:165], v[224:227], 0
	v_mfma_f32_16x16x32_bf16 v[2:5], v[174:177], v[224:227], 0
	v_mfma_f32_16x16x32_bf16 v[30:33], v[170:173], v[204:207], v[30:33]
	v_mfma_f32_16x16x32_bf16 v[26:29], v[178:181], v[204:207], v[26:29]
	v_mfma_f32_16x16x32_bf16 v[22:25], v[170:173], v[212:215], v[22:25]
	v_mfma_f32_16x16x32_bf16 v[18:21], v[178:181], v[212:215], v[18:21]
	v_mfma_f32_16x16x32_bf16 v[14:17], v[170:173], v[220:223], v[14:17]
	v_mfma_f32_16x16x32_bf16 v[10:13], v[178:181], v[220:223], v[10:13]
	v_mfma_f32_16x16x32_bf16 v[6:9], v[170:173], v[228:231], v[6:9]
	v_mfma_f32_16x16x32_bf16 v[2:5], v[178:181], v[228:231], v[2:5]
	s_barrier
; #define PG8_STAGE(bufoff, gbase, voff) do { _Pragma("unroll") for (int _i = 0; _i < 2; ++_i) \
;         __builtin_amdgcn_global_load_lds((const unsigned*)((const char*)(gbase) + (voff)[_i]), (PG8_LAS unsigned*)(lds + (bufoff) + ldsw + _i * 8192), 16, 0, 0); } while (0)
; #define PG8_LDA(dst, b, h) do { _Pragma("unroll") for (int m = 0; m < 4; ++m) _Pragma("unroll") for (int k = 0; k < 2; ++k) dst[m][k] = *(const PG8_LAS bf16x8*)(lds + PG8_SA(b, h) + aoff + m * 2048 + k * 1024); } while (0)
; #define PG8_LDB(dst, b, h) do { _Pragma("unroll") for (int n = 0; n < 2; ++n) _Pragma("unroll") for (int k = 0; k < 2; ++k) dst[n][k] = *(const PG8_LAS bf16x8*)(lds + PG8_SB(b, h) + boff + n * 2048 + k * 1024); } while (0)
; #define PG8_MMA(ai, bj, At, Bt) do { __builtin_amdgcn_s_setprio(1); _Pragma("unroll") for (int m = 0; m < 4; ++m) _Pragma("unroll") for (int n = 0; n < 2; ++n) _Pragma("unroll") for (int k = 0; k < 2; ++k) \
;         acc[ai][bj][m][n] = __builtin_amdgcn_mfma_f32_16x16x32_bf16(Bt[n][k], At[m][k], acc[ai][bj][m][n], 0, 0, 0); __builtin_amdgcn_s_setprio(0); } while (0)
; #define PG8_WAIT_V(n) asm volatile("s_waitcnt vmcnt(" #n ")" ::: "memory")
; #define PG8_WAIT_L(n) asm volatile("s_waitcnt lgkmcnt(" #n ")" ::: "memory")
; #define PG8_BAR __builtin_amdgcn_s_barrier()
; #define PG8_SCHED __builtin_amdgcn_sched_barrier(0)
; template <class Epi, class Sched, bool ALIGN_EPI = false, bool SP2 = false>
; __device__ __forceinline__ void gemm_phase(PG8_LAS unsigned char* lds, const Gemm g, const Sched& S, const Epi& E) {
;     ...
;             PG8_LDB(B0, 1, 0); PG8_LDB(B1, 1, 1); PG8_SCHED; PG8_LDA(At, 1, 0); PG8_STAGE(PG8_SA(0, 1), a2 + hstep, voffA);
;             PG8_WAIT_V(8); PG8_WAIT_L(0); PG8_BAR; PG8_MMA(0, 0, At, B0); PG8_MMA(0, 1, At, B1); PG8_BAR; PG8_SCHED;
;             PG8_LDA(At, 1, 1); PG8_STAGE(PG8_SB(1, 0), b3, voffB); PG8_STAGE(PG8_SB(1, 1), b3 + hstep, voffB); PG8_STAGE(PG8_SA(1, 0), a3, voffA);
;             PG8_WAIT_V(8); PG8_WAIT_L(0); PG8_BAR; PG8_MMA(1, 0, At, B0); PG8_MMA(1, 1, At, B1); PG8_BAR; PG8_SCHED;
	s_setprio 0
	s_add_i32 s50, 0, 0x18000
	s_add_i32 s51, 0, 0x1c000
	v_add_u32_e32 v158, s50, v167
	v_add_u32_e32 v178, s51, v167
	ds_read_b128 v[140:143], v158
	ds_read_b128 v[144:147], v158 offset:1024
	ds_read_b128 v[154:157], v158 offset:2048
	ds_read_b128 v[158:161], v158 offset:3072
	ds_read_b128 v[162:165], v178
	ds_read_b128 v[170:173], v178 offset:1024
	ds_read_b128 v[174:177], v178 offset:2048
	ds_read_b128 v[178:181], v178 offset:3072
	s_add_u32 s20, s20, 0x40000
	s_addc_u32 s21, s21, 0
	s_mov_b32 m0, s27
	v_lshl_add_u64 v[238:239], s[20:21], 0, v[134:135]
	ds_read_b128 v[200:203], v169 offset:32768
	ds_read_b128 v[204:207], v169 offset:33792
	ds_read_b128 v[208:211], v169 offset:34816
	ds_read_b128 v[212:215], v169 offset:35840
	ds_read_b128 v[216:219], v169 offset:36864
	ds_read_b128 v[220:223], v169 offset:37888
	ds_read_b128 v[224:227], v169 offset:38912
	ds_read_b128 v[228:231], v169 offset:39936
	global_load_lds_dwordx4 v[238:239], off
	v_lshl_add_u64 v[238:239], s[20:21], 0, v[132:133]
	s_mov_b32 m0, s28
	s_nop 0
	global_load_lds_dwordx4 v[238:239], off
	s_waitcnt vmcnt(8)
	s_waitcnt lgkmcnt(0)
	s_barrier
	s_setprio 1
	s_waitcnt lgkmcnt(0)
	v_mfma_f32_16x16x32_bf16 v[126:129], v[140:143], v[200:203], v[126:129]
	v_mfma_f32_16x16x32_bf16 v[122:125], v[154:157], v[200:203], v[122:125]
	v_mfma_f32_16x16x32_bf16 v[118:121], v[140:143], v[208:211], v[118:121]
	v_mfma_f32_16x16x32_bf16 v[114:117], v[154:157], v[208:211], v[114:117]
	v_mfma_f32_16x16x32_bf16 v[110:113], v[140:143], v[216:219], v[110:113]
	v_mfma_f32_16x16x32_bf16 v[106:109], v[154:157], v[216:219], v[106:109]
	v_mfma_f32_16x16x32_bf16 v[102:105], v[140:143], v[224:227], v[102:105]
	v_mfma_f32_16x16x32_bf16 v[98:101], v[154:157], v[224:227], v[98:101]
	v_mfma_f32_16x16x32_bf16 v[126:129], v[144:147], v[204:207], v[126:129]
	v_mfma_f32_16x16x32_bf16 v[122:125], v[158:161], v[204:207], v[122:125]
	v_mfma_f32_16x16x32_bf16 v[118:121], v[144:147], v[212:215], v[118:121]
	v_mfma_f32_16x16x32_bf16 v[114:117], v[158:161], v[212:215], v[114:117]
	v_mfma_f32_16x16x32_bf16 v[110:113], v[144:147], v[220:223], v[110:113]
	v_mfma_f32_16x16x32_bf16 v[106:109], v[158:161], v[220:223], v[106:109]
	v_mfma_f32_16x16x32_bf16 v[102:105], v[144:147], v[228:231], v[102:105]
	v_mfma_f32_16x16x32_bf16 v[98:101], v[158:161], v[228:231], v[98:101]
	s_setprio 0
	s_setprio 1
	v_mfma_f32_16x16x32_bf16 v[62:65], v[162:165], v[200:203], v[62:65]
	v_mfma_f32_16x16x32_bf16 v[58:61], v[174:177], v[200:203], v[58:61]
	v_mfma_f32_16x16x32_bf16 v[54:57], v[162:165], v[208:211], v[54:57]
	v_mfma_f32_16x16x32_bf16 v[50:53], v[174:177], v[208:211], v[50:53]
	v_mfma_f32_16x16x32_bf16 v[46:49], v[162:165], v[216:219], v[46:49]
	v_mfma_f32_16x16x32_bf16 v[42:45], v[174:177], v[216:219], v[42:45]
	v_mfma_f32_16x16x32_bf16 v[38:41], v[162:165], v[224:227], v[38:41]
	v_mfma_f32_16x16x32_bf16 v[34:37], v[174:177], v[224:227], v[34:37]
	v_mfma_f32_16x16x32_bf16 v[62:65], v[170:173], v[204:207], v[62:65]
	v_mfma_f32_16x16x32_bf16 v[58:61], v[178:181], v[204:207], v[58:61]
	v_mfma_f32_16x16x32_bf16 v[54:57], v[170:173], v[212:215], v[54:57]
	v_mfma_f32_16x16x32_bf16 v[50:53], v[178:181], v[212:215], v[50:53]
	v_mfma_f32_16x16x32_bf16 v[46:49], v[170:173], v[220:223], v[46:49]
	v_mfma_f32_16x16x32_bf16 v[42:45], v[178:181], v[220:223], v[42:45]
	v_mfma_f32_16x16x32_bf16 v[38:41], v[170:173], v[228:231], v[38:41]
	v_mfma_f32_16x16x32_bf16 v[34:37], v[178:181], v[228:231], v[34:37]
	s_barrier
	s_setprio 0
	s_add_i32 s20, s50, s24
	v_lshl_add_u64 v[148:149], v[148:149], 0, s[38:39]
	s_mov_b32 m0, s20
	ds_read_b128 v[200:203], v169 offset:49152
	ds_read_b128 v[204:207], v169 offset:50176
	ds_read_b128 v[208:211], v169 offset:51200
	ds_read_b128 v[212:215], v169 offset:52224
	ds_read_b128 v[216:219], v169 offset:53248
	ds_read_b128 v[220:223], v169 offset:54272
	ds_read_b128 v[224:227], v169 offset:55296
	ds_read_b128 v[228:231], v169 offset:56320
	global_load_lds_dwordx4 v[148:149], off
	s_add_i32 m0, s20, 0x2000
	s_add_u32 s18, s18, 0x40080
	v_lshl_add_u64 v[148:149], v[232:233], 0, s[38:39]
	s_addc_u32 s19, s19, 0
	s_add_i32 s20, s51, s24
	global_load_lds_dwordx4 v[148:149], off
	v_lshl_add_u64 v[148:149], s[18:19], 0, v[0:1]
	s_mov_b32 m0, s20
	s_nop 0
	global_load_lds_dwordx4 v[148:149], off
	v_lshl_add_u64 v[148:149], s[18:19], 0, v[130:131]
	s_add_i32 m0, s20, 0x2000
	s_nop 0
	global_load_lds_dwordx4 v[148:149], off
	v_lshl_add_u64 v[148:149], v[234:235], 0, s[38:39]
	s_mov_b32 m0, s31
	s_nop 0
	global_load_lds_dwordx4 v[148:149], off
	v_lshl_add_u64 v[148:149], v[236:237], 0, s[38:39]
	s_mov_b32 m0, s33
	s_nop 0
	global_load_lds_dwordx4 v[148:149], off
	s_waitcnt vmcnt(8)
	s_waitcnt lgkmcnt(0)
	s_barrier
; #define PG8_STAGE(bufoff, gbase, voff) do { _Pragma("unroll") for (int _i = 0; _i < 2; ++_i) \
;         __builtin_amdgcn_global_load_lds((const unsigned*)((const char*)(gbase) + (voff)[_i]), (PG8_LAS unsigned*)(lds + (bufoff) + ldsw + _i * 8192), 16, 0, 0); } while (0)
; #define PG8_LDA(dst, b, h) do { _Pragma("unroll") for (int m = 0; m < 4; ++m) _Pragma("unroll") for (int k = 0; k < 2; ++k) dst[m][k] = *(const PG8_LAS bf16x8*)(lds + PG8_SA(b, h) + aoff + m * 2048 + k * 1024); } while (0)
; #define PG8_LDB(dst, b, h) do { _Pragma("unroll") for (int n = 0; n < 2; ++n) _Pragma("unroll") for (int k = 0; k < 2; ++k) dst[n][k] = *(const PG8_LAS bf16x8*)(lds + PG8_SB(b, h) + boff + n * 2048 + k * 1024); } while (0)
; #define PG8_BAR __builtin_amdgcn_s_barrier()
; template <class Epi, class Sched, bool ALIGN_EPI = false, bool SP2 = false>
; __device__ __forceinline__ void gemm_phase(PG8_LAS unsigned char* lds, const Gemm g, const Sched& S, const Epi& E) {
;     ...
;             const bool last = (t == nt - 2);
;             const char* a1 = cA + (size_t)(t + 1) * kstep;
;             const char* a2 = last ? nA : cA + (size_t)(t + 2) * kstep; const char* b2 = last ? nB : cB + (size_t)(t + 2) * kstep;
;             const char* a3 = a2 + kstep; const char* b3 = b2 + kstep;
;             if (last && has_next) S.a_ready(nxt);
;             if constexpr (SP2) {
;             PG8_LDB(B0, 0, 0); PG8_LDB(B1, 0, 1); PG8_SCHED; PG8_LDA(At, 0, 0); PG8_STAGE(PG8_SA(1, 1), a1 + hstep, voffA);
;             PG8_WAIT_V(8); PG8_WAIT_L(0); PG8_BAR; PG8_MMA(0, 0, At, B0); PG8_MMA(0, 1, At, B1); PG8_BAR; PG8_SCHED;
;             PG8_LDA(At, 0, 1); PG8_STAGE(PG8_SB(0, 0), b2, voffB); PG8_STAGE(PG8_SB(0, 1), b2 + hstep, voffB); PG8_STAGE(PG8_SA(0, 0), a2, voffA);
;             PG8_WAIT_V(8); PG8_WAIT_L(0); PG8_BAR; PG8_MMA(1, 0, At, B0); PG8_MMA(1, 1, At, B1); PG8_BAR; PG8_SCHED;
;             PG8_LDB(B0, 1, 0); PG8_LDB(B1, 1, 1); PG8_SCHED; PG8_LDA(At, 1, 0); PG8_STAGE(PG8_SA(0, 1), a2 + hstep, voffA);
;             PG8_WAIT_V(8); PG8_WAIT_L(0); PG8_BAR; PG8_MMA(0, 0, At, B0); PG8_MMA(0, 1, At, B1); PG8_BAR; PG8_SCHED;
;             PG8_LDA(At, 1, 1); PG8_STAGE(PG8_SB(1, 0), b3, voffB); PG8_STAGE(PG8_SB(1, 1), b3 + hstep, voffB); PG8_STAGE(PG8_SA(1, 0), a3, voffA);
;             PG8_WAIT_V(8); PG8_WAIT_L(0); PG8_BAR; PG8_MMA(1, 0, At, B0); PG8_MMA(1, 1, At, B1); PG8_BAR; PG8_SCHED;
	s_setprio 1
	s_waitcnt lgkmcnt(0)
	v_mfma_f32_16x16x32_bf16 v[94:97], v[140:143], v[200:203], v[94:97]
	v_mfma_f32_16x16x32_bf16 v[90:93], v[154:157], v[200:203], v[90:93]
	v_mfma_f32_16x16x32_bf16 v[86:89], v[140:143], v[208:211], v[86:89]
	v_mfma_f32_16x16x32_bf16 v[82:85], v[154:157], v[208:211], v[82:85]
	v_mfma_f32_16x16x32_bf16 v[78:81], v[140:143], v[216:219], v[78:81]
	v_mfma_f32_16x16x32_bf16 v[74:77], v[154:157], v[216:219], v[74:77]
	v_mfma_f32_16x16x32_bf16 v[70:73], v[140:143], v[224:227], v[70:73]
	v_mfma_f32_16x16x32_bf16 v[66:69], v[154:157], v[224:227], v[66:69]
	v_mfma_f32_16x16x32_bf16 v[94:97], v[144:147], v[204:207], v[94:97]
	v_mfma_f32_16x16x32_bf16 v[90:93], v[158:161], v[204:207], v[90:93]
	v_mfma_f32_16x16x32_bf16 v[86:89], v[144:147], v[212:215], v[86:89]
	v_mfma_f32_16x16x32_bf16 v[82:85], v[158:161], v[212:215], v[82:85]
	v_mfma_f32_16x16x32_bf16 v[78:81], v[144:147], v[220:223], v[78:81]
	v_mfma_f32_16x16x32_bf16 v[74:77], v[158:161], v[220:223], v[74:77]
	v_mfma_f32_16x16x32_bf16 v[70:73], v[144:147], v[228:231], v[70:73]
	v_mfma_f32_16x16x32_bf16 v[66:69], v[158:161], v[228:231], v[66:69]
	s_setprio 0
	s_setprio 1
	v_mfma_f32_16x16x32_bf16 v[30:33], v[162:165], v[200:203], v[30:33]
	v_mfma_f32_16x16x32_bf16 v[26:29], v[174:177], v[200:203], v[26:29]
	v_mfma_f32_16x16x32_bf16 v[22:25], v[162:165], v[208:211], v[22:25]
	v_mfma_f32_16x16x32_bf16 v[18:21], v[174:177], v[208:211], v[18:21]
	v_mfma_f32_16x16x32_bf16 v[14:17], v[162:165], v[216:219], v[14:17]
	v_mfma_f32_16x16x32_bf16 v[10:13], v[174:177], v[216:219], v[10:13]
	v_mfma_f32_16x16x32_bf16 v[6:9], v[162:165], v[224:227], v[6:9]
	v_mfma_f32_16x16x32_bf16 v[2:5], v[174:177], v[224:227], v[2:5]
	v_mfma_f32_16x16x32_bf16 v[30:33], v[170:173], v[204:207], v[30:33]
	v_mfma_f32_16x16x32_bf16 v[26:29], v[178:181], v[204:207], v[26:29]
	v_mfma_f32_16x16x32_bf16 v[22:25], v[170:173], v[212:215], v[22:25]
	v_mfma_f32_16x16x32_bf16 v[18:21], v[178:181], v[212:215], v[18:21]
	v_mfma_f32_16x16x32_bf16 v[14:17], v[170:173], v[220:223], v[14:17]
	v_mfma_f32_16x16x32_bf16 v[10:13], v[178:181], v[220:223], v[10:13]
	v_mfma_f32_16x16x32_bf16 v[6:9], v[170:173], v[228:231], v[6:9]
	v_mfma_f32_16x16x32_bf16 v[2:5], v[178:181], v[228:231], v[2:5]
	s_barrier
	s_setprio 0
	s_add_i32 s49, s49, 2
	s_add_u32 s16, s16, 0x100
	s_addc_u32 s17, s17, 0
	s_add_u32 s47, s47, 0x100
	s_addc_u32 s48, s48, 0
.LBB0_1090:
	s_add_u32 s18, s16, 0xfffc0080
	s_addc_u32 s19, s17, -1
	s_add_i32 s50, 0, 0x10000
	s_cmp_eq_u32 s49, 12
	s_cselect_b32 s21, s11, s19
	s_cselect_b32 s20, s45, s18
	v_add_u32_e32 v148, s50, v167
	s_cselect_b32 s19, s9, s48
	s_cselect_b32 s18, s46, s47
	s_add_i32 s52, 0, 0x14000
	ds_read_b128 v[140:143], v148
	ds_read_b128 v[144:147], v148 offset:1024
	ds_read_b128 v[154:157], v148 offset:2048
	ds_read_b128 v[158:161], v148 offset:3072
	v_add_u32_e32 v148, s52, v167
	ds_read_b128 v[162:165], v148
	ds_read_b128 v[170:173], v148 offset:1024
	ds_read_b128 v[174:177], v148 offset:2048
	ds_read_b128 v[178:181], v148 offset:3072
	v_lshl_add_u64 v[148:149], s[16:17], 0, v[136:137]
	s_add_i32 m0, s25, 0xc000
	ds_read_b128 v[200:203], v169
	ds_read_b128 v[204:207], v169 offset:1024
	ds_read_b128 v[208:211], v169 offset:2048
	ds_read_b128 v[212:215], v169 offset:3072
	ds_read_b128 v[216:219], v169 offset:4096
	ds_read_b128 v[220:223], v169 offset:5120
	ds_read_b128 v[224:227], v169 offset:6144
	ds_read_b128 v[228:231], v169 offset:7168
	global_load_lds_dwordx4 v[148:149], off
	v_lshl_add_u64 v[148:149], s[16:17], 0, v[138:139]
	s_add_i32 m0, s25, 0xe000
	s_nop 0
	global_load_lds_dwordx4 v[148:149], off
	s_waitcnt vmcnt(8)
	s_waitcnt lgkmcnt(0)
	s_barrier
	s_setprio 1
	s_waitcnt lgkmcnt(0)
	v_mfma_f32_16x16x32_bf16 v[126:129], v[140:143], v[200:203], v[126:129]
	v_mfma_f32_16x16x32_bf16 v[122:125], v[154:157], v[200:203], v[122:125]
	v_mfma_f32_16x16x32_bf16 v[118:121], v[140:143], v[208:211], v[118:121]
	v_mfma_f32_16x16x32_bf16 v[114:117], v[154:157], v[208:211], v[114:117]
	v_mfma_f32_16x16x32_bf16 v[110:113], v[140:143], v[216:219], v[110:113]
	v_mfma_f32_16x16x32_bf16 v[106:109], v[154:157], v[216:219], v[106:109]
	v_mfma_f32_16x16x32_bf16 v[102:105], v[140:143], v[224:227], v[102:105]
	v_mfma_f32_16x16x32_bf16 v[98:101], v[154:157], v[224:227], v[98:101]
	v_mfma_f32_16x16x32_bf16 v[126:129], v[144:147], v[204:207], v[126:129]
	v_mfma_f32_16x16x32_bf16 v[122:125], v[158:161], v[204:207], v[122:125]
	v_mfma_f32_16x16x32_bf16 v[118:121], v[144:147], v[212:215], v[118:121]
	v_mfma_f32_16x16x32_bf16 v[114:117], v[158:161], v[212:215], v[114:117]
	v_mfma_f32_16x16x32_bf16 v[110:113], v[144:147], v[220:223], v[110:113]
	v_mfma_f32_16x16x32_bf16 v[106:109], v[158:161], v[220:223], v[106:109]
	v_mfma_f32_16x16x32_bf16 v[102:105], v[144:147], v[228:231], v[102:105]
	v_mfma_f32_16x16x32_bf16 v[98:101], v[158:161], v[228:231], v[98:101]
	s_setprio 0
	s_setprio 1
	v_mfma_f32_16x16x32_bf16 v[62:65], v[162:165], v[200:203], v[62:65]
	v_mfma_f32_16x16x32_bf16 v[58:61], v[174:177], v[200:203], v[58:61]
	v_mfma_f32_16x16x32_bf16 v[54:57], v[162:165], v[208:211], v[54:57]
	v_mfma_f32_16x16x32_bf16 v[50:53], v[174:177], v[208:211], v[50:53]
	v_mfma_f32_16x16x32_bf16 v[46:49], v[162:165], v[216:219], v[46:49]
	v_mfma_f32_16x16x32_bf16 v[42:45], v[174:177], v[216:219], v[42:45]
	v_mfma_f32_16x16x32_bf16 v[38:41], v[162:165], v[224:227], v[38:41]
	v_mfma_f32_16x16x32_bf16 v[34:37], v[174:177], v[224:227], v[34:37]
	v_mfma_f32_16x16x32_bf16 v[62:65], v[170:173], v[204:207], v[62:65]
	v_mfma_f32_16x16x32_bf16 v[58:61], v[178:181], v[204:207], v[58:61]
	v_mfma_f32_16x16x32_bf16 v[54:57], v[170:173], v[212:215], v[54:57]
	v_mfma_f32_16x16x32_bf16 v[50:53], v[178:181], v[212:215], v[50:53]
	v_mfma_f32_16x16x32_bf16 v[46:49], v[170:173], v[220:223], v[46:49]
	v_mfma_f32_16x16x32_bf16 v[42:45], v[178:181], v[220:223], v[42:45]
	v_mfma_f32_16x16x32_bf16 v[38:41], v[170:173], v[228:231], v[38:41]
	v_mfma_f32_16x16x32_bf16 v[34:37], v[178:181], v[228:231], v[34:37]
	s_barrier
; #define PG8_STAGE(bufoff, gbase, voff) do { _Pragma("unroll") for (int _i = 0; _i < 2; ++_i) \
;         __builtin_amdgcn_global_load_lds((const unsigned*)((const char*)(gbase) + (voff)[_i]), (PG8_LAS unsigned*)(lds + (bufoff) + ldsw + _i * 8192), 16, 0, 0); } while (0)
; #define PG8_LDA(dst, b, h) do { _Pragma("unroll") for (int m = 0; m < 4; ++m) _Pragma("unroll") for (int k = 0; k < 2; ++k) dst[m][k] = *(const PG8_LAS bf16x8*)(lds + PG8_SA(b, h) + aoff + m * 2048 + k * 1024); } while (0)
; #define PG8_LDB(dst, b, h) do { _Pragma("unroll") for (int n = 0; n < 2; ++n) _Pragma("unroll") for (int k = 0; k < 2; ++k) dst[n][k] = *(const PG8_LAS bf16x8*)(lds + PG8_SB(b, h) + boff + n * 2048 + k * 1024); } while (0)
; #define PG8_MMA(ai, bj, At, Bt) do { __builtin_amdgcn_s_setprio(1); _Pragma("unroll") for (int m = 0; m < 4; ++m) _Pragma("unroll") for (int n = 0; n < 2; ++n) _Pragma("unroll") for (int k = 0; k < 2; ++k) \
;         acc[ai][bj][m][n] = __builtin_amdgcn_mfma_f32_16x16x32_bf16(Bt[n][k], At[m][k], acc[ai][bj][m][n], 0, 0, 0); __builtin_amdgcn_s_setprio(0); } while (0)
; #define PG8_WAIT_V(n) asm volatile("s_waitcnt vmcnt(" #n ")" ::: "memory")
; #define PG8_WAIT_L(n) asm volatile("s_waitcnt lgkmcnt(" #n ")" ::: "memory")
; #define PG8_BAR __builtin_amdgcn_s_barrier()
; #define PG8_SCHED __builtin_amdgcn_sched_barrier(0)
; template <class Epi, class Sched, bool ALIGN_EPI = false, bool SP2 = false>
; __device__ __forceinline__ void gemm_phase(PG8_LAS unsigned char* lds, const Gemm g, const Sched& S, const Epi& E) {
;     ...
;             PG8_LDA(At, 0, 1); PG8_STAGE(PG8_SB(0, 0), b2, voffB); PG8_STAGE(PG8_SB(0, 1), b2 + hstep, voffB); PG8_STAGE(PG8_SA(0, 0), a2, voffA);
;             PG8_WAIT_V(8); PG8_WAIT_L(0); PG8_BAR; PG8_MMA(1, 0, At, B0); PG8_MMA(1, 1, At, B1); PG8_BAR; PG8_SCHED;
;             PG8_LDB(B0, 1, 0); PG8_LDB(B1, 1, 1); PG8_SCHED; PG8_LDA(At, 1, 0); PG8_STAGE(PG8_SA(0, 1), a2 + hstep, voffA);
;             PG8_WAIT_V(8); PG8_WAIT_L(0); PG8_BAR; PG8_MMA(0, 0, At, B0); PG8_MMA(0, 1, At, B1); PG8_BAR; PG8_SCHED;
	s_setprio 0
	s_add_i32 s50, s50, s24
	v_lshl_add_u64 v[148:149], s[18:19], 0, v[0:1]
	s_mov_b32 m0, s50
	ds_read_b128 v[200:203], v169 offset:16384
	ds_read_b128 v[204:207], v169 offset:17408
	ds_read_b128 v[208:211], v169 offset:18432
	ds_read_b128 v[212:215], v169 offset:19456
	ds_read_b128 v[216:219], v169 offset:20480
	ds_read_b128 v[220:223], v169 offset:21504
	ds_read_b128 v[224:227], v169 offset:22528
	ds_read_b128 v[228:231], v169 offset:23552
	global_load_lds_dwordx4 v[148:149], off
	s_add_i32 m0, s50, 0x2000
	s_add_u32 s50, s18, 0x40000
	v_lshl_add_u64 v[232:233], s[18:19], 0, v[130:131]
	s_addc_u32 s51, s19, 0
	s_add_i32 s52, s52, s24
	global_load_lds_dwordx4 v[232:233], off
	v_lshl_add_u64 v[234:235], s[50:51], 0, v[0:1]
	s_mov_b32 m0, s52
	v_lshl_add_u64 v[236:237], s[20:21], 0, v[132:133]
	global_load_lds_dwordx4 v[234:235], off
	v_lshl_add_u64 v[234:235], s[50:51], 0, v[130:131]
	s_add_i32 m0, s52, 0x2000
	s_nop 0
	global_load_lds_dwordx4 v[234:235], off
	v_lshl_add_u64 v[234:235], s[20:21], 0, v[134:135]
	s_mov_b32 m0, s25
	s_nop 0
	global_load_lds_dwordx4 v[234:235], off
	s_mov_b32 m0, s26
	s_nop 0
	global_load_lds_dwordx4 v[236:237], off
	s_waitcnt vmcnt(8)
	s_waitcnt lgkmcnt(0)
	s_barrier
	s_setprio 1
	s_waitcnt lgkmcnt(0)
	v_mfma_f32_16x16x32_bf16 v[94:97], v[140:143], v[200:203], v[94:97]
	v_mfma_f32_16x16x32_bf16 v[90:93], v[154:157], v[200:203], v[90:93]
	v_mfma_f32_16x16x32_bf16 v[86:89], v[140:143], v[208:211], v[86:89]
	v_mfma_f32_16x16x32_bf16 v[82:85], v[154:157], v[208:211], v[82:85]
	v_mfma_f32_16x16x32_bf16 v[78:81], v[140:143], v[216:219], v[78:81]
	v_mfma_f32_16x16x32_bf16 v[74:77], v[154:157], v[216:219], v[74:77]
	v_mfma_f32_16x16x32_bf16 v[70:73], v[140:143], v[224:227], v[70:73]
	v_mfma_f32_16x16x32_bf16 v[66:69], v[154:157], v[224:227], v[66:69]
	v_mfma_f32_16x16x32_bf16 v[94:97], v[144:147], v[204:207], v[94:97]
	v_mfma_f32_16x16x32_bf16 v[90:93], v[158:161], v[204:207], v[90:93]
	v_mfma_f32_16x16x32_bf16 v[86:89], v[144:147], v[212:215], v[86:89]
	v_mfma_f32_16x16x32_bf16 v[82:85], v[158:161], v[212:215], v[82:85]
	v_mfma_f32_16x16x32_bf16 v[78:81], v[144:147], v[220:223], v[78:81]
	v_mfma_f32_16x16x32_bf16 v[74:77], v[158:161], v[220:223], v[74:77]
	v_mfma_f32_16x16x32_bf16 v[70:73], v[144:147], v[228:231], v[70:73]
	v_mfma_f32_16x16x32_bf16 v[66:69], v[158:161], v[228:231], v[66:69]
	s_setprio 0
	s_setprio 1
	v_mfma_f32_16x16x32_bf16 v[30:33], v[162:165], v[200:203], v[30:33]
	v_mfma_f32_16x16x32_bf16 v[26:29], v[174:177], v[200:203], v[26:29]
	v_mfma_f32_16x16x32_bf16 v[22:25], v[162:165], v[208:211], v[22:25]
	v_mfma_f32_16x16x32_bf16 v[18:21], v[174:177], v[208:211], v[18:21]
	v_mfma_f32_16x16x32_bf16 v[14:17], v[162:165], v[216:219], v[14:17]
	v_mfma_f32_16x16x32_bf16 v[10:13], v[174:177], v[216:219], v[10:13]
	v_mfma_f32_16x16x32_bf16 v[6:9], v[162:165], v[224:227], v[6:9]
	v_mfma_f32_16x16x32_bf16 v[2:5], v[174:177], v[224:227], v[2:5]
	v_mfma_f32_16x16x32_bf16 v[30:33], v[170:173], v[204:207], v[30:33]
	v_mfma_f32_16x16x32_bf16 v[26:29], v[178:181], v[204:207], v[26:29]
	v_mfma_f32_16x16x32_bf16 v[22:25], v[170:173], v[212:215], v[22:25]
	v_mfma_f32_16x16x32_bf16 v[18:21], v[178:181], v[212:215], v[18:21]
	v_mfma_f32_16x16x32_bf16 v[14:17], v[170:173], v[220:223], v[14:17]
	v_mfma_f32_16x16x32_bf16 v[10:13], v[178:181], v[220:223], v[10:13]
	v_mfma_f32_16x16x32_bf16 v[6:9], v[170:173], v[228:231], v[6:9]
	v_mfma_f32_16x16x32_bf16 v[2:5], v[178:181], v[228:231], v[2:5]
	s_barrier
	s_setprio 0
	s_add_i32 s50, 0, 0x18000
	s_add_i32 s51, 0, 0x1c000
	v_add_u32_e32 v158, s50, v167
	v_add_u32_e32 v178, s51, v167
	ds_read_b128 v[140:143], v158
	ds_read_b128 v[144:147], v158 offset:1024
	ds_read_b128 v[154:157], v158 offset:2048
	ds_read_b128 v[158:161], v158 offset:3072
	ds_read_b128 v[162:165], v178
	ds_read_b128 v[170:173], v178 offset:1024
	ds_read_b128 v[174:177], v178 offset:2048
	ds_read_b128 v[178:181], v178 offset:3072
	s_add_u32 s20, s20, 0x40000
	s_addc_u32 s21, s21, 0
	s_mov_b32 m0, s27
	v_lshl_add_u64 v[238:239], s[20:21], 0, v[134:135]
	ds_read_b128 v[200:203], v169 offset:32768
	ds_read_b128 v[204:207], v169 offset:33792
	ds_read_b128 v[208:211], v169 offset:34816
	ds_read_b128 v[212:215], v169 offset:35840
	ds_read_b128 v[216:219], v169 offset:36864
	ds_read_b128 v[220:223], v169 offset:37888
	ds_read_b128 v[224:227], v169 offset:38912
	ds_read_b128 v[228:231], v169 offset:39936
	global_load_lds_dwordx4 v[238:239], off
	v_lshl_add_u64 v[238:239], s[20:21], 0, v[132:133]
	s_mov_b32 m0, s28
	s_nop 0
	global_load_lds_dwordx4 v[238:239], off
	s_waitcnt vmcnt(8)
	s_waitcnt lgkmcnt(0)
	s_barrier
; #define PG8_STAGE(bufoff, gbase, voff) do { _Pragma("unroll") for (int _i = 0; _i < 2; ++_i) \
;         __builtin_amdgcn_global_load_lds((const unsigned*)((const char*)(gbase) + (voff)[_i]), (PG8_LAS unsigned*)(lds + (bufoff) + ldsw + _i * 8192), 16, 0, 0); } while (0)
; #define PG8_LDA(dst, b, h) do { _Pragma("unroll") for (int m = 0; m < 4; ++m) _Pragma("unroll") for (int k = 0; k < 2; ++k) dst[m][k] = *(const PG8_LAS bf16x8*)(lds + PG8_SA(b, h) + aoff + m * 2048 + k * 1024); } while (0)
; #define PG8_MMA(ai, bj, At, Bt) do { __builtin_amdgcn_s_setprio(1); _Pragma("unroll") for (int m = 0; m < 4; ++m) _Pragma("unroll") for (int n = 0; n < 2; ++n) _Pragma("unroll") for (int k = 0; k < 2; ++k) \
;         acc[ai][bj][m][n] = __builtin_amdgcn_mfma_f32_16x16x32_bf16(Bt[n][k], At[m][k], acc[ai][bj][m][n], 0, 0, 0); __builtin_amdgcn_s_setprio(0); } while (0)
; #define PG8_WAIT_V(n) asm volatile("s_waitcnt vmcnt(" #n ")" ::: "memory")
; #define PG8_WAIT_L(n) asm volatile("s_waitcnt lgkmcnt(" #n ")" ::: "memory")
; #define PG8_BAR __builtin_amdgcn_s_barrier()
; #define PG8_SCHED __builtin_amdgcn_sched_barrier(0)
; template <class Epi, class Sched, bool ALIGN_EPI = false, bool SP2 = false>
; __device__ __forceinline__ void gemm_phase(PG8_LAS unsigned char* lds, const Gemm g, const Sched& S, const Epi& E) {
;     ...
;             PG8_WAIT_V(8); PG8_WAIT_L(0); PG8_BAR; PG8_MMA(0, 0, At, B0); PG8_MMA(0, 1, At, B1); PG8_BAR; PG8_SCHED;
;             PG8_LDA(At, 1, 1); PG8_STAGE(PG8_SB(1, 0), b3, voffB); PG8_STAGE(PG8_SB(1, 1), b3 + hstep, voffB); PG8_STAGE(PG8_SA(1, 0), a3, voffA);
;             PG8_WAIT_V(8); PG8_WAIT_L(0); PG8_BAR; PG8_MMA(1, 0, At, B0); PG8_MMA(1, 1, At, B1); PG8_BAR; PG8_SCHED;
;     ...
;         if constexpr (ALIGN_EPI) { if (wr == 0) PG8_BAR; }
	s_setprio 1
	s_waitcnt lgkmcnt(0)
	v_mfma_f32_16x16x32_bf16 v[126:129], v[140:143], v[200:203], v[126:129]
	v_mfma_f32_16x16x32_bf16 v[122:125], v[154:157], v[200:203], v[122:125]
	v_mfma_f32_16x16x32_bf16 v[118:121], v[140:143], v[208:211], v[118:121]
	v_mfma_f32_16x16x32_bf16 v[114:117], v[154:157], v[208:211], v[114:117]
	v_mfma_f32_16x16x32_bf16 v[110:113], v[140:143], v[216:219], v[110:113]
	v_mfma_f32_16x16x32_bf16 v[106:109], v[154:157], v[216:219], v[106:109]
	v_mfma_f32_16x16x32_bf16 v[102:105], v[140:143], v[224:227], v[102:105]
	v_mfma_f32_16x16x32_bf16 v[98:101], v[154:157], v[224:227], v[98:101]
	v_mfma_f32_16x16x32_bf16 v[126:129], v[144:147], v[204:207], v[126:129]
	v_mfma_f32_16x16x32_bf16 v[122:125], v[158:161], v[204:207], v[122:125]
	v_mfma_f32_16x16x32_bf16 v[118:121], v[144:147], v[212:215], v[118:121]
	v_mfma_f32_16x16x32_bf16 v[114:117], v[158:161], v[212:215], v[114:117]
	v_mfma_f32_16x16x32_bf16 v[110:113], v[144:147], v[220:223], v[110:113]
	v_mfma_f32_16x16x32_bf16 v[106:109], v[158:161], v[220:223], v[106:109]
	v_mfma_f32_16x16x32_bf16 v[102:105], v[144:147], v[228:231], v[102:105]
	v_mfma_f32_16x16x32_bf16 v[98:101], v[158:161], v[228:231], v[98:101]
	s_setprio 0
	s_setprio 1
	v_mfma_f32_16x16x32_bf16 v[62:65], v[162:165], v[200:203], v[62:65]
	v_mfma_f32_16x16x32_bf16 v[58:61], v[174:177], v[200:203], v[58:61]
	v_mfma_f32_16x16x32_bf16 v[54:57], v[162:165], v[208:211], v[54:57]
	v_mfma_f32_16x16x32_bf16 v[50:53], v[174:177], v[208:211], v[50:53]
	v_mfma_f32_16x16x32_bf16 v[46:49], v[162:165], v[216:219], v[46:49]
	v_mfma_f32_16x16x32_bf16 v[42:45], v[174:177], v[216:219], v[42:45]
	v_mfma_f32_16x16x32_bf16 v[38:41], v[162:165], v[224:227], v[38:41]
	v_mfma_f32_16x16x32_bf16 v[34:37], v[174:177], v[224:227], v[34:37]
	v_mfma_f32_16x16x32_bf16 v[62:65], v[170:173], v[204:207], v[62:65]
	v_mfma_f32_16x16x32_bf16 v[58:61], v[178:181], v[204:207], v[58:61]
	v_mfma_f32_16x16x32_bf16 v[54:57], v[170:173], v[212:215], v[54:57]
	v_mfma_f32_16x16x32_bf16 v[50:53], v[178:181], v[212:215], v[50:53]
	v_mfma_f32_16x16x32_bf16 v[46:49], v[170:173], v[220:223], v[46:49]
	v_mfma_f32_16x16x32_bf16 v[42:45], v[178:181], v[220:223], v[42:45]
	v_mfma_f32_16x16x32_bf16 v[38:41], v[170:173], v[228:231], v[38:41]
	v_mfma_f32_16x16x32_bf16 v[34:37], v[178:181], v[228:231], v[34:37]
	s_barrier
	s_setprio 0
	s_add_i32 s20, s50, s24
	v_lshl_add_u64 v[148:149], v[148:149], 0, s[38:39]
	s_mov_b32 m0, s20
	ds_read_b128 v[200:203], v169 offset:49152
	ds_read_b128 v[204:207], v169 offset:50176
	ds_read_b128 v[208:211], v169 offset:51200
	ds_read_b128 v[212:215], v169 offset:52224
	ds_read_b128 v[216:219], v169 offset:53248
	ds_read_b128 v[220:223], v169 offset:54272
	ds_read_b128 v[224:227], v169 offset:55296
	ds_read_b128 v[228:231], v169 offset:56320
	global_load_lds_dwordx4 v[148:149], off
	s_add_i32 m0, s20, 0x2000
	s_add_u32 s18, s18, 0x40080
	v_lshl_add_u64 v[148:149], v[232:233], 0, s[38:39]
	s_addc_u32 s19, s19, 0
	s_add_i32 s20, s51, s24
	global_load_lds_dwordx4 v[148:149], off
	v_lshl_add_u64 v[148:149], s[18:19], 0, v[0:1]
	s_mov_b32 m0, s20
	s_nop 0
	global_load_lds_dwordx4 v[148:149], off
	v_lshl_add_u64 v[148:149], s[18:19], 0, v[130:131]
	s_add_i32 m0, s20, 0x2000
	s_nop 0
	global_load_lds_dwordx4 v[148:149], off
	v_lshl_add_u64 v[148:149], v[234:235], 0, s[38:39]
	s_mov_b32 m0, s31
	s_nop 0
	global_load_lds_dwordx4 v[148:149], off
	v_lshl_add_u64 v[148:149], v[236:237], 0, s[38:39]
	s_mov_b32 m0, s33
	s_nop 0
	global_load_lds_dwordx4 v[148:149], off
	s_waitcnt vmcnt(8)
	s_waitcnt lgkmcnt(0)
	s_barrier
	s_setprio 1
	s_waitcnt lgkmcnt(0)
	v_mfma_f32_16x16x32_bf16 v[94:97], v[140:143], v[200:203], v[94:97]
	v_mfma_f32_16x16x32_bf16 v[90:93], v[154:157], v[200:203], v[90:93]
	v_mfma_f32_16x16x32_bf16 v[86:89], v[140:143], v[208:211], v[86:89]
	v_mfma_f32_16x16x32_bf16 v[82:85], v[154:157], v[208:211], v[82:85]
	v_mfma_f32_16x16x32_bf16 v[78:81], v[140:143], v[216:219], v[78:81]
	v_mfma_f32_16x16x32_bf16 v[74:77], v[154:157], v[216:219], v[74:77]
	v_mfma_f32_16x16x32_bf16 v[70:73], v[140:143], v[224:227], v[70:73]
	v_mfma_f32_16x16x32_bf16 v[66:69], v[154:157], v[224:227], v[66:69]
	v_mfma_f32_16x16x32_bf16 v[94:97], v[144:147], v[204:207], v[94:97]
	v_mfma_f32_16x16x32_bf16 v[90:93], v[158:161], v[204:207], v[90:93]
	v_mfma_f32_16x16x32_bf16 v[86:89], v[144:147], v[212:215], v[86:89]
	v_mfma_f32_16x16x32_bf16 v[82:85], v[158:161], v[212:215], v[82:85]
	v_mfma_f32_16x16x32_bf16 v[78:81], v[144:147], v[220:223], v[78:81]
	v_mfma_f32_16x16x32_bf16 v[74:77], v[158:161], v[220:223], v[74:77]
	v_mfma_f32_16x16x32_bf16 v[70:73], v[144:147], v[228:231], v[70:73]
	v_mfma_f32_16x16x32_bf16 v[66:69], v[158:161], v[228:231], v[66:69]
	s_setprio 0
	s_setprio 1
	v_mfma_f32_16x16x32_bf16 v[30:33], v[162:165], v[200:203], v[30:33]
	v_mfma_f32_16x16x32_bf16 v[26:29], v[174:177], v[200:203], v[26:29]
	v_mfma_f32_16x16x32_bf16 v[22:25], v[162:165], v[208:211], v[22:25]
	v_mfma_f32_16x16x32_bf16 v[18:21], v[174:177], v[208:211], v[18:21]
	v_mfma_f32_16x16x32_bf16 v[14:17], v[162:165], v[216:219], v[14:17]
	v_mfma_f32_16x16x32_bf16 v[10:13], v[174:177], v[216:219], v[10:13]
	v_mfma_f32_16x16x32_bf16 v[6:9], v[162:165], v[224:227], v[6:9]
	v_mfma_f32_16x16x32_bf16 v[2:5], v[174:177], v[224:227], v[2:5]
	v_mfma_f32_16x16x32_bf16 v[30:33], v[170:173], v[204:207], v[30:33]
	v_mfma_f32_16x16x32_bf16 v[26:29], v[178:181], v[204:207], v[26:29]
	v_mfma_f32_16x16x32_bf16 v[22:25], v[170:173], v[212:215], v[22:25]
	v_mfma_f32_16x16x32_bf16 v[18:21], v[178:181], v[212:215], v[18:21]
	v_mfma_f32_16x16x32_bf16 v[14:17], v[170:173], v[220:223], v[14:17]
	v_mfma_f32_16x16x32_bf16 v[10:13], v[178:181], v[220:223], v[10:13]
	v_mfma_f32_16x16x32_bf16 v[6:9], v[170:173], v[228:231], v[6:9]
	v_mfma_f32_16x16x32_bf16 v[2:5], v[178:181], v[228:231], v[2:5]
	s_barrier
	s_setprio 0
	s_add_i32 s49, s49, 2
	s_add_u32 s16, s16, 0x100
	s_addc_u32 s17, s17, 0
	s_add_u32 s47, s47, 0x100
	s_addc_u32 s48, s48, 0
	s_cmp_gt_u32 s49, 13
	s_cbranch_scc0 .LBB0_1090
	s_and_b64 vcc, exec, s[6:7]
	s_cbranch_vccz .LBB0_1093
	s_barrier
